# GEMM 8-phase main loops (7): post-barrier lgkmcnt(0) drain replaced by a counted ladder (each MFMA waits only for the ds_reads it consumes; segment still ends drained)
# baseline (speedup 1.0000x reference)
.LBB0_152:
	ds_read_b128 v[140:143], v208
	ds_read_b128 v[144:147], v208 offset:1024
	ds_read_b128 v[148:151], v208 offset:2048
	ds_read_b128 v[152:155], v208 offset:3072
	v_lshl_add_u64 v[160:161], v[136:137], 0, s[8:9]
	s_mov_b32 m0, s15
	v_lshl_add_u64 v[194:195], v[160:161], 0, s[20:21]
	v_lshl_add_u64 v[206:207], v[138:139], 0, s[8:9]
	ds_read_b128 v[156:159], v209
	ds_read_b128 v[166:169], v209 offset:1024
	ds_read_b128 v[170:173], v210
	ds_read_b128 v[174:177], v210 offset:1024
	ds_read_b128 v[178:181], v211
	ds_read_b128 v[182:185], v211 offset:1024
	ds_read_b128 v[186:189], v212
	ds_read_b128 v[190:193], v212 offset:1024
	global_load_lds_dwordx4 v[194:195], off
	v_lshl_add_u64 v[194:195], v[206:207], 0, s[20:21]
	s_mov_b32 m0, s11
	s_nop 0
	global_load_lds_dwordx4 v[194:195], off
	s_waitcnt lgkmcnt(8)
	s_barrier
	s_setprio 1
	s_waitcnt lgkmcnt(7)
	v_mfma_f32_16x16x32_bf16 v[126:129], v[156:159], v[140:143], v[126:129]
	v_mfma_f32_16x16x32_bf16 v[122:125], v[156:159], v[148:151], v[122:125]
	s_waitcnt lgkmcnt(5)
	v_mfma_f32_16x16x32_bf16 v[118:121], v[170:173], v[140:143], v[118:121]
	v_mfma_f32_16x16x32_bf16 v[114:117], v[170:173], v[148:151], v[114:117]
	s_waitcnt lgkmcnt(3)
	v_mfma_f32_16x16x32_bf16 v[110:113], v[178:181], v[140:143], v[110:113]
	v_mfma_f32_16x16x32_bf16 v[106:109], v[178:181], v[148:151], v[106:109]
	s_waitcnt lgkmcnt(1)
	v_mfma_f32_16x16x32_bf16 v[102:105], v[186:189], v[140:143], v[102:105]
	v_mfma_f32_16x16x32_bf16 v[98:101], v[186:189], v[148:151], v[98:101]
	v_mfma_f32_16x16x32_bf16 v[126:129], v[166:169], v[144:147], v[126:129]
	v_mfma_f32_16x16x32_bf16 v[122:125], v[166:169], v[152:155], v[122:125]
	v_mfma_f32_16x16x32_bf16 v[118:121], v[174:177], v[144:147], v[118:121]
	v_mfma_f32_16x16x32_bf16 v[114:117], v[174:177], v[152:155], v[114:117]
	v_mfma_f32_16x16x32_bf16 v[110:113], v[182:185], v[144:147], v[110:113]
	v_mfma_f32_16x16x32_bf16 v[106:109], v[182:185], v[152:155], v[106:109]
	s_waitcnt lgkmcnt(0)
	v_mfma_f32_16x16x32_bf16 v[102:105], v[190:193], v[144:147], v[102:105]
	v_mfma_f32_16x16x32_bf16 v[98:101], v[190:193], v[152:155], v[98:101]
	s_setprio 0
	s_barrier
	v_lshl_add_u64 v[224:225], v[132:133], 0, s[8:9]
	s_mov_b32 m0, s87
	v_lshl_add_u64 v[226:227], v[224:225], 0, s[22:23]
	ds_read_b128 v[194:197], v213
	ds_read_b128 v[198:201], v213 offset:1024
	ds_read_b128 v[202:205], v213 offset:2048
	ds_read_b128 v[220:223], v213 offset:3072
	global_load_lds_dwordx4 v[226:227], off
	v_lshl_add_u64 v[226:227], v[134:135], 0, s[8:9]
	v_lshl_add_u64 v[228:229], v[226:227], 0, s[22:23]
	s_mov_b32 m0, s88
	s_nop 0
	global_load_lds_dwordx4 v[228:229], off
	s_barrier
	s_setprio 1
	s_waitcnt lgkmcnt(3)
	v_mfma_f32_16x16x32_bf16 v[94:97], v[156:159], v[194:197], v[94:97]
	s_waitcnt lgkmcnt(1)
	v_mfma_f32_16x16x32_bf16 v[90:93], v[156:159], v[202:205], v[90:93]
	v_mfma_f32_16x16x32_bf16 v[86:89], v[170:173], v[194:197], v[86:89]
	v_mfma_f32_16x16x32_bf16 v[82:85], v[170:173], v[202:205], v[82:85]
	v_mfma_f32_16x16x32_bf16 v[78:81], v[178:181], v[194:197], v[78:81]
	v_mfma_f32_16x16x32_bf16 v[74:77], v[178:181], v[202:205], v[74:77]
	v_mfma_f32_16x16x32_bf16 v[70:73], v[186:189], v[194:197], v[70:73]
	v_mfma_f32_16x16x32_bf16 v[66:69], v[186:189], v[202:205], v[66:69]
	v_mfma_f32_16x16x32_bf16 v[94:97], v[166:169], v[198:201], v[94:97]
	s_waitcnt lgkmcnt(0)
	v_mfma_f32_16x16x32_bf16 v[90:93], v[166:169], v[220:223], v[90:93]
	v_mfma_f32_16x16x32_bf16 v[86:89], v[174:177], v[198:201], v[86:89]
	v_mfma_f32_16x16x32_bf16 v[82:85], v[174:177], v[220:223], v[82:85]
	v_mfma_f32_16x16x32_bf16 v[78:81], v[182:185], v[198:201], v[78:81]
	v_mfma_f32_16x16x32_bf16 v[74:77], v[182:185], v[220:223], v[74:77]
	v_mfma_f32_16x16x32_bf16 v[70:73], v[190:193], v[198:201], v[70:73]
	v_mfma_f32_16x16x32_bf16 v[66:69], v[190:193], v[220:223], v[66:69]
	s_setprio 0
	s_mov_b32 m0, s14
	v_lshl_add_u64 v[228:229], v[160:161], 0, s[22:23]
	s_barrier
	ds_read_b128 v[156:159], v209 offset:16384
	ds_read_b128 v[166:169], v209 offset:17408
	ds_read_b128 v[170:173], v210 offset:16384
	ds_read_b128 v[174:177], v210 offset:17408
	ds_read_b128 v[178:181], v211 offset:16384
	ds_read_b128 v[182:185], v211 offset:17408
	ds_read_b128 v[186:189], v212 offset:16384
	ds_read_b128 v[190:193], v212 offset:17408
	global_load_lds_dwordx4 v[228:229], off
	v_lshl_add_u64 v[228:229], v[206:207], 0, s[22:23]
	s_mov_b32 m0, s89
	s_nop 0
	global_load_lds_dwordx4 v[228:229], off
	s_barrier
	s_setprio 1
	s_waitcnt lgkmcnt(7)
	v_mfma_f32_16x16x32_bf16 v[62:65], v[156:159], v[140:143], v[62:65]
	v_mfma_f32_16x16x32_bf16 v[58:61], v[156:159], v[148:151], v[58:61]
	s_waitcnt lgkmcnt(5)
	v_mfma_f32_16x16x32_bf16 v[54:57], v[170:173], v[140:143], v[54:57]
	v_mfma_f32_16x16x32_bf16 v[50:53], v[170:173], v[148:151], v[50:53]
	s_waitcnt lgkmcnt(3)
	v_mfma_f32_16x16x32_bf16 v[46:49], v[178:181], v[140:143], v[46:49]
	v_mfma_f32_16x16x32_bf16 v[42:45], v[178:181], v[148:151], v[42:45]
	s_waitcnt lgkmcnt(1)
	v_mfma_f32_16x16x32_bf16 v[38:41], v[186:189], v[140:143], v[38:41]
	v_mfma_f32_16x16x32_bf16 v[34:37], v[186:189], v[148:151], v[34:37]
	v_mfma_f32_16x16x32_bf16 v[62:65], v[166:169], v[144:147], v[62:65]
	v_mfma_f32_16x16x32_bf16 v[58:61], v[166:169], v[152:155], v[58:61]
	v_mfma_f32_16x16x32_bf16 v[54:57], v[174:177], v[144:147], v[54:57]
	v_mfma_f32_16x16x32_bf16 v[50:53], v[174:177], v[152:155], v[50:53]
	v_mfma_f32_16x16x32_bf16 v[46:49], v[182:185], v[144:147], v[46:49]
	v_mfma_f32_16x16x32_bf16 v[42:45], v[182:185], v[152:155], v[42:45]
	s_waitcnt lgkmcnt(0)
	v_mfma_f32_16x16x32_bf16 v[38:41], v[190:193], v[144:147], v[38:41]
	v_mfma_f32_16x16x32_bf16 v[34:37], v[190:193], v[152:155], v[34:37]
	s_setprio 0
	s_barrier
	s_mov_b32 m0, s90
	v_lshl_add_u64 v[140:141], v[224:225], 0, s[24:25]
	global_load_lds_dwordx4 v[140:141], off
	v_lshl_add_u64 v[140:141], v[226:227], 0, s[24:25]
	s_mov_b32 m0, s91
	s_nop 0
	global_load_lds_dwordx4 v[140:141], off
	s_waitcnt vmcnt(6)
	s_barrier
	s_setprio 1
	v_mfma_f32_16x16x32_bf16 v[30:33], v[156:159], v[194:197], v[30:33]
	v_mfma_f32_16x16x32_bf16 v[26:29], v[156:159], v[202:205], v[26:29]
	v_mfma_f32_16x16x32_bf16 v[22:25], v[170:173], v[194:197], v[22:25]
	v_mfma_f32_16x16x32_bf16 v[18:21], v[170:173], v[202:205], v[18:21]
	v_mfma_f32_16x16x32_bf16 v[14:17], v[178:181], v[194:197], v[14:17]
	v_mfma_f32_16x16x32_bf16 v[10:13], v[178:181], v[202:205], v[10:13]
	v_mfma_f32_16x16x32_bf16 v[6:9], v[186:189], v[194:197], v[6:9]
	v_mfma_f32_16x16x32_bf16 v[2:5], v[186:189], v[202:205], v[2:5]
	v_mfma_f32_16x16x32_bf16 v[30:33], v[166:169], v[198:201], v[30:33]
	v_mfma_f32_16x16x32_bf16 v[26:29], v[166:169], v[220:223], v[26:29]
	v_mfma_f32_16x16x32_bf16 v[22:25], v[174:177], v[198:201], v[22:25]
	v_mfma_f32_16x16x32_bf16 v[18:21], v[174:177], v[220:223], v[18:21]
	v_mfma_f32_16x16x32_bf16 v[14:17], v[182:185], v[198:201], v[14:17]
	v_mfma_f32_16x16x32_bf16 v[10:13], v[182:185], v[220:223], v[10:13]
	v_mfma_f32_16x16x32_bf16 v[6:9], v[190:193], v[198:201], v[6:9]
	v_mfma_f32_16x16x32_bf16 v[2:5], v[190:193], v[220:223], v[2:5]
	s_setprio 0
	s_barrier
	ds_read_b128 v[140:143], v214
	ds_read_b128 v[144:147], v214 offset:1024
	ds_read_b128 v[148:151], v214 offset:2048
	ds_read_b128 v[152:155], v214 offset:3072
	s_mov_b32 m0, s95
	v_lshl_add_u64 v[194:195], v[160:161], 0, s[24:25]
	ds_read_b128 v[156:159], v209 offset:32768
	ds_read_b128 v[166:169], v209 offset:33792
	ds_read_b128 v[170:173], v210 offset:32768
	ds_read_b128 v[174:177], v210 offset:33792
	ds_read_b128 v[178:181], v211 offset:32768
	ds_read_b128 v[182:185], v211 offset:33792
	ds_read_b128 v[186:189], v212 offset:32768
	ds_read_b128 v[190:193], v212 offset:33792
	global_load_lds_dwordx4 v[194:195], off
	v_lshl_add_u64 v[194:195], v[206:207], 0, s[24:25]
	s_mov_b32 m0, s97
	s_nop 0
	global_load_lds_dwordx4 v[194:195], off
	s_waitcnt lgkmcnt(8)
	s_barrier
	s_setprio 1
	s_waitcnt lgkmcnt(7)
	v_mfma_f32_16x16x32_bf16 v[126:129], v[156:159], v[140:143], v[126:129]
	v_mfma_f32_16x16x32_bf16 v[122:125], v[156:159], v[148:151], v[122:125]
	s_waitcnt lgkmcnt(5)
	v_mfma_f32_16x16x32_bf16 v[118:121], v[170:173], v[140:143], v[118:121]
	v_mfma_f32_16x16x32_bf16 v[114:117], v[170:173], v[148:151], v[114:117]
	s_waitcnt lgkmcnt(3)
	v_mfma_f32_16x16x32_bf16 v[110:113], v[178:181], v[140:143], v[110:113]
	v_mfma_f32_16x16x32_bf16 v[106:109], v[178:181], v[148:151], v[106:109]
	s_waitcnt lgkmcnt(1)
	v_mfma_f32_16x16x32_bf16 v[102:105], v[186:189], v[140:143], v[102:105]
	v_mfma_f32_16x16x32_bf16 v[98:101], v[186:189], v[148:151], v[98:101]
	v_mfma_f32_16x16x32_bf16 v[126:129], v[166:169], v[144:147], v[126:129]
	v_mfma_f32_16x16x32_bf16 v[122:125], v[166:169], v[152:155], v[122:125]
	v_mfma_f32_16x16x32_bf16 v[118:121], v[174:177], v[144:147], v[118:121]
	v_mfma_f32_16x16x32_bf16 v[114:117], v[174:177], v[152:155], v[114:117]
	v_mfma_f32_16x16x32_bf16 v[110:113], v[182:185], v[144:147], v[110:113]
	v_mfma_f32_16x16x32_bf16 v[106:109], v[182:185], v[152:155], v[106:109]
	s_waitcnt lgkmcnt(0)
	v_mfma_f32_16x16x32_bf16 v[102:105], v[190:193], v[144:147], v[102:105]
	v_mfma_f32_16x16x32_bf16 v[98:101], v[190:193], v[152:155], v[98:101]
	s_setprio 0
	s_barrier
	s_mov_b32 m0, vcc_lo
	v_lshl_add_u64 v[228:229], v[224:225], 0, s[26:27]
	ds_read_b128 v[194:197], v215
	ds_read_b128 v[198:201], v215 offset:1024
	ds_read_b128 v[202:205], v215 offset:2048
	ds_read_b128 v[220:223], v215 offset:3072
	global_load_lds_dwordx4 v[228:229], off
	v_lshl_add_u64 v[228:229], v[226:227], 0, s[26:27]
	s_mov_b32 m0, vcc_hi
	s_nop 0
	global_load_lds_dwordx4 v[228:229], off
	s_barrier
	s_setprio 1
	s_waitcnt lgkmcnt(3)
	v_mfma_f32_16x16x32_bf16 v[94:97], v[156:159], v[194:197], v[94:97]
	s_waitcnt lgkmcnt(1)
	v_mfma_f32_16x16x32_bf16 v[90:93], v[156:159], v[202:205], v[90:93]
	v_mfma_f32_16x16x32_bf16 v[86:89], v[170:173], v[194:197], v[86:89]
	v_mfma_f32_16x16x32_bf16 v[82:85], v[170:173], v[202:205], v[82:85]
	v_mfma_f32_16x16x32_bf16 v[78:81], v[178:181], v[194:197], v[78:81]
	v_mfma_f32_16x16x32_bf16 v[74:77], v[178:181], v[202:205], v[74:77]
	v_mfma_f32_16x16x32_bf16 v[70:73], v[186:189], v[194:197], v[70:73]
	v_mfma_f32_16x16x32_bf16 v[66:69], v[186:189], v[202:205], v[66:69]
	v_mfma_f32_16x16x32_bf16 v[94:97], v[166:169], v[198:201], v[94:97]
	s_waitcnt lgkmcnt(0)
	v_mfma_f32_16x16x32_bf16 v[90:93], v[166:169], v[220:223], v[90:93]
	v_mfma_f32_16x16x32_bf16 v[86:89], v[174:177], v[198:201], v[86:89]
	v_mfma_f32_16x16x32_bf16 v[82:85], v[174:177], v[220:223], v[82:85]
	v_mfma_f32_16x16x32_bf16 v[78:81], v[182:185], v[198:201], v[78:81]
	v_mfma_f32_16x16x32_bf16 v[74:77], v[182:185], v[220:223], v[74:77]
	v_mfma_f32_16x16x32_bf16 v[70:73], v[190:193], v[198:201], v[70:73]
	v_mfma_f32_16x16x32_bf16 v[66:69], v[190:193], v[220:223], v[66:69]
	s_setprio 0
	s_mov_b32 m0, s30
	v_lshl_add_u64 v[160:161], v[160:161], 0, s[26:27]
	s_barrier
	ds_read_b128 v[156:159], v209 offset:49152
	ds_read_b128 v[166:169], v209 offset:50176
	ds_read_b128 v[170:173], v210 offset:49152
	ds_read_b128 v[174:177], v210 offset:50176
	ds_read_b128 v[178:181], v211 offset:49152
	ds_read_b128 v[182:185], v211 offset:50176
	ds_read_b128 v[186:189], v212 offset:49152
	ds_read_b128 v[190:193], v212 offset:50176
	global_load_lds_dwordx4 v[160:161], off
	v_lshl_add_u64 v[160:161], v[206:207], 0, s[26:27]
	s_mov_b32 m0, s31
	s_nop 0
	global_load_lds_dwordx4 v[160:161], off
	s_barrier
	s_setprio 1
	s_waitcnt lgkmcnt(7)
	v_mfma_f32_16x16x32_bf16 v[62:65], v[156:159], v[140:143], v[62:65]
	v_mfma_f32_16x16x32_bf16 v[58:61], v[156:159], v[148:151], v[58:61]
	s_waitcnt lgkmcnt(5)
	v_mfma_f32_16x16x32_bf16 v[54:57], v[170:173], v[140:143], v[54:57]
	v_mfma_f32_16x16x32_bf16 v[50:53], v[170:173], v[148:151], v[50:53]
	s_waitcnt lgkmcnt(3)
	v_mfma_f32_16x16x32_bf16 v[46:49], v[178:181], v[140:143], v[46:49]
	v_mfma_f32_16x16x32_bf16 v[42:45], v[178:181], v[148:151], v[42:45]
	s_waitcnt lgkmcnt(1)
	v_mfma_f32_16x16x32_bf16 v[38:41], v[186:189], v[140:143], v[38:41]
	v_mfma_f32_16x16x32_bf16 v[34:37], v[186:189], v[148:151], v[34:37]
	v_mfma_f32_16x16x32_bf16 v[62:65], v[166:169], v[144:147], v[62:65]
	v_mfma_f32_16x16x32_bf16 v[58:61], v[166:169], v[152:155], v[58:61]
	v_mfma_f32_16x16x32_bf16 v[54:57], v[174:177], v[144:147], v[54:57]
	v_mfma_f32_16x16x32_bf16 v[50:53], v[174:177], v[152:155], v[50:53]
	v_mfma_f32_16x16x32_bf16 v[46:49], v[182:185], v[144:147], v[46:49]
	v_mfma_f32_16x16x32_bf16 v[42:45], v[182:185], v[152:155], v[42:45]
	s_waitcnt lgkmcnt(0)
	v_mfma_f32_16x16x32_bf16 v[38:41], v[190:193], v[144:147], v[38:41]
	v_mfma_f32_16x16x32_bf16 v[34:37], v[190:193], v[152:155], v[34:37]
	s_setprio 0
	s_barrier
	s_mov_b32 m0, s33
	v_lshl_add_u64 v[140:141], v[224:225], 0, s[16:17]
	global_load_lds_dwordx4 v[140:141], off
	v_lshl_add_u64 v[140:141], v[226:227], 0, s[16:17]
	s_mov_b32 m0, s84
	s_nop 0
	global_load_lds_dwordx4 v[140:141], off
	s_waitcnt vmcnt(6)
	s_barrier
	s_setprio 1
	v_mfma_f32_16x16x32_bf16 v[30:33], v[156:159], v[194:197], v[30:33]
	v_mfma_f32_16x16x32_bf16 v[26:29], v[156:159], v[202:205], v[26:29]
	v_mfma_f32_16x16x32_bf16 v[22:25], v[170:173], v[194:197], v[22:25]
	v_mfma_f32_16x16x32_bf16 v[18:21], v[170:173], v[202:205], v[18:21]
	v_mfma_f32_16x16x32_bf16 v[14:17], v[178:181], v[194:197], v[14:17]
	v_mfma_f32_16x16x32_bf16 v[10:13], v[178:181], v[202:205], v[10:13]
	v_mfma_f32_16x16x32_bf16 v[6:9], v[186:189], v[194:197], v[6:9]
	v_mfma_f32_16x16x32_bf16 v[2:5], v[186:189], v[202:205], v[2:5]
	v_mfma_f32_16x16x32_bf16 v[30:33], v[166:169], v[198:201], v[30:33]
	v_mfma_f32_16x16x32_bf16 v[26:29], v[166:169], v[220:223], v[26:29]
	v_mfma_f32_16x16x32_bf16 v[22:25], v[174:177], v[198:201], v[22:25]
	v_mfma_f32_16x16x32_bf16 v[18:21], v[174:177], v[220:223], v[18:21]
	v_mfma_f32_16x16x32_bf16 v[14:17], v[182:185], v[198:201], v[14:17]
	v_mfma_f32_16x16x32_bf16 v[10:13], v[182:185], v[220:223], v[10:13]
	v_mfma_f32_16x16x32_bf16 v[6:9], v[190:193], v[198:201], v[6:9]
	v_mfma_f32_16x16x32_bf16 v[2:5], v[190:193], v[220:223], v[2:5]
	s_setprio 0
	s_add_i32 s85, s85, 2
	s_add_u32 s8, s8, 0x100
	s_addc_u32 s9, s9, 0
	s_cmp_lt_u32 s85, 12
	s_barrier
	s_cbranch_scc1 .LBB0_152
	s_add_u32 s8, s28, 0x40780
	s_addc_u32 s9, s29, 0
	s_mov_b32 m0, s15
	v_lshl_add_u64 v[160:161], v[164:165], 1, s[8:9]
	ds_read_b128 v[132:135], v208
	ds_read_b128 v[136:139], v208 offset:1024
	ds_read_b128 v[140:143], v208 offset:2048
	ds_read_b128 v[144:147], v208 offset:3072
	ds_read_b128 v[148:151], v209
	ds_read_b128 v[152:155], v209 offset:1024
	ds_read_b128 v[156:159], v210
	ds_read_b128 v[166:169], v210 offset:1024
	ds_read_b128 v[170:173], v211
	ds_read_b128 v[174:177], v211 offset:1024
	ds_read_b128 v[178:181], v212
	ds_read_b128 v[182:185], v212 offset:1024
	global_load_lds_dwordx4 v[160:161], off
	v_lshl_add_u64 v[130:131], v[130:131], 1, s[8:9]
	s_mov_b32 m0, s11
	s_nop 0
	global_load_lds_dwordx4 v[130:131], off
	s_barrier
	s_waitcnt lgkmcnt(0)
	s_setprio 1
	s_waitcnt lgkmcnt(0)
	v_mfma_f32_16x16x32_bf16 v[126:129], v[148:151], v[132:135], v[126:129]
	v_mfma_f32_16x16x32_bf16 v[122:125], v[148:151], v[140:143], v[122:125]
	v_mfma_f32_16x16x32_bf16 v[118:121], v[156:159], v[132:135], v[118:121]
	v_mfma_f32_16x16x32_bf16 v[114:117], v[156:159], v[140:143], v[114:117]
	v_mfma_f32_16x16x32_bf16 v[110:113], v[170:173], v[132:135], v[110:113]
	v_mfma_f32_16x16x32_bf16 v[106:109], v[170:173], v[140:143], v[106:109]
	v_mfma_f32_16x16x32_bf16 v[102:105], v[178:181], v[132:135], v[102:105]
	v_mfma_f32_16x16x32_bf16 v[98:101], v[178:181], v[140:143], v[98:101]
	v_mfma_f32_16x16x32_bf16 v[126:129], v[152:155], v[136:139], v[126:129]
	v_mfma_f32_16x16x32_bf16 v[122:125], v[152:155], v[144:147], v[122:125]
	v_mfma_f32_16x16x32_bf16 v[118:121], v[166:169], v[136:139], v[118:121]
	v_mfma_f32_16x16x32_bf16 v[114:117], v[166:169], v[144:147], v[114:117]
	v_mfma_f32_16x16x32_bf16 v[110:113], v[174:177], v[136:139], v[110:113]
	v_mfma_f32_16x16x32_bf16 v[106:109], v[174:177], v[144:147], v[106:109]
	v_mfma_f32_16x16x32_bf16 v[102:105], v[182:185], v[136:139], v[102:105]
	v_mfma_f32_16x16x32_bf16 v[98:101], v[182:185], v[144:147], v[98:101]
	s_setprio 0
	s_barrier
	ds_read_b128 v[186:189], v213
	ds_read_b128 v[190:193], v213 offset:1024
	ds_read_b128 v[194:197], v213 offset:2048
	ds_read_b128 v[198:201], v213 offset:3072
	s_barrier
	s_waitcnt lgkmcnt(0)
	s_setprio 1
	s_waitcnt lgkmcnt(0)
	v_mfma_f32_16x16x32_bf16 v[78:81], v[170:173], v[186:189], v[78:81]
	v_mfma_f32_16x16x32_bf16 v[74:77], v[170:173], v[194:197], v[74:77]
	v_mfma_f32_16x16x32_bf16 v[70:73], v[178:181], v[186:189], v[70:73]
	v_mfma_f32_16x16x32_bf16 v[66:69], v[178:181], v[194:197], v[66:69]
	v_mfma_f32_16x16x32_bf16 v[94:97], v[148:151], v[186:189], v[94:97]
	v_mfma_f32_16x16x32_bf16 v[90:93], v[148:151], v[194:197], v[90:93]
	v_mfma_f32_16x16x32_bf16 v[86:89], v[156:159], v[186:189], v[86:89]
	v_mfma_f32_16x16x32_bf16 v[82:85], v[156:159], v[194:197], v[82:85]
	v_mfma_f32_16x16x32_bf16 v[78:81], v[174:177], v[190:193], v[78:81]
	v_mfma_f32_16x16x32_bf16 v[74:77], v[174:177], v[198:201], v[74:77]
	v_mfma_f32_16x16x32_bf16 v[70:73], v[182:185], v[190:193], v[70:73]
	v_mfma_f32_16x16x32_bf16 v[66:69], v[182:185], v[198:201], v[66:69]
	v_mfma_f32_16x16x32_bf16 v[202:205], v[152:155], v[190:193], v[94:97]
	v_mfma_f32_16x16x32_bf16 v[148:151], v[152:155], v[198:201], v[90:93]
	v_mfma_f32_16x16x32_bf16 v[152:155], v[166:169], v[190:193], v[86:89]
	v_mfma_f32_16x16x32_bf16 v[156:159], v[166:169], v[198:201], v[82:85]
	s_setprio 0
	s_barrier
	s_nop 0
	ds_read_b128 v[82:85], v209 offset:16384
	ds_read_b128 v[86:89], v209 offset:17408
	ds_read_b128 v[90:93], v210 offset:16384
	ds_read_b128 v[94:97], v210 offset:17408
	ds_read_b128 v[166:169], v211 offset:16384
	ds_read_b128 v[170:173], v211 offset:17408
	ds_read_b128 v[174:177], v212 offset:16384
	ds_read_b128 v[178:181], v212 offset:17408
	s_waitcnt vmcnt(4)
	s_barrier
	s_waitcnt lgkmcnt(0)
	s_setprio 1
	s_waitcnt lgkmcnt(0)
	v_mfma_f32_16x16x32_bf16 v[46:49], v[166:169], v[132:135], v[46:49]
	v_mfma_f32_16x16x32_bf16 v[42:45], v[166:169], v[140:143], v[42:45]
	v_mfma_f32_16x16x32_bf16 v[38:41], v[174:177], v[132:135], v[38:41]
	v_mfma_f32_16x16x32_bf16 v[34:37], v[174:177], v[140:143], v[34:37]
	v_mfma_f32_16x16x32_bf16 v[62:65], v[82:85], v[132:135], v[62:65]
	v_mfma_f32_16x16x32_bf16 v[58:61], v[82:85], v[140:143], v[58:61]
	v_mfma_f32_16x16x32_bf16 v[54:57], v[90:93], v[132:135], v[54:57]
	v_mfma_f32_16x16x32_bf16 v[50:53], v[90:93], v[140:143], v[50:53]
	v_mfma_f32_16x16x32_bf16 v[46:49], v[170:173], v[136:139], v[46:49]
	v_mfma_f32_16x16x32_bf16 v[42:45], v[170:173], v[144:147], v[42:45]
	v_mfma_f32_16x16x32_bf16 v[38:41], v[178:181], v[136:139], v[38:41]
	v_mfma_f32_16x16x32_bf16 v[34:37], v[178:181], v[144:147], v[34:37]
	v_mfma_f32_16x16x32_bf16 v[182:185], v[86:89], v[136:139], v[62:65]
	v_mfma_f32_16x16x32_bf16 v[220:223], v[86:89], v[144:147], v[58:61]
	v_mfma_f32_16x16x32_bf16 v[224:227], v[94:97], v[136:139], v[54:57]
	v_mfma_f32_16x16x32_bf16 v[228:231], v[94:97], v[144:147], v[50:53]
	s_setprio 0
	s_setprio 1
	v_mfma_f32_16x16x32_bf16 v[2:5], v[174:177], v[194:197], v[2:5]
	v_mfma_f32_16x16x32_bf16 v[30:33], v[82:85], v[186:189], v[30:33]
	v_mfma_f32_16x16x32_bf16 v[26:29], v[82:85], v[194:197], v[26:29]
	v_mfma_f32_16x16x32_bf16 v[22:25], v[90:93], v[186:189], v[22:25]
	v_mfma_f32_16x16x32_bf16 v[18:21], v[90:93], v[194:197], v[18:21]
	v_mfma_f32_16x16x32_bf16 v[14:17], v[166:169], v[186:189], v[14:17]
	v_mfma_f32_16x16x32_bf16 v[10:13], v[166:169], v[194:197], v[10:13]
	v_mfma_f32_16x16x32_bf16 v[6:9], v[174:177], v[186:189], v[6:9]
	v_mfma_f32_16x16x32_bf16 v[2:5], v[178:181], v[198:201], v[2:5]
	v_mfma_f32_16x16x32_bf16 v[130:133], v[86:89], v[190:193], v[30:33]
	v_mfma_f32_16x16x32_bf16 v[134:137], v[86:89], v[198:201], v[26:29]
	v_mfma_f32_16x16x32_bf16 v[138:141], v[94:97], v[190:193], v[22:25]
	v_mfma_f32_16x16x32_bf16 v[142:145], v[94:97], v[198:201], v[18:21]
	v_mfma_f32_16x16x32_bf16 v[232:235], v[170:173], v[190:193], v[14:17]
	v_mfma_f32_16x16x32_bf16 v[166:169], v[170:173], v[198:201], v[10:13]
	v_mfma_f32_16x16x32_bf16 v[170:173], v[178:181], v[190:193], v[6:9]
	s_setprio 0
	s_barrier
	s_nop 0
	ds_read_b128 v[6:9], v214
	ds_read_b128 v[10:13], v214 offset:1024
	ds_read_b128 v[14:17], v214 offset:2048
	ds_read_b128 v[174:177], v214 offset:3072
	ds_read_b128 v[18:21], v209 offset:32768
	ds_read_b128 v[22:25], v209 offset:33792
	ds_read_b128 v[26:29], v210 offset:32768
	ds_read_b128 v[50:53], v210 offset:33792
	ds_read_b128 v[178:181], v211 offset:32768
	ds_read_b128 v[186:189], v211 offset:33792
	ds_read_b128 v[190:193], v212 offset:32768
	ds_read_b128 v[194:197], v212 offset:33792
	s_waitcnt vmcnt(2)
	s_barrier
	s_waitcnt lgkmcnt(0)
	s_setprio 1
	s_waitcnt lgkmcnt(0)
	v_mfma_f32_16x16x32_bf16 v[30:33], v[18:21], v[6:9], v[126:129]
	v_mfma_f32_16x16x32_bf16 v[126:129], v[22:25], v[10:13], v[30:33]
	v_mfma_f32_16x16x32_bf16 v[30:33], v[18:21], v[14:17], v[122:125]
	v_mfma_f32_16x16x32_bf16 v[94:97], v[22:25], v[174:177], v[30:33]
	v_mfma_f32_16x16x32_bf16 v[30:33], v[26:29], v[6:9], v[118:121]
	v_mfma_f32_16x16x32_bf16 v[122:125], v[50:53], v[10:13], v[30:33]
	v_mfma_f32_16x16x32_bf16 v[30:33], v[26:29], v[14:17], v[114:117]
	v_mfma_f32_16x16x32_bf16 v[90:93], v[50:53], v[174:177], v[30:33]
	v_mfma_f32_16x16x32_bf16 v[30:33], v[178:181], v[6:9], v[110:113]
	v_mfma_f32_16x16x32_bf16 v[118:121], v[186:189], v[10:13], v[30:33]
	v_mfma_f32_16x16x32_bf16 v[30:33], v[178:181], v[14:17], v[106:109]
	v_mfma_f32_16x16x32_bf16 v[86:89], v[186:189], v[174:177], v[30:33]
	v_mfma_f32_16x16x32_bf16 v[30:33], v[190:193], v[6:9], v[102:105]
	v_mfma_f32_16x16x32_bf16 v[114:117], v[194:197], v[10:13], v[30:33]
	v_mfma_f32_16x16x32_bf16 v[30:33], v[190:193], v[14:17], v[98:101]
	v_mfma_f32_16x16x32_bf16 v[82:85], v[194:197], v[174:177], v[30:33]
	s_setprio 0
	s_barrier
	ds_read_b128 v[198:201], v215
	ds_read_b128 v[236:239], v215 offset:1024
	ds_read_b128 v[240:243], v215 offset:2048
	ds_read_b128 v[244:247], v215 offset:3072
	s_waitcnt vmcnt(0)
	s_barrier
	s_waitcnt lgkmcnt(0)
	s_setprio 1
	s_waitcnt lgkmcnt(0)
	v_mfma_f32_16x16x32_bf16 v[30:33], v[18:21], v[198:201], v[202:205]
	v_mfma_f32_16x16x32_bf16 v[18:21], v[18:21], v[240:243], v[148:151]
	v_mfma_f32_16x16x32_bf16 v[62:65], v[22:25], v[236:239], v[30:33]
	v_mfma_f32_16x16x32_bf16 v[30:33], v[22:25], v[244:247], v[18:21]
	v_mfma_f32_16x16x32_bf16 v[18:21], v[26:29], v[198:201], v[152:155]
	v_mfma_f32_16x16x32_bf16 v[58:61], v[50:53], v[236:239], v[18:21]
	v_mfma_f32_16x16x32_bf16 v[18:21], v[26:29], v[240:243], v[156:159]
	v_mfma_f32_16x16x32_bf16 v[26:29], v[50:53], v[244:247], v[18:21]
	v_mfma_f32_16x16x32_bf16 v[18:21], v[178:181], v[198:201], v[78:81]
	v_mfma_f32_16x16x32_bf16 v[54:57], v[186:189], v[236:239], v[18:21]
	v_mfma_f32_16x16x32_bf16 v[18:21], v[178:181], v[240:243], v[74:77]
	v_mfma_f32_16x16x32_bf16 v[22:25], v[186:189], v[244:247], v[18:21]
	v_mfma_f32_16x16x32_bf16 v[18:21], v[190:193], v[198:201], v[70:73]
	v_mfma_f32_16x16x32_bf16 v[50:53], v[194:197], v[236:239], v[18:21]
	v_mfma_f32_16x16x32_bf16 v[18:21], v[190:193], v[240:243], v[66:69]
	v_mfma_f32_16x16x32_bf16 v[18:21], v[194:197], v[244:247], v[18:21]
	s_setprio 0
	s_barrier
	ds_read_b128 v[146:149], v209 offset:49152
	ds_read_b128 v[150:153], v209 offset:50176
	ds_read_b128 v[154:157], v210 offset:49152
	ds_read_b128 v[158:161], v210 offset:50176
	ds_read_b128 v[178:181], v211 offset:49152
	ds_read_b128 v[186:189], v211 offset:50176
	ds_read_b128 v[190:193], v212 offset:49152
	ds_read_b128 v[194:197], v212 offset:50176
	s_barrier
	s_waitcnt lgkmcnt(0)
	s_setprio 1
	s_waitcnt lgkmcnt(0)
	v_mfma_f32_16x16x32_bf16 v[66:69], v[146:149], v[6:9], v[182:185]
	v_mfma_f32_16x16x32_bf16 v[110:113], v[150:153], v[10:13], v[66:69]
	v_mfma_f32_16x16x32_bf16 v[66:69], v[146:149], v[14:17], v[220:223]
	v_mfma_f32_16x16x32_bf16 v[78:81], v[150:153], v[174:177], v[66:69]
	v_mfma_f32_16x16x32_bf16 v[66:69], v[154:157], v[6:9], v[224:227]
	v_mfma_f32_16x16x32_bf16 v[46:49], v[178:181], v[6:9], v[46:49]
	v_mfma_f32_16x16x32_bf16 v[6:9], v[190:193], v[6:9], v[38:41]
	v_mfma_f32_16x16x32_bf16 v[106:109], v[158:161], v[10:13], v[66:69]
	v_mfma_f32_16x16x32_bf16 v[66:69], v[154:157], v[14:17], v[228:231]
	v_mfma_f32_16x16x32_bf16 v[42:45], v[178:181], v[14:17], v[42:45]
	v_mfma_f32_16x16x32_bf16 v[98:101], v[194:197], v[10:13], v[6:9]
	v_mfma_f32_16x16x32_bf16 v[6:9], v[190:193], v[14:17], v[34:37]
	v_mfma_f32_16x16x32_bf16 v[74:77], v[158:161], v[174:177], v[66:69]
	v_mfma_f32_16x16x32_bf16 v[102:105], v[186:189], v[10:13], v[46:49]
	v_mfma_f32_16x16x32_bf16 v[70:73], v[186:189], v[174:177], v[42:45]
	v_mfma_f32_16x16x32_bf16 v[66:69], v[194:197], v[174:177], v[6:9]
	s_setprio 0
	s_setprio 1
	v_mfma_f32_16x16x32_bf16 v[6:9], v[146:149], v[198:201], v[130:133]
	v_mfma_f32_16x16x32_bf16 v[46:49], v[150:153], v[236:239], v[6:9]
	v_mfma_f32_16x16x32_bf16 v[6:9], v[146:149], v[240:243], v[134:137]
	v_mfma_f32_16x16x32_bf16 v[14:17], v[150:153], v[244:247], v[6:9]
	v_mfma_f32_16x16x32_bf16 v[6:9], v[154:157], v[198:201], v[138:141]
	v_mfma_f32_16x16x32_bf16 v[42:45], v[158:161], v[236:239], v[6:9]
	v_mfma_f32_16x16x32_bf16 v[6:9], v[154:157], v[240:243], v[142:145]
	v_mfma_f32_16x16x32_bf16 v[10:13], v[158:161], v[244:247], v[6:9]
	v_mfma_f32_16x16x32_bf16 v[6:9], v[178:181], v[198:201], v[232:235]
	v_mfma_f32_16x16x32_bf16 v[38:41], v[186:189], v[236:239], v[6:9]
	v_mfma_f32_16x16x32_bf16 v[6:9], v[178:181], v[240:243], v[166:169]
	v_mfma_f32_16x16x32_bf16 v[34:37], v[190:193], v[198:201], v[170:173]
	v_mfma_f32_16x16x32_bf16 v[2:5], v[190:193], v[240:243], v[2:5]
	v_mfma_f32_16x16x32_bf16 v[6:9], v[186:189], v[244:247], v[6:9]
	v_mfma_f32_16x16x32_bf16 v[34:37], v[194:197], v[236:239], v[34:37]
	v_mfma_f32_16x16x32_bf16 v[2:5], v[194:197], v[244:247], v[2:5]
	s_setprio 0
	v_readlane_b32 s0, v248, 2
	v_readlane_b32 s1, v248, 3
	s_barrier
	s_and_saveexec_b64 s[8:9], s[0:1]
	s_cbranch_execz .LBB0_155
	s_barrier

.LBB0_188:
	ds_read_b128 v[140:143], v208
	ds_read_b128 v[144:147], v208 offset:1024
	ds_read_b128 v[148:151], v208 offset:2048
	ds_read_b128 v[152:155], v208 offset:3072
	v_lshl_add_u64 v[160:161], v[136:137], 0, s[8:9]
	s_add_i32 s13, s14, 0xc000
	v_lshl_add_u64 v[194:195], v[160:161], 0, s[20:21]
	s_mov_b32 m0, s13
	v_lshl_add_u64 v[206:207], v[138:139], 0, s[8:9]
	s_add_i32 s12, s14, 0xe000
	ds_read_b128 v[156:159], v209
	ds_read_b128 v[166:169], v209 offset:1024
	ds_read_b128 v[170:173], v210
	ds_read_b128 v[174:177], v210 offset:1024
	ds_read_b128 v[178:181], v211
	ds_read_b128 v[182:185], v211 offset:1024
	ds_read_b128 v[186:189], v212
	ds_read_b128 v[190:193], v212 offset:1024
	global_load_lds_dwordx4 v[194:195], off
	v_lshl_add_u64 v[194:195], v[206:207], 0, s[20:21]
	s_mov_b32 m0, s12
	s_nop 0
	global_load_lds_dwordx4 v[194:195], off
	s_waitcnt lgkmcnt(8)
	s_barrier
	s_setprio 1
	s_waitcnt lgkmcnt(7)
	v_mfma_f32_16x16x32_bf16 v[126:129], v[156:159], v[140:143], v[126:129]
	v_mfma_f32_16x16x32_bf16 v[122:125], v[156:159], v[148:151], v[122:125]
	s_waitcnt lgkmcnt(5)
	v_mfma_f32_16x16x32_bf16 v[118:121], v[170:173], v[140:143], v[118:121]
	v_mfma_f32_16x16x32_bf16 v[114:117], v[170:173], v[148:151], v[114:117]
	s_waitcnt lgkmcnt(3)
	v_mfma_f32_16x16x32_bf16 v[110:113], v[178:181], v[140:143], v[110:113]
	v_mfma_f32_16x16x32_bf16 v[106:109], v[178:181], v[148:151], v[106:109]
	s_waitcnt lgkmcnt(1)
	v_mfma_f32_16x16x32_bf16 v[102:105], v[186:189], v[140:143], v[102:105]
	v_mfma_f32_16x16x32_bf16 v[98:101], v[186:189], v[148:151], v[98:101]
	v_mfma_f32_16x16x32_bf16 v[126:129], v[166:169], v[144:147], v[126:129]
	v_mfma_f32_16x16x32_bf16 v[122:125], v[166:169], v[152:155], v[122:125]
	v_mfma_f32_16x16x32_bf16 v[118:121], v[174:177], v[144:147], v[118:121]
	v_mfma_f32_16x16x32_bf16 v[114:117], v[174:177], v[152:155], v[114:117]
	v_mfma_f32_16x16x32_bf16 v[110:113], v[182:185], v[144:147], v[110:113]
	v_mfma_f32_16x16x32_bf16 v[106:109], v[182:185], v[152:155], v[106:109]
	s_waitcnt lgkmcnt(0)
	v_mfma_f32_16x16x32_bf16 v[102:105], v[190:193], v[144:147], v[102:105]
	v_mfma_f32_16x16x32_bf16 v[98:101], v[190:193], v[152:155], v[98:101]
	s_setprio 0
	s_barrier
	v_lshl_add_u64 v[224:225], v[132:133], 0, s[8:9]
	s_mov_b32 m0, s87
	v_lshl_add_u64 v[226:227], v[224:225], 0, s[22:23]
	ds_read_b128 v[194:197], v213
	ds_read_b128 v[198:201], v213 offset:1024
	ds_read_b128 v[202:205], v213 offset:2048
	ds_read_b128 v[220:223], v213 offset:3072
	global_load_lds_dwordx4 v[226:227], off
	v_lshl_add_u64 v[226:227], v[134:135], 0, s[8:9]
	v_lshl_add_u64 v[228:229], v[226:227], 0, s[22:23]
	s_mov_b32 m0, s88
	s_nop 0
	global_load_lds_dwordx4 v[228:229], off
	s_barrier
	s_setprio 1
	s_waitcnt lgkmcnt(3)
	v_mfma_f32_16x16x32_bf16 v[94:97], v[156:159], v[194:197], v[94:97]
	s_waitcnt lgkmcnt(1)
	v_mfma_f32_16x16x32_bf16 v[90:93], v[156:159], v[202:205], v[90:93]
	v_mfma_f32_16x16x32_bf16 v[86:89], v[170:173], v[194:197], v[86:89]
	v_mfma_f32_16x16x32_bf16 v[82:85], v[170:173], v[202:205], v[82:85]
	v_mfma_f32_16x16x32_bf16 v[78:81], v[178:181], v[194:197], v[78:81]
	v_mfma_f32_16x16x32_bf16 v[74:77], v[178:181], v[202:205], v[74:77]
	v_mfma_f32_16x16x32_bf16 v[70:73], v[186:189], v[194:197], v[70:73]
	v_mfma_f32_16x16x32_bf16 v[66:69], v[186:189], v[202:205], v[66:69]
	v_mfma_f32_16x16x32_bf16 v[94:97], v[166:169], v[198:201], v[94:97]
	s_waitcnt lgkmcnt(0)
	v_mfma_f32_16x16x32_bf16 v[90:93], v[166:169], v[220:223], v[90:93]
	v_mfma_f32_16x16x32_bf16 v[86:89], v[174:177], v[198:201], v[86:89]
	v_mfma_f32_16x16x32_bf16 v[82:85], v[174:177], v[220:223], v[82:85]
	v_mfma_f32_16x16x32_bf16 v[78:81], v[182:185], v[198:201], v[78:81]
	v_mfma_f32_16x16x32_bf16 v[74:77], v[182:185], v[220:223], v[74:77]
	v_mfma_f32_16x16x32_bf16 v[70:73], v[190:193], v[198:201], v[70:73]
	v_mfma_f32_16x16x32_bf16 v[66:69], v[190:193], v[220:223], v[66:69]
	s_setprio 0
	s_mov_b32 m0, s14
	v_lshl_add_u64 v[228:229], v[160:161], 0, s[22:23]
	s_barrier
	ds_read_b128 v[156:159], v209 offset:16384
	ds_read_b128 v[166:169], v209 offset:17408
	ds_read_b128 v[170:173], v210 offset:16384
	ds_read_b128 v[174:177], v210 offset:17408
	ds_read_b128 v[178:181], v211 offset:16384
	ds_read_b128 v[182:185], v211 offset:17408
	ds_read_b128 v[186:189], v212 offset:16384
	ds_read_b128 v[190:193], v212 offset:17408
	global_load_lds_dwordx4 v[228:229], off
	v_lshl_add_u64 v[228:229], v[206:207], 0, s[22:23]
	s_mov_b32 m0, s89
	s_nop 0
	global_load_lds_dwordx4 v[228:229], off
	s_barrier
	s_setprio 1
	s_waitcnt lgkmcnt(7)
	v_mfma_f32_16x16x32_bf16 v[62:65], v[156:159], v[140:143], v[62:65]
	v_mfma_f32_16x16x32_bf16 v[58:61], v[156:159], v[148:151], v[58:61]
	s_waitcnt lgkmcnt(5)
	v_mfma_f32_16x16x32_bf16 v[54:57], v[170:173], v[140:143], v[54:57]
	v_mfma_f32_16x16x32_bf16 v[50:53], v[170:173], v[148:151], v[50:53]
	s_waitcnt lgkmcnt(3)
	v_mfma_f32_16x16x32_bf16 v[46:49], v[178:181], v[140:143], v[46:49]
	v_mfma_f32_16x16x32_bf16 v[42:45], v[178:181], v[148:151], v[42:45]
	s_waitcnt lgkmcnt(1)
	v_mfma_f32_16x16x32_bf16 v[38:41], v[186:189], v[140:143], v[38:41]
	v_mfma_f32_16x16x32_bf16 v[34:37], v[186:189], v[148:151], v[34:37]
	v_mfma_f32_16x16x32_bf16 v[62:65], v[166:169], v[144:147], v[62:65]
	v_mfma_f32_16x16x32_bf16 v[58:61], v[166:169], v[152:155], v[58:61]
	v_mfma_f32_16x16x32_bf16 v[54:57], v[174:177], v[144:147], v[54:57]
	v_mfma_f32_16x16x32_bf16 v[50:53], v[174:177], v[152:155], v[50:53]
	v_mfma_f32_16x16x32_bf16 v[46:49], v[182:185], v[144:147], v[46:49]
	v_mfma_f32_16x16x32_bf16 v[42:45], v[182:185], v[152:155], v[42:45]
	s_waitcnt lgkmcnt(0)
	v_mfma_f32_16x16x32_bf16 v[38:41], v[190:193], v[144:147], v[38:41]
	v_mfma_f32_16x16x32_bf16 v[34:37], v[190:193], v[152:155], v[34:37]
	s_setprio 0
	s_barrier
	s_mov_b32 m0, s90
	v_lshl_add_u64 v[140:141], v[224:225], 0, s[24:25]
	global_load_lds_dwordx4 v[140:141], off
	v_lshl_add_u64 v[140:141], v[226:227], 0, s[24:25]
	s_mov_b32 m0, s91
	s_nop 0
	global_load_lds_dwordx4 v[140:141], off
	s_waitcnt vmcnt(6)
	s_barrier
	s_setprio 1
	v_mfma_f32_16x16x32_bf16 v[30:33], v[156:159], v[194:197], v[30:33]
	v_mfma_f32_16x16x32_bf16 v[26:29], v[156:159], v[202:205], v[26:29]
	v_mfma_f32_16x16x32_bf16 v[22:25], v[170:173], v[194:197], v[22:25]
	v_mfma_f32_16x16x32_bf16 v[18:21], v[170:173], v[202:205], v[18:21]
	v_mfma_f32_16x16x32_bf16 v[14:17], v[178:181], v[194:197], v[14:17]
	v_mfma_f32_16x16x32_bf16 v[10:13], v[178:181], v[202:205], v[10:13]
	v_mfma_f32_16x16x32_bf16 v[6:9], v[186:189], v[194:197], v[6:9]
	v_mfma_f32_16x16x32_bf16 v[2:5], v[186:189], v[202:205], v[2:5]
	v_mfma_f32_16x16x32_bf16 v[30:33], v[166:169], v[198:201], v[30:33]
	v_mfma_f32_16x16x32_bf16 v[26:29], v[166:169], v[220:223], v[26:29]
	v_mfma_f32_16x16x32_bf16 v[22:25], v[174:177], v[198:201], v[22:25]
	v_mfma_f32_16x16x32_bf16 v[18:21], v[174:177], v[220:223], v[18:21]
	v_mfma_f32_16x16x32_bf16 v[14:17], v[182:185], v[198:201], v[14:17]
	v_mfma_f32_16x16x32_bf16 v[10:13], v[182:185], v[220:223], v[10:13]
	v_mfma_f32_16x16x32_bf16 v[6:9], v[190:193], v[198:201], v[6:9]
	v_mfma_f32_16x16x32_bf16 v[2:5], v[190:193], v[220:223], v[2:5]
	s_setprio 0
	s_barrier
	ds_read_b128 v[140:143], v214
	ds_read_b128 v[144:147], v214 offset:1024
	ds_read_b128 v[148:151], v214 offset:2048
	ds_read_b128 v[152:155], v214 offset:3072
	s_mov_b32 m0, s95
	v_lshl_add_u64 v[194:195], v[160:161], 0, s[24:25]
	ds_read_b128 v[156:159], v209 offset:32768
	ds_read_b128 v[166:169], v209 offset:33792
	ds_read_b128 v[170:173], v210 offset:32768
	ds_read_b128 v[174:177], v210 offset:33792
	ds_read_b128 v[178:181], v211 offset:32768
	ds_read_b128 v[182:185], v211 offset:33792
	ds_read_b128 v[186:189], v212 offset:32768
	ds_read_b128 v[190:193], v212 offset:33792
	global_load_lds_dwordx4 v[194:195], off
	v_lshl_add_u64 v[194:195], v[206:207], 0, s[24:25]
	s_mov_b32 m0, s97
	s_nop 0
	global_load_lds_dwordx4 v[194:195], off
	s_waitcnt lgkmcnt(8)
	s_barrier
	s_setprio 1
	s_waitcnt lgkmcnt(7)
	v_mfma_f32_16x16x32_bf16 v[126:129], v[156:159], v[140:143], v[126:129]
	v_mfma_f32_16x16x32_bf16 v[122:125], v[156:159], v[148:151], v[122:125]
	s_waitcnt lgkmcnt(5)
	v_mfma_f32_16x16x32_bf16 v[118:121], v[170:173], v[140:143], v[118:121]
	v_mfma_f32_16x16x32_bf16 v[114:117], v[170:173], v[148:151], v[114:117]
	s_waitcnt lgkmcnt(3)
	v_mfma_f32_16x16x32_bf16 v[110:113], v[178:181], v[140:143], v[110:113]
	v_mfma_f32_16x16x32_bf16 v[106:109], v[178:181], v[148:151], v[106:109]
	s_waitcnt lgkmcnt(1)
	v_mfma_f32_16x16x32_bf16 v[102:105], v[186:189], v[140:143], v[102:105]
	v_mfma_f32_16x16x32_bf16 v[98:101], v[186:189], v[148:151], v[98:101]
	v_mfma_f32_16x16x32_bf16 v[126:129], v[166:169], v[144:147], v[126:129]
	v_mfma_f32_16x16x32_bf16 v[122:125], v[166:169], v[152:155], v[122:125]
	v_mfma_f32_16x16x32_bf16 v[118:121], v[174:177], v[144:147], v[118:121]
	v_mfma_f32_16x16x32_bf16 v[114:117], v[174:177], v[152:155], v[114:117]
	v_mfma_f32_16x16x32_bf16 v[110:113], v[182:185], v[144:147], v[110:113]
	v_mfma_f32_16x16x32_bf16 v[106:109], v[182:185], v[152:155], v[106:109]
	s_waitcnt lgkmcnt(0)
	v_mfma_f32_16x16x32_bf16 v[102:105], v[190:193], v[144:147], v[102:105]
	v_mfma_f32_16x16x32_bf16 v[98:101], v[190:193], v[152:155], v[98:101]
	s_setprio 0
	s_barrier
	s_mov_b32 m0, vcc_lo
	v_lshl_add_u64 v[228:229], v[224:225], 0, s[26:27]
	ds_read_b128 v[194:197], v215
	ds_read_b128 v[198:201], v215 offset:1024
	ds_read_b128 v[202:205], v215 offset:2048
	ds_read_b128 v[220:223], v215 offset:3072
	global_load_lds_dwordx4 v[228:229], off
	v_lshl_add_u64 v[228:229], v[226:227], 0, s[26:27]
	s_mov_b32 m0, vcc_hi
	s_nop 0
	global_load_lds_dwordx4 v[228:229], off
	s_barrier
	s_setprio 1
	s_waitcnt lgkmcnt(3)
	v_mfma_f32_16x16x32_bf16 v[94:97], v[156:159], v[194:197], v[94:97]
	s_waitcnt lgkmcnt(1)
	v_mfma_f32_16x16x32_bf16 v[90:93], v[156:159], v[202:205], v[90:93]
	v_mfma_f32_16x16x32_bf16 v[86:89], v[170:173], v[194:197], v[86:89]
	v_mfma_f32_16x16x32_bf16 v[82:85], v[170:173], v[202:205], v[82:85]
	v_mfma_f32_16x16x32_bf16 v[78:81], v[178:181], v[194:197], v[78:81]
	v_mfma_f32_16x16x32_bf16 v[74:77], v[178:181], v[202:205], v[74:77]
	v_mfma_f32_16x16x32_bf16 v[70:73], v[186:189], v[194:197], v[70:73]
	v_mfma_f32_16x16x32_bf16 v[66:69], v[186:189], v[202:205], v[66:69]
	v_mfma_f32_16x16x32_bf16 v[94:97], v[166:169], v[198:201], v[94:97]
	s_waitcnt lgkmcnt(0)
	v_mfma_f32_16x16x32_bf16 v[90:93], v[166:169], v[220:223], v[90:93]
	v_mfma_f32_16x16x32_bf16 v[86:89], v[174:177], v[198:201], v[86:89]
	v_mfma_f32_16x16x32_bf16 v[82:85], v[174:177], v[220:223], v[82:85]
	v_mfma_f32_16x16x32_bf16 v[78:81], v[182:185], v[198:201], v[78:81]
	v_mfma_f32_16x16x32_bf16 v[74:77], v[182:185], v[220:223], v[74:77]
	v_mfma_f32_16x16x32_bf16 v[70:73], v[190:193], v[198:201], v[70:73]
	v_mfma_f32_16x16x32_bf16 v[66:69], v[190:193], v[220:223], v[66:69]
	s_setprio 0
	s_mov_b32 m0, s30
	v_lshl_add_u64 v[160:161], v[160:161], 0, s[26:27]
	s_barrier
	ds_read_b128 v[156:159], v209 offset:49152
	ds_read_b128 v[166:169], v209 offset:50176
	ds_read_b128 v[170:173], v210 offset:49152
	ds_read_b128 v[174:177], v210 offset:50176
	ds_read_b128 v[178:181], v211 offset:49152
	ds_read_b128 v[182:185], v211 offset:50176
	ds_read_b128 v[186:189], v212 offset:49152
	ds_read_b128 v[190:193], v212 offset:50176
	global_load_lds_dwordx4 v[160:161], off
	v_lshl_add_u64 v[160:161], v[206:207], 0, s[26:27]
	s_mov_b32 m0, s31
	s_nop 0
	global_load_lds_dwordx4 v[160:161], off
	s_barrier
	s_setprio 1
	s_waitcnt lgkmcnt(7)
	v_mfma_f32_16x16x32_bf16 v[62:65], v[156:159], v[140:143], v[62:65]
	v_mfma_f32_16x16x32_bf16 v[58:61], v[156:159], v[148:151], v[58:61]
	s_waitcnt lgkmcnt(5)
	v_mfma_f32_16x16x32_bf16 v[54:57], v[170:173], v[140:143], v[54:57]
	v_mfma_f32_16x16x32_bf16 v[50:53], v[170:173], v[148:151], v[50:53]
	s_waitcnt lgkmcnt(3)
	v_mfma_f32_16x16x32_bf16 v[46:49], v[178:181], v[140:143], v[46:49]
	v_mfma_f32_16x16x32_bf16 v[42:45], v[178:181], v[148:151], v[42:45]
	s_waitcnt lgkmcnt(1)
	v_mfma_f32_16x16x32_bf16 v[38:41], v[186:189], v[140:143], v[38:41]
	v_mfma_f32_16x16x32_bf16 v[34:37], v[186:189], v[148:151], v[34:37]
	v_mfma_f32_16x16x32_bf16 v[62:65], v[166:169], v[144:147], v[62:65]
	v_mfma_f32_16x16x32_bf16 v[58:61], v[166:169], v[152:155], v[58:61]
	v_mfma_f32_16x16x32_bf16 v[54:57], v[174:177], v[144:147], v[54:57]
	v_mfma_f32_16x16x32_bf16 v[50:53], v[174:177], v[152:155], v[50:53]
	v_mfma_f32_16x16x32_bf16 v[46:49], v[182:185], v[144:147], v[46:49]
	v_mfma_f32_16x16x32_bf16 v[42:45], v[182:185], v[152:155], v[42:45]
	s_waitcnt lgkmcnt(0)
	v_mfma_f32_16x16x32_bf16 v[38:41], v[190:193], v[144:147], v[38:41]
	v_mfma_f32_16x16x32_bf16 v[34:37], v[190:193], v[152:155], v[34:37]
	s_setprio 0
	s_barrier
	s_mov_b32 m0, s28
	v_lshl_add_u64 v[140:141], v[224:225], 0, s[16:17]
	global_load_lds_dwordx4 v[140:141], off
	v_lshl_add_u64 v[140:141], v[226:227], 0, s[16:17]
	s_mov_b32 m0, s29
	s_nop 0
	global_load_lds_dwordx4 v[140:141], off
	s_waitcnt vmcnt(6)
	s_barrier
	s_setprio 1
	v_mfma_f32_16x16x32_bf16 v[30:33], v[156:159], v[194:197], v[30:33]
	v_mfma_f32_16x16x32_bf16 v[26:29], v[156:159], v[202:205], v[26:29]
	v_mfma_f32_16x16x32_bf16 v[22:25], v[170:173], v[194:197], v[22:25]
	v_mfma_f32_16x16x32_bf16 v[18:21], v[170:173], v[202:205], v[18:21]
	v_mfma_f32_16x16x32_bf16 v[14:17], v[178:181], v[194:197], v[14:17]
	v_mfma_f32_16x16x32_bf16 v[10:13], v[178:181], v[202:205], v[10:13]
	v_mfma_f32_16x16x32_bf16 v[6:9], v[186:189], v[194:197], v[6:9]
	v_mfma_f32_16x16x32_bf16 v[2:5], v[186:189], v[202:205], v[2:5]
	v_mfma_f32_16x16x32_bf16 v[30:33], v[166:169], v[198:201], v[30:33]
	v_mfma_f32_16x16x32_bf16 v[26:29], v[166:169], v[220:223], v[26:29]
	v_mfma_f32_16x16x32_bf16 v[22:25], v[174:177], v[198:201], v[22:25]
	v_mfma_f32_16x16x32_bf16 v[18:21], v[174:177], v[220:223], v[18:21]
	v_mfma_f32_16x16x32_bf16 v[14:17], v[182:185], v[198:201], v[14:17]
	v_mfma_f32_16x16x32_bf16 v[10:13], v[182:185], v[220:223], v[10:13]
	v_mfma_f32_16x16x32_bf16 v[6:9], v[190:193], v[198:201], v[6:9]
	v_mfma_f32_16x16x32_bf16 v[2:5], v[190:193], v[220:223], v[2:5]
	s_setprio 0
	s_add_i32 s11, s11, 2
	s_add_u32 s8, s8, 0x100
	s_addc_u32 s9, s9, 0
	s_cmp_lt_u32 s11, 12
	s_barrier
	s_cbranch_scc1 .LBB0_188
	s_add_u32 s8, s92, 0x40780
	s_addc_u32 s9, s93, 0
	s_mov_b32 m0, s13
	v_lshl_add_u64 v[160:161], v[164:165], 1, s[8:9]
	ds_read_b128 v[132:135], v208
	ds_read_b128 v[136:139], v208 offset:1024
	ds_read_b128 v[140:143], v208 offset:2048
	ds_read_b128 v[144:147], v208 offset:3072
	ds_read_b128 v[148:151], v209
	ds_read_b128 v[152:155], v209 offset:1024
	ds_read_b128 v[156:159], v210
	ds_read_b128 v[166:169], v210 offset:1024
	ds_read_b128 v[170:173], v211
	ds_read_b128 v[174:177], v211 offset:1024
	ds_read_b128 v[178:181], v212
	ds_read_b128 v[182:185], v212 offset:1024
	global_load_lds_dwordx4 v[160:161], off
	v_lshl_add_u64 v[130:131], v[130:131], 1, s[8:9]
	s_mov_b32 m0, s12
	s_nop 0
	global_load_lds_dwordx4 v[130:131], off
	s_barrier
	s_waitcnt lgkmcnt(0)
	s_setprio 1
	s_waitcnt lgkmcnt(0)
	v_mfma_f32_16x16x32_bf16 v[126:129], v[148:151], v[132:135], v[126:129]
	v_mfma_f32_16x16x32_bf16 v[122:125], v[148:151], v[140:143], v[122:125]
	v_mfma_f32_16x16x32_bf16 v[118:121], v[156:159], v[132:135], v[118:121]
	v_mfma_f32_16x16x32_bf16 v[106:109], v[170:173], v[140:143], v[106:109]
	v_mfma_f32_16x16x32_bf16 v[102:105], v[178:181], v[132:135], v[102:105]
	v_mfma_f32_16x16x32_bf16 v[126:129], v[152:155], v[136:139], v[126:129]
	v_mfma_f32_16x16x32_bf16 v[122:125], v[152:155], v[144:147], v[122:125]
	v_mfma_f32_16x16x32_bf16 v[118:121], v[166:169], v[136:139], v[118:121]
	v_mfma_f32_16x16x32_bf16 v[114:117], v[156:159], v[140:143], v[114:117]
	v_mfma_f32_16x16x32_bf16 v[110:113], v[170:173], v[132:135], v[110:113]
	v_mfma_f32_16x16x32_bf16 v[106:109], v[174:177], v[144:147], v[106:109]
	v_mfma_f32_16x16x32_bf16 v[102:105], v[182:185], v[136:139], v[102:105]
	v_mfma_f32_16x16x32_bf16 v[98:101], v[178:181], v[140:143], v[98:101]
	v_mfma_f32_16x16x32_bf16 v[186:189], v[166:169], v[144:147], v[114:117]
	v_mfma_f32_16x16x32_bf16 v[190:193], v[174:177], v[136:139], v[110:113]
	v_mfma_f32_16x16x32_bf16 v[194:197], v[182:185], v[144:147], v[98:101]
	s_setprio 0
	s_barrier
	s_nop 2
	ds_read_b128 v[98:101], v213
	ds_read_b128 v[110:113], v213 offset:1024
	ds_read_b128 v[114:117], v213 offset:2048
	ds_read_b128 v[198:201], v213 offset:3072
	s_barrier
	s_waitcnt lgkmcnt(0)
	s_setprio 1
	s_waitcnt lgkmcnt(0)
	v_mfma_f32_16x16x32_bf16 v[90:93], v[148:151], v[114:117], v[90:93]
	v_mfma_f32_16x16x32_bf16 v[86:89], v[156:159], v[98:101], v[86:89]
	v_mfma_f32_16x16x32_bf16 v[74:77], v[170:173], v[114:117], v[74:77]
	v_mfma_f32_16x16x32_bf16 v[70:73], v[178:181], v[98:101], v[70:73]
	v_mfma_f32_16x16x32_bf16 v[66:69], v[178:181], v[114:117], v[66:69]
	v_mfma_f32_16x16x32_bf16 v[94:97], v[148:151], v[98:101], v[94:97]
	v_mfma_f32_16x16x32_bf16 v[90:93], v[152:155], v[198:201], v[90:93]
	v_mfma_f32_16x16x32_bf16 v[86:89], v[166:169], v[110:113], v[86:89]
	v_mfma_f32_16x16x32_bf16 v[82:85], v[156:159], v[114:117], v[82:85]
	v_mfma_f32_16x16x32_bf16 v[78:81], v[170:173], v[98:101], v[78:81]
	v_mfma_f32_16x16x32_bf16 v[74:77], v[174:177], v[198:201], v[74:77]
	v_mfma_f32_16x16x32_bf16 v[70:73], v[182:185], v[110:113], v[70:73]
	v_mfma_f32_16x16x32_bf16 v[66:69], v[182:185], v[198:201], v[66:69]
	v_mfma_f32_16x16x32_bf16 v[202:205], v[152:155], v[110:113], v[94:97]
	v_mfma_f32_16x16x32_bf16 v[148:151], v[166:169], v[198:201], v[82:85]
	v_mfma_f32_16x16x32_bf16 v[152:155], v[174:177], v[110:113], v[78:81]
	s_setprio 0
	s_barrier
	s_nop 0
	ds_read_b128 v[78:81], v209 offset:16384
	ds_read_b128 v[82:85], v209 offset:17408
	ds_read_b128 v[94:97], v210 offset:16384
	ds_read_b128 v[156:159], v210 offset:17408
	ds_read_b128 v[166:169], v211 offset:16384
	ds_read_b128 v[170:173], v211 offset:17408
	ds_read_b128 v[174:177], v212 offset:16384
	ds_read_b128 v[178:181], v212 offset:17408
	s_waitcnt vmcnt(4)
	s_barrier
	s_waitcnt lgkmcnt(0)
	s_setprio 1
	s_waitcnt lgkmcnt(0)
	v_mfma_f32_16x16x32_bf16 v[58:61], v[78:81], v[140:143], v[58:61]
	v_mfma_f32_16x16x32_bf16 v[50:53], v[94:97], v[140:143], v[50:53]
	v_mfma_f32_16x16x32_bf16 v[42:45], v[166:169], v[140:143], v[42:45]
	v_mfma_f32_16x16x32_bf16 v[34:37], v[174:177], v[140:143], v[34:37]
	v_mfma_f32_16x16x32_bf16 v[62:65], v[78:81], v[132:135], v[62:65]
	v_mfma_f32_16x16x32_bf16 v[58:61], v[82:85], v[144:147], v[58:61]
	v_mfma_f32_16x16x32_bf16 v[54:57], v[94:97], v[132:135], v[54:57]
	v_mfma_f32_16x16x32_bf16 v[50:53], v[156:159], v[144:147], v[50:53]
	v_mfma_f32_16x16x32_bf16 v[46:49], v[166:169], v[132:135], v[46:49]
	v_mfma_f32_16x16x32_bf16 v[42:45], v[170:173], v[144:147], v[42:45]
	v_mfma_f32_16x16x32_bf16 v[38:41], v[174:177], v[132:135], v[38:41]
	v_mfma_f32_16x16x32_bf16 v[34:37], v[178:181], v[144:147], v[34:37]
	v_mfma_f32_16x16x32_bf16 v[182:185], v[82:85], v[136:139], v[62:65]
	v_mfma_f32_16x16x32_bf16 v[220:223], v[156:159], v[136:139], v[54:57]
	v_mfma_f32_16x16x32_bf16 v[224:227], v[170:173], v[136:139], v[46:49]
	v_mfma_f32_16x16x32_bf16 v[130:133], v[178:181], v[136:139], v[38:41]
	s_setprio 0
	s_setprio 1
	v_mfma_f32_16x16x32_bf16 v[26:29], v[78:81], v[114:117], v[26:29]
	v_mfma_f32_16x16x32_bf16 v[18:21], v[94:97], v[114:117], v[18:21]
	v_mfma_f32_16x16x32_bf16 v[10:13], v[166:169], v[114:117], v[10:13]
	v_mfma_f32_16x16x32_bf16 v[2:5], v[174:177], v[114:117], v[2:5]
	v_mfma_f32_16x16x32_bf16 v[30:33], v[78:81], v[98:101], v[30:33]
	v_mfma_f32_16x16x32_bf16 v[26:29], v[82:85], v[198:201], v[26:29]
	v_mfma_f32_16x16x32_bf16 v[22:25], v[94:97], v[98:101], v[22:25]
	v_mfma_f32_16x16x32_bf16 v[18:21], v[156:159], v[198:201], v[18:21]
	v_mfma_f32_16x16x32_bf16 v[14:17], v[166:169], v[98:101], v[14:17]
	v_mfma_f32_16x16x32_bf16 v[10:13], v[170:173], v[198:201], v[10:13]
	v_mfma_f32_16x16x32_bf16 v[6:9], v[174:177], v[98:101], v[6:9]
	v_mfma_f32_16x16x32_bf16 v[2:5], v[178:181], v[198:201], v[2:5]
	v_mfma_f32_16x16x32_bf16 v[134:137], v[82:85], v[110:113], v[30:33]
	v_mfma_f32_16x16x32_bf16 v[138:141], v[156:159], v[110:113], v[22:25]
	v_mfma_f32_16x16x32_bf16 v[142:145], v[170:173], v[110:113], v[14:17]
	v_mfma_f32_16x16x32_bf16 v[156:159], v[178:181], v[110:113], v[6:9]
	s_setprio 0
	s_barrier
	s_nop 0
	ds_read_b128 v[6:9], v214
	ds_read_b128 v[14:17], v214 offset:1024
	ds_read_b128 v[166:169], v214 offset:2048
	ds_read_b128 v[170:173], v214 offset:3072
	ds_read_b128 v[22:25], v209 offset:32768
	ds_read_b128 v[30:33], v209 offset:33792
	ds_read_b128 v[38:41], v210 offset:32768
	ds_read_b128 v[46:49], v210 offset:33792
	ds_read_b128 v[54:57], v211 offset:32768
	ds_read_b128 v[174:177], v211 offset:33792
	ds_read_b128 v[178:181], v212 offset:32768
	ds_read_b128 v[198:201], v212 offset:33792
	s_waitcnt vmcnt(2)
	s_barrier
	s_waitcnt lgkmcnt(0)
	s_setprio 1
	s_waitcnt lgkmcnt(0)
	v_mfma_f32_16x16x32_bf16 v[62:65], v[22:25], v[6:9], v[126:129]
	v_mfma_f32_16x16x32_bf16 v[126:129], v[30:33], v[14:17], v[62:65]
	v_mfma_f32_16x16x32_bf16 v[62:65], v[22:25], v[166:169], v[122:125]
	v_mfma_f32_16x16x32_bf16 v[114:117], v[30:33], v[170:173], v[62:65]
	v_mfma_f32_16x16x32_bf16 v[62:65], v[38:41], v[6:9], v[118:121]
	v_mfma_f32_16x16x32_bf16 v[110:113], v[46:49], v[14:17], v[62:65]
	v_mfma_f32_16x16x32_bf16 v[62:65], v[38:41], v[166:169], v[186:189]
	v_mfma_f32_16x16x32_bf16 v[98:101], v[46:49], v[170:173], v[62:65]
	v_mfma_f32_16x16x32_bf16 v[62:65], v[54:57], v[6:9], v[190:193]
	v_mfma_f32_16x16x32_bf16 v[94:97], v[174:177], v[14:17], v[62:65]
	v_mfma_f32_16x16x32_bf16 v[62:65], v[54:57], v[166:169], v[106:109]
	v_mfma_f32_16x16x32_bf16 v[82:85], v[174:177], v[170:173], v[62:65]
	v_mfma_f32_16x16x32_bf16 v[62:65], v[178:181], v[6:9], v[102:105]
	v_mfma_f32_16x16x32_bf16 v[78:81], v[198:201], v[14:17], v[62:65]
	v_mfma_f32_16x16x32_bf16 v[62:65], v[178:181], v[166:169], v[194:197]
	v_mfma_f32_16x16x32_bf16 v[62:65], v[198:201], v[170:173], v[62:65]
	s_setprio 0
	s_barrier
	ds_read_b128 v[186:189], v215
	ds_read_b128 v[190:193], v215 offset:1024
	ds_read_b128 v[194:197], v215 offset:2048
	ds_read_b128 v[228:231], v215 offset:3072
	s_waitcnt vmcnt(0)
	s_barrier
	s_waitcnt lgkmcnt(0)
	s_setprio 1
	s_waitcnt lgkmcnt(0)
	v_mfma_f32_16x16x32_bf16 v[102:105], v[22:25], v[186:189], v[202:205]
	v_mfma_f32_16x16x32_bf16 v[22:25], v[22:25], v[194:197], v[90:93]
	v_mfma_f32_16x16x32_bf16 v[118:121], v[30:33], v[228:231], v[22:25]
	v_mfma_f32_16x16x32_bf16 v[22:25], v[38:41], v[186:189], v[86:89]
	v_mfma_f32_16x16x32_bf16 v[106:109], v[46:49], v[190:193], v[22:25]
	v_mfma_f32_16x16x32_bf16 v[22:25], v[38:41], v[194:197], v[148:151]
	v_mfma_f32_16x16x32_bf16 v[122:125], v[30:33], v[190:193], v[102:105]
	v_mfma_f32_16x16x32_bf16 v[102:105], v[46:49], v[228:231], v[22:25]
	v_mfma_f32_16x16x32_bf16 v[22:25], v[54:57], v[186:189], v[152:155]
	v_mfma_f32_16x16x32_bf16 v[90:93], v[174:177], v[190:193], v[22:25]
	v_mfma_f32_16x16x32_bf16 v[22:25], v[54:57], v[194:197], v[74:77]
	v_mfma_f32_16x16x32_bf16 v[86:89], v[174:177], v[228:231], v[22:25]
	v_mfma_f32_16x16x32_bf16 v[22:25], v[178:181], v[186:189], v[70:73]
	v_mfma_f32_16x16x32_bf16 v[74:77], v[198:201], v[190:193], v[22:25]
	v_mfma_f32_16x16x32_bf16 v[22:25], v[178:181], v[194:197], v[66:69]
	v_mfma_f32_16x16x32_bf16 v[70:73], v[198:201], v[228:231], v[22:25]
	s_setprio 0
	s_barrier
	ds_read_b128 v[146:149], v209 offset:49152
	ds_read_b128 v[150:153], v209 offset:50176
	ds_read_b128 v[174:177], v210 offset:49152
	ds_read_b128 v[178:181], v210 offset:50176
	ds_read_b128 v[198:201], v211 offset:49152
	ds_read_b128 v[202:205], v211 offset:50176
	ds_read_b128 v[232:235], v212 offset:49152
	ds_read_b128 v[236:239], v212 offset:50176
	s_barrier
	s_waitcnt lgkmcnt(0)
	s_setprio 1
	s_waitcnt lgkmcnt(0)
	v_mfma_f32_16x16x32_bf16 v[22:25], v[146:149], v[6:9], v[182:185]
	v_mfma_f32_16x16x32_bf16 v[66:69], v[150:153], v[14:17], v[22:25]
	v_mfma_f32_16x16x32_bf16 v[22:25], v[146:149], v[166:169], v[58:61]
	v_mfma_f32_16x16x32_bf16 v[54:57], v[150:153], v[170:173], v[22:25]
	v_mfma_f32_16x16x32_bf16 v[22:25], v[174:177], v[6:9], v[220:223]
	v_mfma_f32_16x16x32_bf16 v[46:49], v[178:181], v[14:17], v[22:25]
	v_mfma_f32_16x16x32_bf16 v[22:25], v[174:177], v[166:169], v[50:53]
	v_mfma_f32_16x16x32_bf16 v[38:41], v[178:181], v[170:173], v[22:25]
	v_mfma_f32_16x16x32_bf16 v[22:25], v[198:201], v[6:9], v[224:227]
	v_mfma_f32_16x16x32_bf16 v[6:9], v[232:235], v[6:9], v[130:133]
	v_mfma_f32_16x16x32_bf16 v[30:33], v[202:205], v[14:17], v[22:25]
	v_mfma_f32_16x16x32_bf16 v[22:25], v[198:201], v[166:169], v[42:45]
	v_mfma_f32_16x16x32_bf16 v[14:17], v[236:239], v[14:17], v[6:9]
	v_mfma_f32_16x16x32_bf16 v[6:9], v[232:235], v[166:169], v[34:37]
	v_mfma_f32_16x16x32_bf16 v[22:25], v[202:205], v[170:173], v[22:25]
	v_mfma_f32_16x16x32_bf16 v[6:9], v[236:239], v[170:173], v[6:9]
	s_setprio 0
	s_setprio 1
	v_mfma_f32_16x16x32_bf16 v[34:37], v[146:149], v[186:189], v[134:137]
	v_mfma_f32_16x16x32_bf16 v[26:29], v[146:149], v[194:197], v[26:29]
	v_mfma_f32_16x16x32_bf16 v[18:21], v[174:177], v[194:197], v[18:21]
	v_mfma_f32_16x16x32_bf16 v[58:61], v[150:153], v[190:193], v[34:37]
	v_mfma_f32_16x16x32_bf16 v[50:53], v[150:153], v[228:231], v[26:29]
	v_mfma_f32_16x16x32_bf16 v[26:29], v[174:177], v[186:189], v[138:141]
	v_mfma_f32_16x16x32_bf16 v[34:37], v[178:181], v[228:231], v[18:21]
	v_mfma_f32_16x16x32_bf16 v[18:21], v[198:201], v[186:189], v[142:145]
	v_mfma_f32_16x16x32_bf16 v[10:13], v[198:201], v[194:197], v[10:13]
	v_mfma_f32_16x16x32_bf16 v[42:45], v[178:181], v[190:193], v[26:29]
	v_mfma_f32_16x16x32_bf16 v[26:29], v[202:205], v[190:193], v[18:21]
	v_mfma_f32_16x16x32_bf16 v[18:21], v[202:205], v[228:231], v[10:13]
	v_mfma_f32_16x16x32_bf16 v[10:13], v[232:235], v[186:189], v[156:159]
	v_mfma_f32_16x16x32_bf16 v[2:5], v[232:235], v[194:197], v[2:5]
	v_mfma_f32_16x16x32_bf16 v[10:13], v[236:239], v[190:193], v[10:13]
	v_mfma_f32_16x16x32_bf16 v[2:5], v[236:239], v[228:231], v[2:5]
	s_setprio 0
	v_readlane_b32 s0, v248, 2
	v_readlane_b32 s1, v248, 3
	s_barrier
	s_and_saveexec_b64 s[8:9], s[0:1]
	s_cbranch_execz .LBB0_146
	s_barrier
	s_branch .LBB0_146

.LBB0_285:
	ds_read_b128 v[142:145], v161
	ds_read_b128 v[146:149], v161 offset:1024
	ds_read_b128 v[150:153], v161 offset:2048
	ds_read_b128 v[154:157], v161 offset:3072
	v_lshl_add_u64 v[158:159], v[138:139], 0, s[54:55]
	s_mov_b32 m0, s85
	v_lshl_add_u64 v[202:203], v[158:159], 0, s[18:19]
	v_lshl_add_u64 v[218:219], v[140:141], 0, s[54:55]
	ds_read_b128 v[170:173], v162
	ds_read_b128 v[174:177], v162 offset:1024
	ds_read_b128 v[178:181], v163
	ds_read_b128 v[182:185], v163 offset:1024
	ds_read_b128 v[186:189], v164
	ds_read_b128 v[190:193], v164 offset:1024
	ds_read_b128 v[194:197], v165
	ds_read_b128 v[198:201], v165 offset:1024
	global_load_lds_dwordx4 v[202:203], off
	v_lshl_add_u64 v[202:203], v[218:219], 0, s[18:19]
	s_mov_b32 m0, s75
	s_nop 0
	global_load_lds_dwordx4 v[202:203], off
	s_waitcnt lgkmcnt(8)
	s_barrier
	s_setprio 1
	s_waitcnt lgkmcnt(7)
	v_mfma_f32_16x16x32_bf16 v[126:129], v[170:173], v[142:145], v[126:129]
	v_mfma_f32_16x16x32_bf16 v[122:125], v[170:173], v[150:153], v[122:125]
	s_waitcnt lgkmcnt(5)
	v_mfma_f32_16x16x32_bf16 v[118:121], v[178:181], v[142:145], v[118:121]
	v_mfma_f32_16x16x32_bf16 v[114:117], v[178:181], v[150:153], v[114:117]
	s_waitcnt lgkmcnt(3)
	v_mfma_f32_16x16x32_bf16 v[110:113], v[186:189], v[142:145], v[110:113]
	v_mfma_f32_16x16x32_bf16 v[106:109], v[186:189], v[150:153], v[106:109]
	s_waitcnt lgkmcnt(1)
	v_mfma_f32_16x16x32_bf16 v[102:105], v[194:197], v[142:145], v[102:105]
	v_mfma_f32_16x16x32_bf16 v[98:101], v[194:197], v[150:153], v[98:101]
	v_mfma_f32_16x16x32_bf16 v[126:129], v[174:177], v[146:149], v[126:129]
	v_mfma_f32_16x16x32_bf16 v[122:125], v[174:177], v[154:157], v[122:125]
	v_mfma_f32_16x16x32_bf16 v[118:121], v[182:185], v[146:149], v[118:121]
	v_mfma_f32_16x16x32_bf16 v[114:117], v[182:185], v[154:157], v[114:117]
	v_mfma_f32_16x16x32_bf16 v[110:113], v[190:193], v[146:149], v[110:113]
	v_mfma_f32_16x16x32_bf16 v[106:109], v[190:193], v[154:157], v[106:109]
	s_waitcnt lgkmcnt(0)
	v_mfma_f32_16x16x32_bf16 v[102:105], v[198:201], v[146:149], v[102:105]
	v_mfma_f32_16x16x32_bf16 v[98:101], v[198:201], v[154:157], v[98:101]
	s_setprio 0
	s_barrier
	v_lshl_add_u64 v[220:221], v[134:135], 0, s[54:55]
	s_mov_b32 m0, s51
	v_lshl_add_u64 v[222:223], v[220:221], 0, s[20:21]
	ds_read_b128 v[202:205], v166
	ds_read_b128 v[206:209], v166 offset:1024
	ds_read_b128 v[210:213], v166 offset:2048
	ds_read_b128 v[214:217], v166 offset:3072
	global_load_lds_dwordx4 v[222:223], off
	v_lshl_add_u64 v[222:223], v[136:137], 0, s[54:55]
	v_lshl_add_u64 v[224:225], v[222:223], 0, s[20:21]
	s_mov_b32 m0, s67
	s_nop 0
	global_load_lds_dwordx4 v[224:225], off
	s_barrier
	s_setprio 1
	s_waitcnt lgkmcnt(3)
	v_mfma_f32_16x16x32_bf16 v[94:97], v[170:173], v[202:205], v[94:97]
	s_waitcnt lgkmcnt(1)
	v_mfma_f32_16x16x32_bf16 v[90:93], v[170:173], v[210:213], v[90:93]
	v_mfma_f32_16x16x32_bf16 v[86:89], v[178:181], v[202:205], v[86:89]
	v_mfma_f32_16x16x32_bf16 v[82:85], v[178:181], v[210:213], v[82:85]
	v_mfma_f32_16x16x32_bf16 v[78:81], v[186:189], v[202:205], v[78:81]
	v_mfma_f32_16x16x32_bf16 v[74:77], v[186:189], v[210:213], v[74:77]
	v_mfma_f32_16x16x32_bf16 v[70:73], v[194:197], v[202:205], v[70:73]
	v_mfma_f32_16x16x32_bf16 v[66:69], v[194:197], v[210:213], v[66:69]
	v_mfma_f32_16x16x32_bf16 v[94:97], v[174:177], v[206:209], v[94:97]
	s_waitcnt lgkmcnt(0)
	v_mfma_f32_16x16x32_bf16 v[90:93], v[174:177], v[214:217], v[90:93]
	v_mfma_f32_16x16x32_bf16 v[86:89], v[182:185], v[206:209], v[86:89]
	v_mfma_f32_16x16x32_bf16 v[82:85], v[182:185], v[214:217], v[82:85]
	v_mfma_f32_16x16x32_bf16 v[78:81], v[190:193], v[206:209], v[78:81]
	v_mfma_f32_16x16x32_bf16 v[74:77], v[190:193], v[214:217], v[74:77]
	v_mfma_f32_16x16x32_bf16 v[70:73], v[198:201], v[206:209], v[70:73]
	v_mfma_f32_16x16x32_bf16 v[66:69], v[198:201], v[214:217], v[66:69]
	s_setprio 0
	s_mov_b32 m0, s49
	v_lshl_add_u64 v[224:225], v[158:159], 0, s[20:21]
	s_barrier
	ds_read_b128 v[170:173], v162 offset:16384
	ds_read_b128 v[174:177], v162 offset:17408
	ds_read_b128 v[178:181], v163 offset:16384
	ds_read_b128 v[182:185], v163 offset:17408
	ds_read_b128 v[186:189], v164 offset:16384
	ds_read_b128 v[190:193], v164 offset:17408
	ds_read_b128 v[194:197], v165 offset:16384
	ds_read_b128 v[198:201], v165 offset:17408
	global_load_lds_dwordx4 v[224:225], off
	v_lshl_add_u64 v[224:225], v[218:219], 0, s[20:21]
	s_mov_b32 m0, s68
	s_nop 0
	global_load_lds_dwordx4 v[224:225], off
	s_barrier
	s_setprio 1
	s_waitcnt lgkmcnt(7)
	v_mfma_f32_16x16x32_bf16 v[62:65], v[170:173], v[142:145], v[62:65]
	v_mfma_f32_16x16x32_bf16 v[58:61], v[170:173], v[150:153], v[58:61]
	s_waitcnt lgkmcnt(5)
	v_mfma_f32_16x16x32_bf16 v[54:57], v[178:181], v[142:145], v[54:57]
	v_mfma_f32_16x16x32_bf16 v[50:53], v[178:181], v[150:153], v[50:53]
	s_waitcnt lgkmcnt(3)
	v_mfma_f32_16x16x32_bf16 v[46:49], v[186:189], v[142:145], v[46:49]
	v_mfma_f32_16x16x32_bf16 v[42:45], v[186:189], v[150:153], v[42:45]
	s_waitcnt lgkmcnt(1)
	v_mfma_f32_16x16x32_bf16 v[38:41], v[194:197], v[142:145], v[38:41]
	v_mfma_f32_16x16x32_bf16 v[34:37], v[194:197], v[150:153], v[34:37]
	v_mfma_f32_16x16x32_bf16 v[62:65], v[174:177], v[146:149], v[62:65]
	v_mfma_f32_16x16x32_bf16 v[58:61], v[174:177], v[154:157], v[58:61]
	v_mfma_f32_16x16x32_bf16 v[54:57], v[182:185], v[146:149], v[54:57]
	v_mfma_f32_16x16x32_bf16 v[50:53], v[182:185], v[154:157], v[50:53]
	v_mfma_f32_16x16x32_bf16 v[46:49], v[190:193], v[146:149], v[46:49]
	v_mfma_f32_16x16x32_bf16 v[42:45], v[190:193], v[154:157], v[42:45]
	s_waitcnt lgkmcnt(0)
	v_mfma_f32_16x16x32_bf16 v[38:41], v[198:201], v[146:149], v[38:41]
	v_mfma_f32_16x16x32_bf16 v[34:37], v[198:201], v[154:157], v[34:37]
	s_setprio 0
	s_barrier
	s_mov_b32 m0, s69
	v_lshl_add_u64 v[142:143], v[220:221], 0, s[22:23]
	global_load_lds_dwordx4 v[142:143], off
	v_lshl_add_u64 v[142:143], v[222:223], 0, s[22:23]
	s_mov_b32 m0, s70
	s_nop 0
	global_load_lds_dwordx4 v[142:143], off
	s_waitcnt vmcnt(6)
	s_barrier
	s_setprio 1
	v_mfma_f32_16x16x32_bf16 v[30:33], v[170:173], v[202:205], v[30:33]
	v_mfma_f32_16x16x32_bf16 v[26:29], v[170:173], v[210:213], v[26:29]
	v_mfma_f32_16x16x32_bf16 v[22:25], v[178:181], v[202:205], v[22:25]
	v_mfma_f32_16x16x32_bf16 v[18:21], v[178:181], v[210:213], v[18:21]
	v_mfma_f32_16x16x32_bf16 v[14:17], v[186:189], v[202:205], v[14:17]
	v_mfma_f32_16x16x32_bf16 v[10:13], v[186:189], v[210:213], v[10:13]
	v_mfma_f32_16x16x32_bf16 v[6:9], v[194:197], v[202:205], v[6:9]
	v_mfma_f32_16x16x32_bf16 v[2:5], v[194:197], v[210:213], v[2:5]
	v_mfma_f32_16x16x32_bf16 v[30:33], v[174:177], v[206:209], v[30:33]
	v_mfma_f32_16x16x32_bf16 v[26:29], v[174:177], v[214:217], v[26:29]
	v_mfma_f32_16x16x32_bf16 v[22:25], v[182:185], v[206:209], v[22:25]
	v_mfma_f32_16x16x32_bf16 v[18:21], v[182:185], v[214:217], v[18:21]
	v_mfma_f32_16x16x32_bf16 v[14:17], v[190:193], v[206:209], v[14:17]
	v_mfma_f32_16x16x32_bf16 v[10:13], v[190:193], v[214:217], v[10:13]
	v_mfma_f32_16x16x32_bf16 v[6:9], v[198:201], v[206:209], v[6:9]
	v_mfma_f32_16x16x32_bf16 v[2:5], v[198:201], v[214:217], v[2:5]
	s_setprio 0
	s_barrier
	ds_read_b128 v[142:145], v167
	ds_read_b128 v[146:149], v167 offset:1024
	ds_read_b128 v[150:153], v167 offset:2048
	ds_read_b128 v[154:157], v167 offset:3072
	s_mov_b32 m0, s71
	v_lshl_add_u64 v[202:203], v[158:159], 0, s[22:23]
	ds_read_b128 v[170:173], v162 offset:32768
	ds_read_b128 v[174:177], v162 offset:33792
	ds_read_b128 v[178:181], v163 offset:32768
	ds_read_b128 v[182:185], v163 offset:33792
	ds_read_b128 v[186:189], v164 offset:32768
	ds_read_b128 v[190:193], v164 offset:33792
	ds_read_b128 v[194:197], v165 offset:32768
	ds_read_b128 v[198:201], v165 offset:33792
	global_load_lds_dwordx4 v[202:203], off
	v_lshl_add_u64 v[202:203], v[218:219], 0, s[22:23]
	s_mov_b32 m0, s72
	s_nop 0
	global_load_lds_dwordx4 v[202:203], off
	s_waitcnt lgkmcnt(8)
	s_barrier
	s_setprio 1
	s_waitcnt lgkmcnt(7)
	v_mfma_f32_16x16x32_bf16 v[126:129], v[170:173], v[142:145], v[126:129]
	v_mfma_f32_16x16x32_bf16 v[122:125], v[170:173], v[150:153], v[122:125]
	s_waitcnt lgkmcnt(5)
	v_mfma_f32_16x16x32_bf16 v[118:121], v[178:181], v[142:145], v[118:121]
	v_mfma_f32_16x16x32_bf16 v[114:117], v[178:181], v[150:153], v[114:117]
	s_waitcnt lgkmcnt(3)
	v_mfma_f32_16x16x32_bf16 v[110:113], v[186:189], v[142:145], v[110:113]
	v_mfma_f32_16x16x32_bf16 v[106:109], v[186:189], v[150:153], v[106:109]
	s_waitcnt lgkmcnt(1)
	v_mfma_f32_16x16x32_bf16 v[102:105], v[194:197], v[142:145], v[102:105]
	v_mfma_f32_16x16x32_bf16 v[98:101], v[194:197], v[150:153], v[98:101]
	v_mfma_f32_16x16x32_bf16 v[126:129], v[174:177], v[146:149], v[126:129]
	v_mfma_f32_16x16x32_bf16 v[122:125], v[174:177], v[154:157], v[122:125]
	v_mfma_f32_16x16x32_bf16 v[118:121], v[182:185], v[146:149], v[118:121]
	v_mfma_f32_16x16x32_bf16 v[114:117], v[182:185], v[154:157], v[114:117]
	v_mfma_f32_16x16x32_bf16 v[110:113], v[190:193], v[146:149], v[110:113]
	v_mfma_f32_16x16x32_bf16 v[106:109], v[190:193], v[154:157], v[106:109]
	s_waitcnt lgkmcnt(0)
	v_mfma_f32_16x16x32_bf16 v[102:105], v[198:201], v[146:149], v[102:105]
	v_mfma_f32_16x16x32_bf16 v[98:101], v[198:201], v[154:157], v[98:101]
	s_setprio 0
	s_barrier
	s_mov_b32 m0, s58
	v_lshl_add_u64 v[224:225], v[220:221], 0, s[26:27]
	ds_read_b128 v[202:205], v168
	ds_read_b128 v[206:209], v168 offset:1024
	ds_read_b128 v[210:213], v168 offset:2048
	ds_read_b128 v[214:217], v168 offset:3072
	global_load_lds_dwordx4 v[224:225], off
	v_lshl_add_u64 v[224:225], v[222:223], 0, s[26:27]
	s_mov_b32 m0, s59
	s_nop 0
	global_load_lds_dwordx4 v[224:225], off
	s_barrier
	s_setprio 1
	s_waitcnt lgkmcnt(3)
	v_mfma_f32_16x16x32_bf16 v[94:97], v[170:173], v[202:205], v[94:97]
	s_waitcnt lgkmcnt(1)
	v_mfma_f32_16x16x32_bf16 v[90:93], v[170:173], v[210:213], v[90:93]
	v_mfma_f32_16x16x32_bf16 v[86:89], v[178:181], v[202:205], v[86:89]
	v_mfma_f32_16x16x32_bf16 v[82:85], v[178:181], v[210:213], v[82:85]
	v_mfma_f32_16x16x32_bf16 v[78:81], v[186:189], v[202:205], v[78:81]
	v_mfma_f32_16x16x32_bf16 v[74:77], v[186:189], v[210:213], v[74:77]
	v_mfma_f32_16x16x32_bf16 v[70:73], v[194:197], v[202:205], v[70:73]
	v_mfma_f32_16x16x32_bf16 v[66:69], v[194:197], v[210:213], v[66:69]
	v_mfma_f32_16x16x32_bf16 v[94:97], v[174:177], v[206:209], v[94:97]
	s_waitcnt lgkmcnt(0)
	v_mfma_f32_16x16x32_bf16 v[90:93], v[174:177], v[214:217], v[90:93]
	v_mfma_f32_16x16x32_bf16 v[86:89], v[182:185], v[206:209], v[86:89]
	v_mfma_f32_16x16x32_bf16 v[82:85], v[182:185], v[214:217], v[82:85]
	v_mfma_f32_16x16x32_bf16 v[78:81], v[190:193], v[206:209], v[78:81]
	v_mfma_f32_16x16x32_bf16 v[74:77], v[190:193], v[214:217], v[74:77]
	v_mfma_f32_16x16x32_bf16 v[70:73], v[198:201], v[206:209], v[70:73]
	v_mfma_f32_16x16x32_bf16 v[66:69], v[198:201], v[214:217], v[66:69]
	s_setprio 0
	s_mov_b32 m0, s73
	v_lshl_add_u64 v[158:159], v[158:159], 0, s[26:27]
	s_barrier
	ds_read_b128 v[170:173], v162 offset:49152
	ds_read_b128 v[174:177], v162 offset:50176
	ds_read_b128 v[178:181], v163 offset:49152
	ds_read_b128 v[182:185], v163 offset:50176
	ds_read_b128 v[186:189], v164 offset:49152
	ds_read_b128 v[190:193], v164 offset:50176
	ds_read_b128 v[194:197], v165 offset:49152
	ds_read_b128 v[198:201], v165 offset:50176
	global_load_lds_dwordx4 v[158:159], off
	v_lshl_add_u64 v[158:159], v[218:219], 0, s[26:27]
	s_mov_b32 m0, s74
	s_nop 0
	global_load_lds_dwordx4 v[158:159], off
	s_barrier
	s_setprio 1
	s_waitcnt lgkmcnt(7)
	v_mfma_f32_16x16x32_bf16 v[62:65], v[170:173], v[142:145], v[62:65]
	v_mfma_f32_16x16x32_bf16 v[58:61], v[170:173], v[150:153], v[58:61]
	s_waitcnt lgkmcnt(5)
	v_mfma_f32_16x16x32_bf16 v[54:57], v[178:181], v[142:145], v[54:57]
	v_mfma_f32_16x16x32_bf16 v[50:53], v[178:181], v[150:153], v[50:53]
	s_waitcnt lgkmcnt(3)
	v_mfma_f32_16x16x32_bf16 v[46:49], v[186:189], v[142:145], v[46:49]
	v_mfma_f32_16x16x32_bf16 v[42:45], v[186:189], v[150:153], v[42:45]
	s_waitcnt lgkmcnt(1)
	v_mfma_f32_16x16x32_bf16 v[38:41], v[194:197], v[142:145], v[38:41]
	v_mfma_f32_16x16x32_bf16 v[34:37], v[194:197], v[150:153], v[34:37]
	v_mfma_f32_16x16x32_bf16 v[62:65], v[174:177], v[146:149], v[62:65]
	v_mfma_f32_16x16x32_bf16 v[58:61], v[174:177], v[154:157], v[58:61]
	v_mfma_f32_16x16x32_bf16 v[54:57], v[182:185], v[146:149], v[54:57]
	v_mfma_f32_16x16x32_bf16 v[50:53], v[182:185], v[154:157], v[50:53]
	v_mfma_f32_16x16x32_bf16 v[46:49], v[190:193], v[146:149], v[46:49]
	v_mfma_f32_16x16x32_bf16 v[42:45], v[190:193], v[154:157], v[42:45]
	s_waitcnt lgkmcnt(0)
	v_mfma_f32_16x16x32_bf16 v[38:41], v[198:201], v[146:149], v[38:41]
	v_mfma_f32_16x16x32_bf16 v[34:37], v[198:201], v[154:157], v[34:37]
	s_setprio 0
	s_barrier
	s_mov_b32 m0, s56
	v_lshl_add_u64 v[142:143], v[220:221], 0, s[28:29]
	global_load_lds_dwordx4 v[142:143], off
	v_lshl_add_u64 v[142:143], v[222:223], 0, s[28:29]
	s_mov_b32 m0, s57
	s_nop 0
	global_load_lds_dwordx4 v[142:143], off
	s_waitcnt vmcnt(6)
	s_barrier
	s_setprio 1
	v_mfma_f32_16x16x32_bf16 v[30:33], v[170:173], v[202:205], v[30:33]
	v_mfma_f32_16x16x32_bf16 v[26:29], v[170:173], v[210:213], v[26:29]
	v_mfma_f32_16x16x32_bf16 v[22:25], v[178:181], v[202:205], v[22:25]
	v_mfma_f32_16x16x32_bf16 v[18:21], v[178:181], v[210:213], v[18:21]
	v_mfma_f32_16x16x32_bf16 v[14:17], v[186:189], v[202:205], v[14:17]
	v_mfma_f32_16x16x32_bf16 v[10:13], v[186:189], v[210:213], v[10:13]
	v_mfma_f32_16x16x32_bf16 v[6:9], v[194:197], v[202:205], v[6:9]
	v_mfma_f32_16x16x32_bf16 v[2:5], v[194:197], v[210:213], v[2:5]
	v_mfma_f32_16x16x32_bf16 v[30:33], v[174:177], v[206:209], v[30:33]
	v_mfma_f32_16x16x32_bf16 v[26:29], v[174:177], v[214:217], v[26:29]
	v_mfma_f32_16x16x32_bf16 v[22:25], v[182:185], v[206:209], v[22:25]
	v_mfma_f32_16x16x32_bf16 v[18:21], v[182:185], v[214:217], v[18:21]
	v_mfma_f32_16x16x32_bf16 v[14:17], v[190:193], v[206:209], v[14:17]
	v_mfma_f32_16x16x32_bf16 v[10:13], v[190:193], v[214:217], v[10:13]
	v_mfma_f32_16x16x32_bf16 v[6:9], v[198:201], v[206:209], v[6:9]
	v_mfma_f32_16x16x32_bf16 v[2:5], v[198:201], v[214:217], v[2:5]
	s_setprio 0
	s_add_i32 s84, s84, 2
	s_add_u32 s54, s54, 0x100
	s_addc_u32 s55, s55, 0
	s_cmp_lt_u32 s84, 4
	s_barrier
	s_cbranch_scc1 .LBB0_285
	s_add_u32 s0, s6, 0x20380
	s_addc_u32 s1, s7, 0
	s_mov_b32 m0, s85
	v_lshl_add_u64 v[158:159], v[130:131], 1, s[0:1]
	ds_read_b128 v[134:137], v161
	ds_read_b128 v[138:141], v161 offset:1024
	ds_read_b128 v[142:145], v161 offset:2048
	ds_read_b128 v[146:149], v161 offset:3072
	ds_read_b128 v[150:153], v162
	ds_read_b128 v[154:157], v162 offset:1024
	ds_read_b128 v[170:173], v163
	ds_read_b128 v[174:177], v163 offset:1024
	ds_read_b128 v[178:181], v164
	ds_read_b128 v[182:185], v164 offset:1024
	ds_read_b128 v[186:189], v165
	ds_read_b128 v[190:193], v165 offset:1024
	global_load_lds_dwordx4 v[158:159], off
	v_lshl_add_u64 v[132:133], v[132:133], 1, s[0:1]
	s_mov_b32 m0, s75
	s_nop 0
	global_load_lds_dwordx4 v[132:133], off
	s_barrier
	s_waitcnt lgkmcnt(0)
	s_setprio 1
	s_waitcnt lgkmcnt(0)
	v_mfma_f32_16x16x32_bf16 v[126:129], v[150:153], v[134:137], v[126:129]
	v_mfma_f32_16x16x32_bf16 v[122:125], v[150:153], v[142:145], v[122:125]
	v_mfma_f32_16x16x32_bf16 v[118:121], v[170:173], v[134:137], v[118:121]
	v_mfma_f32_16x16x32_bf16 v[114:117], v[170:173], v[142:145], v[114:117]
	v_mfma_f32_16x16x32_bf16 v[110:113], v[178:181], v[134:137], v[110:113]
	v_mfma_f32_16x16x32_bf16 v[126:129], v[154:157], v[138:141], v[126:129]
	v_mfma_f32_16x16x32_bf16 v[122:125], v[154:157], v[146:149], v[122:125]
	v_mfma_f32_16x16x32_bf16 v[118:121], v[174:177], v[138:141], v[118:121]
	v_mfma_f32_16x16x32_bf16 v[114:117], v[174:177], v[146:149], v[114:117]
	v_mfma_f32_16x16x32_bf16 v[110:113], v[182:185], v[138:141], v[110:113]
	v_mfma_f32_16x16x32_bf16 v[106:109], v[178:181], v[142:145], v[106:109]
	v_mfma_f32_16x16x32_bf16 v[102:105], v[186:189], v[134:137], v[102:105]
	v_mfma_f32_16x16x32_bf16 v[98:101], v[186:189], v[142:145], v[98:101]
	v_mfma_f32_16x16x32_bf16 v[194:197], v[182:185], v[146:149], v[106:109]
	v_mfma_f32_16x16x32_bf16 v[198:201], v[190:193], v[138:141], v[102:105]
	v_mfma_f32_16x16x32_bf16 v[202:205], v[190:193], v[146:149], v[98:101]
	s_setprio 0
	s_barrier
	s_nop 2
	ds_read_b128 v[98:101], v166
	ds_read_b128 v[102:105], v166 offset:1024
	ds_read_b128 v[106:109], v166 offset:2048
	ds_read_b128 v[206:209], v166 offset:3072
	s_barrier
	s_waitcnt lgkmcnt(0)
	s_setprio 1
	s_waitcnt lgkmcnt(0)
	v_mfma_f32_16x16x32_bf16 v[90:93], v[150:153], v[106:109], v[90:93]
	v_mfma_f32_16x16x32_bf16 v[86:89], v[170:173], v[98:101], v[86:89]
	v_mfma_f32_16x16x32_bf16 v[78:81], v[178:181], v[98:101], v[78:81]
	v_mfma_f32_16x16x32_bf16 v[70:73], v[186:189], v[98:101], v[70:73]
	v_mfma_f32_16x16x32_bf16 v[94:97], v[150:153], v[98:101], v[94:97]
	v_mfma_f32_16x16x32_bf16 v[90:93], v[154:157], v[206:209], v[90:93]
	v_mfma_f32_16x16x32_bf16 v[86:89], v[174:177], v[102:105], v[86:89]
	v_mfma_f32_16x16x32_bf16 v[82:85], v[170:173], v[106:109], v[82:85]
	v_mfma_f32_16x16x32_bf16 v[78:81], v[182:185], v[102:105], v[78:81]
	v_mfma_f32_16x16x32_bf16 v[74:77], v[178:181], v[106:109], v[74:77]
	v_mfma_f32_16x16x32_bf16 v[70:73], v[190:193], v[102:105], v[70:73]
	v_mfma_f32_16x16x32_bf16 v[66:69], v[186:189], v[106:109], v[66:69]
	v_mfma_f32_16x16x32_bf16 v[210:213], v[154:157], v[102:105], v[94:97]
	v_mfma_f32_16x16x32_bf16 v[150:153], v[174:177], v[206:209], v[82:85]
	v_mfma_f32_16x16x32_bf16 v[154:157], v[182:185], v[206:209], v[74:77]
	v_mfma_f32_16x16x32_bf16 v[170:173], v[190:193], v[206:209], v[66:69]
	s_setprio 0
	s_barrier
	s_nop 1
	ds_read_b128 v[66:69], v162 offset:16384
	ds_read_b128 v[74:77], v162 offset:17408
	ds_read_b128 v[82:85], v163 offset:16384
	ds_read_b128 v[94:97], v163 offset:17408
	ds_read_b128 v[174:177], v164 offset:16384
	ds_read_b128 v[178:181], v164 offset:17408
	ds_read_b128 v[182:185], v165 offset:16384
	ds_read_b128 v[186:189], v165 offset:17408
	s_waitcnt vmcnt(4)
	s_barrier
	s_waitcnt lgkmcnt(0)
	s_setprio 1
	s_waitcnt lgkmcnt(0)
	v_mfma_f32_16x16x32_bf16 v[62:65], v[66:69], v[134:137], v[62:65]
	v_mfma_f32_16x16x32_bf16 v[58:61], v[66:69], v[142:145], v[58:61]
	v_mfma_f32_16x16x32_bf16 v[54:57], v[82:85], v[134:137], v[54:57]
	v_mfma_f32_16x16x32_bf16 v[34:37], v[182:185], v[142:145], v[34:37]
	v_mfma_f32_16x16x32_bf16 v[62:65], v[74:77], v[138:141], v[62:65]
	v_mfma_f32_16x16x32_bf16 v[58:61], v[74:77], v[146:149], v[58:61]
	v_mfma_f32_16x16x32_bf16 v[54:57], v[94:97], v[138:141], v[54:57]
	v_mfma_f32_16x16x32_bf16 v[50:53], v[82:85], v[142:145], v[50:53]
	v_mfma_f32_16x16x32_bf16 v[46:49], v[174:177], v[134:137], v[46:49]
	v_mfma_f32_16x16x32_bf16 v[42:45], v[174:177], v[142:145], v[42:45]
	v_mfma_f32_16x16x32_bf16 v[38:41], v[182:185], v[134:137], v[38:41]
	v_mfma_f32_16x16x32_bf16 v[34:37], v[186:189], v[146:149], v[34:37]
	v_mfma_f32_16x16x32_bf16 v[190:193], v[94:97], v[146:149], v[50:53]
	v_mfma_f32_16x16x32_bf16 v[214:217], v[178:181], v[138:141], v[46:49]
	v_mfma_f32_16x16x32_bf16 v[218:221], v[178:181], v[146:149], v[42:45]
	v_mfma_f32_16x16x32_bf16 v[132:135], v[186:189], v[138:141], v[38:41]
	s_setprio 0
	s_setprio 1
	v_mfma_f32_16x16x32_bf16 v[26:29], v[66:69], v[106:109], v[26:29]
	v_mfma_f32_16x16x32_bf16 v[18:21], v[82:85], v[106:109], v[18:21]
	v_mfma_f32_16x16x32_bf16 v[10:13], v[174:177], v[106:109], v[10:13]
	v_mfma_f32_16x16x32_bf16 v[2:5], v[182:185], v[106:109], v[2:5]
	v_mfma_f32_16x16x32_bf16 v[30:33], v[66:69], v[98:101], v[30:33]
	v_mfma_f32_16x16x32_bf16 v[26:29], v[74:77], v[206:209], v[26:29]
	v_mfma_f32_16x16x32_bf16 v[22:25], v[82:85], v[98:101], v[22:25]
	v_mfma_f32_16x16x32_bf16 v[18:21], v[94:97], v[206:209], v[18:21]
	v_mfma_f32_16x16x32_bf16 v[14:17], v[174:177], v[98:101], v[14:17]
	v_mfma_f32_16x16x32_bf16 v[10:13], v[178:181], v[206:209], v[10:13]
	v_mfma_f32_16x16x32_bf16 v[6:9], v[182:185], v[98:101], v[6:9]
	v_mfma_f32_16x16x32_bf16 v[2:5], v[186:189], v[206:209], v[2:5]
	v_mfma_f32_16x16x32_bf16 v[136:139], v[74:77], v[102:105], v[30:33]
	v_mfma_f32_16x16x32_bf16 v[140:143], v[94:97], v[102:105], v[22:25]
	v_mfma_f32_16x16x32_bf16 v[144:147], v[178:181], v[102:105], v[14:17]
	v_mfma_f32_16x16x32_bf16 v[174:177], v[186:189], v[102:105], v[6:9]
	s_setprio 0
	s_barrier
	ds_read_b128 v[178:181], v167
	ds_read_b128 v[182:185], v167 offset:1024
	ds_read_b128 v[186:189], v167 offset:2048
	ds_read_b128 v[206:209], v167 offset:3072
	ds_read_b128 v[6:9], v162 offset:32768
	ds_read_b128 v[14:17], v162 offset:33792
	ds_read_b128 v[22:25], v163 offset:32768
	ds_read_b128 v[46:49], v163 offset:33792
	ds_read_b128 v[50:53], v164 offset:32768
	ds_read_b128 v[222:225], v164 offset:33792
	ds_read_b128 v[226:229], v165 offset:32768
	ds_read_b128 v[230:233], v165 offset:33792
	s_waitcnt vmcnt(2)
	s_barrier
	s_waitcnt lgkmcnt(0)
	s_setprio 1
	s_waitcnt lgkmcnt(0)
	v_mfma_f32_16x16x32_bf16 v[30:33], v[6:9], v[178:181], v[126:129]
	v_mfma_f32_16x16x32_bf16 v[98:101], v[14:17], v[182:185], v[30:33]
	v_mfma_f32_16x16x32_bf16 v[30:33], v[6:9], v[186:189], v[122:125]
	v_mfma_f32_16x16x32_bf16 v[94:97], v[14:17], v[206:209], v[30:33]
	v_mfma_f32_16x16x32_bf16 v[30:33], v[22:25], v[178:181], v[118:121]
	v_mfma_f32_16x16x32_bf16 v[102:105], v[46:49], v[182:185], v[30:33]
	v_mfma_f32_16x16x32_bf16 v[30:33], v[22:25], v[186:189], v[114:117]
	v_mfma_f32_16x16x32_bf16 v[82:85], v[46:49], v[206:209], v[30:33]
	v_mfma_f32_16x16x32_bf16 v[30:33], v[50:53], v[178:181], v[110:113]
	v_mfma_f32_16x16x32_bf16 v[106:109], v[222:225], v[182:185], v[30:33]
	v_mfma_f32_16x16x32_bf16 v[30:33], v[50:53], v[186:189], v[194:197]
	v_mfma_f32_16x16x32_bf16 v[74:77], v[222:225], v[206:209], v[30:33]
	v_mfma_f32_16x16x32_bf16 v[30:33], v[226:229], v[178:181], v[198:201]
	v_mfma_f32_16x16x32_bf16 v[110:113], v[230:233], v[182:185], v[30:33]
	v_mfma_f32_16x16x32_bf16 v[30:33], v[226:229], v[186:189], v[202:205]
	v_mfma_f32_16x16x32_bf16 v[66:69], v[230:233], v[206:209], v[30:33]
	s_setprio 0
	s_barrier
	ds_read_b128 v[194:197], v168
	ds_read_b128 v[198:201], v168 offset:1024
	ds_read_b128 v[202:205], v168 offset:2048
	ds_read_b128 v[234:237], v168 offset:3072
	s_waitcnt vmcnt(0)
	s_barrier
	s_waitcnt lgkmcnt(0)
	s_setprio 1
	s_waitcnt lgkmcnt(0)
	v_mfma_f32_16x16x32_bf16 v[30:33], v[6:9], v[194:197], v[210:213]
	v_mfma_f32_16x16x32_bf16 v[6:9], v[6:9], v[202:205], v[90:93]
	v_mfma_f32_16x16x32_bf16 v[38:41], v[14:17], v[198:201], v[30:33]
	v_mfma_f32_16x16x32_bf16 v[30:33], v[14:17], v[234:237], v[6:9]
	v_mfma_f32_16x16x32_bf16 v[6:9], v[22:25], v[194:197], v[86:89]
	v_mfma_f32_16x16x32_bf16 v[42:45], v[46:49], v[198:201], v[6:9]
	v_mfma_f32_16x16x32_bf16 v[6:9], v[22:25], v[202:205], v[150:153]
	v_mfma_f32_16x16x32_bf16 v[22:25], v[46:49], v[234:237], v[6:9]
	v_mfma_f32_16x16x32_bf16 v[6:9], v[50:53], v[194:197], v[78:81]
	v_mfma_f32_16x16x32_bf16 v[46:49], v[222:225], v[198:201], v[6:9]
	v_mfma_f32_16x16x32_bf16 v[6:9], v[50:53], v[202:205], v[154:157]
	v_mfma_f32_16x16x32_bf16 v[14:17], v[222:225], v[234:237], v[6:9]
	v_mfma_f32_16x16x32_bf16 v[6:9], v[226:229], v[194:197], v[70:73]
	v_mfma_f32_16x16x32_bf16 v[50:53], v[230:233], v[198:201], v[6:9]
	v_mfma_f32_16x16x32_bf16 v[6:9], v[226:229], v[202:205], v[170:173]
	v_mfma_f32_16x16x32_bf16 v[6:9], v[230:233], v[234:237], v[6:9]
	s_setprio 0
	s_barrier
	ds_read_b128 v[148:151], v162 offset:49152
	ds_read_b128 v[152:155], v162 offset:50176
	ds_read_b128 v[156:159], v163 offset:49152
	ds_read_b128 v[170:173], v163 offset:50176
	ds_read_b128 v[210:213], v164 offset:49152
	ds_read_b128 v[222:225], v164 offset:50176
	ds_read_b128 v[226:229], v165 offset:49152
	ds_read_b128 v[230:233], v165 offset:50176
	s_barrier
	s_waitcnt lgkmcnt(0)
	s_setprio 1
	s_waitcnt lgkmcnt(0)
	v_mfma_f32_16x16x32_bf16 v[54:57], v[156:159], v[178:181], v[54:57]
	v_mfma_f32_16x16x32_bf16 v[126:129], v[170:173], v[182:185], v[54:57]
	v_mfma_f32_16x16x32_bf16 v[54:57], v[156:159], v[186:189], v[190:193]
	v_mfma_f32_16x16x32_bf16 v[86:89], v[170:173], v[206:209], v[54:57]
	v_mfma_f32_16x16x32_bf16 v[54:57], v[210:213], v[178:181], v[214:217]
	v_mfma_f32_16x16x32_bf16 v[118:121], v[222:225], v[182:185], v[54:57]
	v_mfma_f32_16x16x32_bf16 v[54:57], v[210:213], v[186:189], v[218:221]
	v_mfma_f32_16x16x32_bf16 v[62:65], v[148:151], v[178:181], v[62:65]
	v_mfma_f32_16x16x32_bf16 v[58:61], v[148:151], v[186:189], v[58:61]
	v_mfma_f32_16x16x32_bf16 v[78:81], v[222:225], v[206:209], v[54:57]
	v_mfma_f32_16x16x32_bf16 v[54:57], v[226:229], v[178:181], v[132:135]
	v_mfma_f32_16x16x32_bf16 v[34:37], v[226:229], v[186:189], v[34:37]
	v_mfma_f32_16x16x32_bf16 v[122:125], v[152:155], v[182:185], v[62:65]
	v_mfma_f32_16x16x32_bf16 v[90:93], v[152:155], v[206:209], v[58:61]
	v_mfma_f32_16x16x32_bf16 v[114:117], v[230:233], v[182:185], v[54:57]
	v_mfma_f32_16x16x32_bf16 v[70:73], v[230:233], v[206:209], v[34:37]
	s_setprio 0
	s_setprio 1
	v_mfma_f32_16x16x32_bf16 v[34:37], v[148:151], v[194:197], v[136:139]
	v_mfma_f32_16x16x32_bf16 v[62:65], v[152:155], v[198:201], v[34:37]
	v_mfma_f32_16x16x32_bf16 v[34:37], v[156:159], v[194:197], v[140:143]
	v_mfma_f32_16x16x32_bf16 v[58:61], v[170:173], v[198:201], v[34:37]
	v_mfma_f32_16x16x32_bf16 v[34:37], v[210:213], v[194:197], v[144:147]
	v_mfma_f32_16x16x32_bf16 v[26:29], v[148:151], v[202:205], v[26:29]
	v_mfma_f32_16x16x32_bf16 v[18:21], v[156:159], v[202:205], v[18:21]
	v_mfma_f32_16x16x32_bf16 v[54:57], v[222:225], v[198:201], v[34:37]
	v_mfma_f32_16x16x32_bf16 v[10:13], v[210:213], v[202:205], v[10:13]
	v_mfma_f32_16x16x32_bf16 v[34:37], v[226:229], v[194:197], v[174:177]
	v_mfma_f32_16x16x32_bf16 v[2:5], v[226:229], v[202:205], v[2:5]
	v_mfma_f32_16x16x32_bf16 v[26:29], v[152:155], v[234:237], v[26:29]
	v_mfma_f32_16x16x32_bf16 v[18:21], v[170:173], v[234:237], v[18:21]
	v_mfma_f32_16x16x32_bf16 v[10:13], v[222:225], v[234:237], v[10:13]
	v_mfma_f32_16x16x32_bf16 v[34:37], v[230:233], v[198:201], v[34:37]
	v_mfma_f32_16x16x32_bf16 v[2:5], v[230:233], v[234:237], v[2:5]
	s_setprio 0
	s_barrier
	s_and_saveexec_b64 s[6:7], s[2:3]
	s_cbranch_execz .LBB0_288
	s_barrier

.LBB0_291:
	ds_read_b128 v[146:149], v161
	ds_read_b128 v[150:153], v161 offset:1024
	ds_read_b128 v[154:157], v161 offset:2048
	ds_read_b128 v[170:173], v161 offset:3072
	v_lshl_add_u64 v[158:159], v[142:143], 0, s[50:51]
	s_add_i32 s84, s49, 0xc000
	v_lshl_add_u64 v[206:207], v[158:159], 0, s[30:31]
	s_mov_b32 m0, s84
	v_lshl_add_u64 v[222:223], v[144:145], 0, s[50:51]
	s_add_i32 s55, s49, 0xe000
	ds_read_b128 v[174:177], v162
	ds_read_b128 v[178:181], v162 offset:1024
	ds_read_b128 v[182:185], v163
	ds_read_b128 v[186:189], v163 offset:1024
	ds_read_b128 v[190:193], v164
	ds_read_b128 v[194:197], v164 offset:1024
	ds_read_b128 v[198:201], v165
	ds_read_b128 v[202:205], v165 offset:1024
	global_load_lds_dwordx4 v[206:207], off
	v_lshl_add_u64 v[206:207], v[222:223], 0, s[30:31]
	s_mov_b32 m0, s55
	s_nop 0
	global_load_lds_dwordx4 v[206:207], off
	s_waitcnt lgkmcnt(8)
	s_barrier
	s_setprio 1
	s_waitcnt lgkmcnt(7)
	v_mfma_f32_16x16x32_bf16 v[126:129], v[174:177], v[146:149], v[126:129]
	v_mfma_f32_16x16x32_bf16 v[122:125], v[174:177], v[154:157], v[122:125]
	s_waitcnt lgkmcnt(5)
	v_mfma_f32_16x16x32_bf16 v[118:121], v[182:185], v[146:149], v[118:121]
	v_mfma_f32_16x16x32_bf16 v[114:117], v[182:185], v[154:157], v[114:117]
	s_waitcnt lgkmcnt(3)
	v_mfma_f32_16x16x32_bf16 v[110:113], v[190:193], v[146:149], v[110:113]
	v_mfma_f32_16x16x32_bf16 v[106:109], v[190:193], v[154:157], v[106:109]
	s_waitcnt lgkmcnt(1)
	v_mfma_f32_16x16x32_bf16 v[102:105], v[198:201], v[146:149], v[102:105]
	v_mfma_f32_16x16x32_bf16 v[98:101], v[198:201], v[154:157], v[98:101]
	v_mfma_f32_16x16x32_bf16 v[126:129], v[178:181], v[150:153], v[126:129]
	v_mfma_f32_16x16x32_bf16 v[122:125], v[178:181], v[170:173], v[122:125]
	v_mfma_f32_16x16x32_bf16 v[118:121], v[186:189], v[150:153], v[118:121]
	v_mfma_f32_16x16x32_bf16 v[114:117], v[186:189], v[170:173], v[114:117]
	v_mfma_f32_16x16x32_bf16 v[110:113], v[194:197], v[150:153], v[110:113]
	v_mfma_f32_16x16x32_bf16 v[106:109], v[194:197], v[170:173], v[106:109]
	s_waitcnt lgkmcnt(0)
	v_mfma_f32_16x16x32_bf16 v[102:105], v[202:205], v[150:153], v[102:105]
	v_mfma_f32_16x16x32_bf16 v[98:101], v[202:205], v[170:173], v[98:101]
	s_setprio 0
	s_barrier
	v_lshl_add_u64 v[224:225], v[138:139], 0, s[50:51]
	s_mov_b32 m0, s67
	v_lshl_add_u64 v[226:227], v[224:225], 0, s[20:21]
	ds_read_b128 v[206:209], v166
	ds_read_b128 v[210:213], v166 offset:1024
	ds_read_b128 v[214:217], v166 offset:2048
	ds_read_b128 v[218:221], v166 offset:3072
	global_load_lds_dwordx4 v[226:227], off
	v_lshl_add_u64 v[226:227], v[140:141], 0, s[50:51]
	v_lshl_add_u64 v[228:229], v[226:227], 0, s[20:21]
	s_mov_b32 m0, s68
	s_nop 0
	global_load_lds_dwordx4 v[228:229], off
	s_barrier
	s_setprio 1
	s_waitcnt lgkmcnt(3)
	v_mfma_f32_16x16x32_bf16 v[94:97], v[174:177], v[206:209], v[94:97]
	s_waitcnt lgkmcnt(1)
	v_mfma_f32_16x16x32_bf16 v[90:93], v[174:177], v[214:217], v[90:93]
	v_mfma_f32_16x16x32_bf16 v[86:89], v[182:185], v[206:209], v[86:89]
	v_mfma_f32_16x16x32_bf16 v[82:85], v[182:185], v[214:217], v[82:85]
	v_mfma_f32_16x16x32_bf16 v[78:81], v[190:193], v[206:209], v[78:81]
	v_mfma_f32_16x16x32_bf16 v[74:77], v[190:193], v[214:217], v[74:77]
	v_mfma_f32_16x16x32_bf16 v[70:73], v[198:201], v[206:209], v[70:73]
	v_mfma_f32_16x16x32_bf16 v[66:69], v[198:201], v[214:217], v[66:69]
	v_mfma_f32_16x16x32_bf16 v[94:97], v[178:181], v[210:213], v[94:97]
	s_waitcnt lgkmcnt(0)
	v_mfma_f32_16x16x32_bf16 v[90:93], v[178:181], v[218:221], v[90:93]
	v_mfma_f32_16x16x32_bf16 v[86:89], v[186:189], v[210:213], v[86:89]
	v_mfma_f32_16x16x32_bf16 v[82:85], v[186:189], v[218:221], v[82:85]
	v_mfma_f32_16x16x32_bf16 v[78:81], v[194:197], v[210:213], v[78:81]
	v_mfma_f32_16x16x32_bf16 v[74:77], v[194:197], v[218:221], v[74:77]
	v_mfma_f32_16x16x32_bf16 v[70:73], v[202:205], v[210:213], v[70:73]
	v_mfma_f32_16x16x32_bf16 v[66:69], v[202:205], v[218:221], v[66:69]
	s_setprio 0
	s_mov_b32 m0, s49
	v_lshl_add_u64 v[228:229], v[158:159], 0, s[20:21]
	s_barrier
	ds_read_b128 v[174:177], v162 offset:16384
	ds_read_b128 v[178:181], v162 offset:17408
	ds_read_b128 v[182:185], v163 offset:16384
	ds_read_b128 v[186:189], v163 offset:17408
	ds_read_b128 v[190:193], v164 offset:16384
	ds_read_b128 v[194:197], v164 offset:17408
	ds_read_b128 v[198:201], v165 offset:16384
	ds_read_b128 v[202:205], v165 offset:17408
	global_load_lds_dwordx4 v[228:229], off
	v_lshl_add_u64 v[228:229], v[222:223], 0, s[20:21]
	s_mov_b32 m0, s69
	s_nop 0
	global_load_lds_dwordx4 v[228:229], off
	s_barrier
	s_setprio 1
	s_waitcnt lgkmcnt(7)
	v_mfma_f32_16x16x32_bf16 v[62:65], v[174:177], v[146:149], v[62:65]
	v_mfma_f32_16x16x32_bf16 v[58:61], v[174:177], v[154:157], v[58:61]
	s_waitcnt lgkmcnt(5)
	v_mfma_f32_16x16x32_bf16 v[54:57], v[182:185], v[146:149], v[54:57]
	v_mfma_f32_16x16x32_bf16 v[50:53], v[182:185], v[154:157], v[50:53]
	s_waitcnt lgkmcnt(3)
	v_mfma_f32_16x16x32_bf16 v[46:49], v[190:193], v[146:149], v[46:49]
	v_mfma_f32_16x16x32_bf16 v[42:45], v[190:193], v[154:157], v[42:45]
	s_waitcnt lgkmcnt(1)
	v_mfma_f32_16x16x32_bf16 v[38:41], v[198:201], v[146:149], v[38:41]
	v_mfma_f32_16x16x32_bf16 v[34:37], v[198:201], v[154:157], v[34:37]
	v_mfma_f32_16x16x32_bf16 v[62:65], v[178:181], v[150:153], v[62:65]
	v_mfma_f32_16x16x32_bf16 v[58:61], v[178:181], v[170:173], v[58:61]
	v_mfma_f32_16x16x32_bf16 v[54:57], v[186:189], v[150:153], v[54:57]
	v_mfma_f32_16x16x32_bf16 v[50:53], v[186:189], v[170:173], v[50:53]
	v_mfma_f32_16x16x32_bf16 v[46:49], v[194:197], v[150:153], v[46:49]
	v_mfma_f32_16x16x32_bf16 v[42:45], v[194:197], v[170:173], v[42:45]
	s_waitcnt lgkmcnt(0)
	v_mfma_f32_16x16x32_bf16 v[38:41], v[202:205], v[150:153], v[38:41]
	v_mfma_f32_16x16x32_bf16 v[34:37], v[202:205], v[170:173], v[34:37]
	s_setprio 0
	s_barrier
	s_mov_b32 m0, s70
	v_lshl_add_u64 v[146:147], v[224:225], 0, s[34:35]
	global_load_lds_dwordx4 v[146:147], off
	v_lshl_add_u64 v[146:147], v[226:227], 0, s[34:35]
	s_mov_b32 m0, s71
	s_nop 0
	global_load_lds_dwordx4 v[146:147], off
	s_waitcnt vmcnt(6)
	s_barrier
	s_setprio 1
	v_mfma_f32_16x16x32_bf16 v[30:33], v[174:177], v[206:209], v[30:33]
	v_mfma_f32_16x16x32_bf16 v[26:29], v[174:177], v[214:217], v[26:29]
	v_mfma_f32_16x16x32_bf16 v[22:25], v[182:185], v[206:209], v[22:25]
	v_mfma_f32_16x16x32_bf16 v[18:21], v[182:185], v[214:217], v[18:21]
	v_mfma_f32_16x16x32_bf16 v[14:17], v[190:193], v[206:209], v[14:17]
	v_mfma_f32_16x16x32_bf16 v[10:13], v[190:193], v[214:217], v[10:13]
	v_mfma_f32_16x16x32_bf16 v[6:9], v[198:201], v[206:209], v[6:9]
	v_mfma_f32_16x16x32_bf16 v[2:5], v[198:201], v[214:217], v[2:5]
	v_mfma_f32_16x16x32_bf16 v[30:33], v[178:181], v[210:213], v[30:33]
	v_mfma_f32_16x16x32_bf16 v[26:29], v[178:181], v[218:221], v[26:29]
	v_mfma_f32_16x16x32_bf16 v[22:25], v[186:189], v[210:213], v[22:25]
	v_mfma_f32_16x16x32_bf16 v[18:21], v[186:189], v[218:221], v[18:21]
	v_mfma_f32_16x16x32_bf16 v[14:17], v[194:197], v[210:213], v[14:17]
	v_mfma_f32_16x16x32_bf16 v[10:13], v[194:197], v[218:221], v[10:13]
	v_mfma_f32_16x16x32_bf16 v[6:9], v[202:205], v[210:213], v[6:9]
	v_mfma_f32_16x16x32_bf16 v[2:5], v[202:205], v[218:221], v[2:5]
	s_setprio 0
	s_barrier
	ds_read_b128 v[146:149], v167
	ds_read_b128 v[150:153], v167 offset:1024
	ds_read_b128 v[154:157], v167 offset:2048
	ds_read_b128 v[170:173], v167 offset:3072
	s_mov_b32 m0, s72
	v_lshl_add_u64 v[206:207], v[158:159], 0, s[34:35]
	ds_read_b128 v[174:177], v162 offset:32768
	ds_read_b128 v[178:181], v162 offset:33792
	ds_read_b128 v[182:185], v163 offset:32768
	ds_read_b128 v[186:189], v163 offset:33792
	ds_read_b128 v[190:193], v164 offset:32768
	ds_read_b128 v[194:197], v164 offset:33792
	ds_read_b128 v[198:201], v165 offset:32768
	ds_read_b128 v[202:205], v165 offset:33792
	global_load_lds_dwordx4 v[206:207], off
	v_lshl_add_u64 v[206:207], v[222:223], 0, s[34:35]
	s_mov_b32 m0, s73
	s_nop 0
	global_load_lds_dwordx4 v[206:207], off
	s_waitcnt lgkmcnt(8)
	s_barrier
	s_setprio 1
	s_waitcnt lgkmcnt(7)
	v_mfma_f32_16x16x32_bf16 v[126:129], v[174:177], v[146:149], v[126:129]
	v_mfma_f32_16x16x32_bf16 v[122:125], v[174:177], v[154:157], v[122:125]
	s_waitcnt lgkmcnt(5)
	v_mfma_f32_16x16x32_bf16 v[118:121], v[182:185], v[146:149], v[118:121]
	v_mfma_f32_16x16x32_bf16 v[114:117], v[182:185], v[154:157], v[114:117]
	s_waitcnt lgkmcnt(3)
	v_mfma_f32_16x16x32_bf16 v[110:113], v[190:193], v[146:149], v[110:113]
	v_mfma_f32_16x16x32_bf16 v[106:109], v[190:193], v[154:157], v[106:109]
	s_waitcnt lgkmcnt(1)
	v_mfma_f32_16x16x32_bf16 v[102:105], v[198:201], v[146:149], v[102:105]
	v_mfma_f32_16x16x32_bf16 v[98:101], v[198:201], v[154:157], v[98:101]
	v_mfma_f32_16x16x32_bf16 v[126:129], v[178:181], v[150:153], v[126:129]
	v_mfma_f32_16x16x32_bf16 v[122:125], v[178:181], v[170:173], v[122:125]
	v_mfma_f32_16x16x32_bf16 v[118:121], v[186:189], v[150:153], v[118:121]
	v_mfma_f32_16x16x32_bf16 v[114:117], v[186:189], v[170:173], v[114:117]
	v_mfma_f32_16x16x32_bf16 v[110:113], v[194:197], v[150:153], v[110:113]
	v_mfma_f32_16x16x32_bf16 v[106:109], v[194:197], v[170:173], v[106:109]
	s_waitcnt lgkmcnt(0)
	v_mfma_f32_16x16x32_bf16 v[102:105], v[202:205], v[150:153], v[102:105]
	v_mfma_f32_16x16x32_bf16 v[98:101], v[202:205], v[170:173], v[98:101]
	s_setprio 0
	s_barrier
	s_mov_b32 m0, s58
	v_lshl_add_u64 v[228:229], v[224:225], 0, s[26:27]
	ds_read_b128 v[206:209], v168
	ds_read_b128 v[210:213], v168 offset:1024
	ds_read_b128 v[214:217], v168 offset:2048
	ds_read_b128 v[218:221], v168 offset:3072
	global_load_lds_dwordx4 v[228:229], off
	v_lshl_add_u64 v[228:229], v[226:227], 0, s[26:27]
	s_mov_b32 m0, s59
	s_nop 0
	global_load_lds_dwordx4 v[228:229], off
	s_barrier
	s_setprio 1
	s_waitcnt lgkmcnt(3)
	v_mfma_f32_16x16x32_bf16 v[94:97], v[174:177], v[206:209], v[94:97]
	s_waitcnt lgkmcnt(1)
	v_mfma_f32_16x16x32_bf16 v[90:93], v[174:177], v[214:217], v[90:93]
	v_mfma_f32_16x16x32_bf16 v[86:89], v[182:185], v[206:209], v[86:89]
	v_mfma_f32_16x16x32_bf16 v[82:85], v[182:185], v[214:217], v[82:85]
	v_mfma_f32_16x16x32_bf16 v[78:81], v[190:193], v[206:209], v[78:81]
	v_mfma_f32_16x16x32_bf16 v[74:77], v[190:193], v[214:217], v[74:77]
	v_mfma_f32_16x16x32_bf16 v[70:73], v[198:201], v[206:209], v[70:73]
	v_mfma_f32_16x16x32_bf16 v[66:69], v[198:201], v[214:217], v[66:69]
	v_mfma_f32_16x16x32_bf16 v[94:97], v[178:181], v[210:213], v[94:97]
	s_waitcnt lgkmcnt(0)
	v_mfma_f32_16x16x32_bf16 v[90:93], v[178:181], v[218:221], v[90:93]
	v_mfma_f32_16x16x32_bf16 v[86:89], v[186:189], v[210:213], v[86:89]
	v_mfma_f32_16x16x32_bf16 v[82:85], v[186:189], v[218:221], v[82:85]
	v_mfma_f32_16x16x32_bf16 v[78:81], v[194:197], v[210:213], v[78:81]
	v_mfma_f32_16x16x32_bf16 v[74:77], v[194:197], v[218:221], v[74:77]
	v_mfma_f32_16x16x32_bf16 v[70:73], v[202:205], v[210:213], v[70:73]
	v_mfma_f32_16x16x32_bf16 v[66:69], v[202:205], v[218:221], v[66:69]
	s_setprio 0
	s_mov_b32 m0, s74
	v_lshl_add_u64 v[158:159], v[158:159], 0, s[26:27]
	s_barrier
	ds_read_b128 v[174:177], v162 offset:49152
	ds_read_b128 v[178:181], v162 offset:50176
	ds_read_b128 v[182:185], v163 offset:49152
	ds_read_b128 v[186:189], v163 offset:50176
	ds_read_b128 v[190:193], v164 offset:49152
	ds_read_b128 v[194:197], v164 offset:50176
	ds_read_b128 v[198:201], v165 offset:49152
	ds_read_b128 v[202:205], v165 offset:50176
	global_load_lds_dwordx4 v[158:159], off
	v_lshl_add_u64 v[158:159], v[222:223], 0, s[26:27]
	s_mov_b32 m0, s75
	s_nop 0
	global_load_lds_dwordx4 v[158:159], off
	s_barrier
	s_setprio 1
	s_waitcnt lgkmcnt(7)
	v_mfma_f32_16x16x32_bf16 v[62:65], v[174:177], v[146:149], v[62:65]
	v_mfma_f32_16x16x32_bf16 v[58:61], v[174:177], v[154:157], v[58:61]
	s_waitcnt lgkmcnt(5)
	v_mfma_f32_16x16x32_bf16 v[54:57], v[182:185], v[146:149], v[54:57]
	v_mfma_f32_16x16x32_bf16 v[50:53], v[182:185], v[154:157], v[50:53]
	s_waitcnt lgkmcnt(3)
	v_mfma_f32_16x16x32_bf16 v[46:49], v[190:193], v[146:149], v[46:49]
	v_mfma_f32_16x16x32_bf16 v[42:45], v[190:193], v[154:157], v[42:45]
	s_waitcnt lgkmcnt(1)
	v_mfma_f32_16x16x32_bf16 v[38:41], v[198:201], v[146:149], v[38:41]
	v_mfma_f32_16x16x32_bf16 v[34:37], v[198:201], v[154:157], v[34:37]
	v_mfma_f32_16x16x32_bf16 v[62:65], v[178:181], v[150:153], v[62:65]
	v_mfma_f32_16x16x32_bf16 v[58:61], v[178:181], v[170:173], v[58:61]
	v_mfma_f32_16x16x32_bf16 v[54:57], v[186:189], v[150:153], v[54:57]
	v_mfma_f32_16x16x32_bf16 v[50:53], v[186:189], v[170:173], v[50:53]
	v_mfma_f32_16x16x32_bf16 v[46:49], v[194:197], v[150:153], v[46:49]
	v_mfma_f32_16x16x32_bf16 v[42:45], v[194:197], v[170:173], v[42:45]
	s_waitcnt lgkmcnt(0)
	v_mfma_f32_16x16x32_bf16 v[38:41], v[202:205], v[150:153], v[38:41]
	v_mfma_f32_16x16x32_bf16 v[34:37], v[202:205], v[170:173], v[34:37]
	s_setprio 0
	s_barrier
	s_mov_b32 m0, s56
	v_lshl_add_u64 v[146:147], v[224:225], 0, s[46:47]
	global_load_lds_dwordx4 v[146:147], off
	v_lshl_add_u64 v[146:147], v[226:227], 0, s[46:47]
	s_mov_b32 m0, s57
	s_nop 0
	global_load_lds_dwordx4 v[146:147], off
	s_waitcnt vmcnt(6)
	s_barrier
	s_setprio 1
	v_mfma_f32_16x16x32_bf16 v[30:33], v[174:177], v[206:209], v[30:33]
	v_mfma_f32_16x16x32_bf16 v[26:29], v[174:177], v[214:217], v[26:29]
	v_mfma_f32_16x16x32_bf16 v[22:25], v[182:185], v[206:209], v[22:25]
	v_mfma_f32_16x16x32_bf16 v[18:21], v[182:185], v[214:217], v[18:21]
	v_mfma_f32_16x16x32_bf16 v[14:17], v[190:193], v[206:209], v[14:17]
	v_mfma_f32_16x16x32_bf16 v[10:13], v[190:193], v[214:217], v[10:13]
	v_mfma_f32_16x16x32_bf16 v[6:9], v[198:201], v[206:209], v[6:9]
	v_mfma_f32_16x16x32_bf16 v[2:5], v[198:201], v[214:217], v[2:5]
	v_mfma_f32_16x16x32_bf16 v[30:33], v[178:181], v[210:213], v[30:33]
	v_mfma_f32_16x16x32_bf16 v[26:29], v[178:181], v[218:221], v[26:29]
	v_mfma_f32_16x16x32_bf16 v[22:25], v[186:189], v[210:213], v[22:25]
	v_mfma_f32_16x16x32_bf16 v[18:21], v[186:189], v[218:221], v[18:21]
	v_mfma_f32_16x16x32_bf16 v[14:17], v[194:197], v[210:213], v[14:17]
	v_mfma_f32_16x16x32_bf16 v[10:13], v[194:197], v[218:221], v[10:13]
	v_mfma_f32_16x16x32_bf16 v[6:9], v[202:205], v[210:213], v[6:9]
	v_mfma_f32_16x16x32_bf16 v[2:5], v[202:205], v[218:221], v[2:5]
	s_setprio 0
	s_add_i32 s54, s54, 2
	s_add_u32 s50, s50, 0x100
	s_addc_u32 s51, s51, 0
	s_cmp_lt_u32 s54, 12
	s_barrier
	s_cbranch_scc1 .LBB0_291
	s_add_u32 s0, s6, 0x40780
	s_addc_u32 s1, s7, 0
	s_mov_b32 m0, s84
	v_lshl_add_u64 v[158:159], v[130:131], 1, s[0:1]
	ds_read_b128 v[138:141], v161
	ds_read_b128 v[142:145], v161 offset:1024
	ds_read_b128 v[146:149], v161 offset:2048
	ds_read_b128 v[150:153], v161 offset:3072
	ds_read_b128 v[154:157], v162
	ds_read_b128 v[170:173], v162 offset:1024
	ds_read_b128 v[174:177], v163
	ds_read_b128 v[178:181], v163 offset:1024
	ds_read_b128 v[182:185], v164
	ds_read_b128 v[186:189], v164 offset:1024
	ds_read_b128 v[190:193], v165
	ds_read_b128 v[194:197], v165 offset:1024
	global_load_lds_dwordx4 v[158:159], off
	v_lshl_add_u64 v[136:137], v[136:137], 1, s[0:1]
	s_mov_b32 m0, s55
	s_nop 0
	global_load_lds_dwordx4 v[136:137], off
	s_barrier
	s_waitcnt lgkmcnt(0)
	s_setprio 1
	s_waitcnt lgkmcnt(0)
	v_mfma_f32_16x16x32_bf16 v[126:129], v[154:157], v[138:141], v[126:129]
	v_mfma_f32_16x16x32_bf16 v[118:121], v[174:177], v[138:141], v[118:121]
	v_mfma_f32_16x16x32_bf16 v[114:117], v[174:177], v[146:149], v[114:117]
	v_mfma_f32_16x16x32_bf16 v[110:113], v[182:185], v[138:141], v[110:113]
	v_mfma_f32_16x16x32_bf16 v[106:109], v[182:185], v[146:149], v[106:109]
	v_mfma_f32_16x16x32_bf16 v[102:105], v[190:193], v[138:141], v[102:105]
	v_mfma_f32_16x16x32_bf16 v[98:101], v[190:193], v[146:149], v[98:101]
	v_mfma_f32_16x16x32_bf16 v[126:129], v[170:173], v[142:145], v[126:129]
	v_mfma_f32_16x16x32_bf16 v[122:125], v[154:157], v[146:149], v[122:125]
	v_mfma_f32_16x16x32_bf16 v[118:121], v[178:181], v[142:145], v[118:121]
	v_mfma_f32_16x16x32_bf16 v[114:117], v[178:181], v[150:153], v[114:117]
	v_mfma_f32_16x16x32_bf16 v[110:113], v[186:189], v[142:145], v[110:113]
	v_mfma_f32_16x16x32_bf16 v[106:109], v[186:189], v[150:153], v[106:109]
	v_mfma_f32_16x16x32_bf16 v[102:105], v[194:197], v[142:145], v[102:105]
	v_mfma_f32_16x16x32_bf16 v[98:101], v[194:197], v[150:153], v[98:101]
	v_mfma_f32_16x16x32_bf16 v[198:201], v[170:173], v[150:153], v[122:125]
	s_setprio 0
	s_barrier
	s_nop 0
	ds_read_b128 v[122:125], v166
	ds_read_b128 v[202:205], v166 offset:1024
	ds_read_b128 v[206:209], v166 offset:2048
	ds_read_b128 v[210:213], v166 offset:3072
	s_barrier
	s_waitcnt lgkmcnt(0)
	s_setprio 1
	s_waitcnt lgkmcnt(0)
	v_mfma_f32_16x16x32_bf16 v[86:89], v[174:177], v[122:125], v[86:89]
	v_mfma_f32_16x16x32_bf16 v[78:81], v[182:185], v[122:125], v[78:81]
	v_mfma_f32_16x16x32_bf16 v[70:73], v[190:193], v[122:125], v[70:73]
	v_mfma_f32_16x16x32_bf16 v[66:69], v[190:193], v[206:209], v[66:69]
	v_mfma_f32_16x16x32_bf16 v[94:97], v[154:157], v[122:125], v[94:97]
	v_mfma_f32_16x16x32_bf16 v[90:93], v[154:157], v[206:209], v[90:93]
	v_mfma_f32_16x16x32_bf16 v[86:89], v[178:181], v[202:205], v[86:89]
	v_mfma_f32_16x16x32_bf16 v[82:85], v[174:177], v[206:209], v[82:85]
	v_mfma_f32_16x16x32_bf16 v[78:81], v[186:189], v[202:205], v[78:81]
	v_mfma_f32_16x16x32_bf16 v[74:77], v[182:185], v[206:209], v[74:77]
	v_mfma_f32_16x16x32_bf16 v[70:73], v[194:197], v[202:205], v[70:73]
	v_mfma_f32_16x16x32_bf16 v[66:69], v[194:197], v[210:213], v[66:69]
	v_mfma_f32_16x16x32_bf16 v[214:217], v[170:173], v[202:205], v[94:97]
	v_mfma_f32_16x16x32_bf16 v[154:157], v[170:173], v[210:213], v[90:93]
	v_mfma_f32_16x16x32_bf16 v[170:173], v[178:181], v[210:213], v[82:85]
	v_mfma_f32_16x16x32_bf16 v[174:177], v[186:189], v[210:213], v[74:77]
	s_setprio 0
	s_barrier
	s_nop 0
	ds_read_b128 v[74:77], v162 offset:16384
	ds_read_b128 v[82:85], v162 offset:17408
	ds_read_b128 v[90:93], v163 offset:16384
	ds_read_b128 v[94:97], v163 offset:17408
	ds_read_b128 v[178:181], v164 offset:16384
	ds_read_b128 v[182:185], v164 offset:17408
	ds_read_b128 v[186:189], v165 offset:16384
	ds_read_b128 v[190:193], v165 offset:17408
	s_waitcnt vmcnt(4)
	s_barrier
	s_waitcnt lgkmcnt(0)
	s_setprio 1
	s_waitcnt lgkmcnt(0)
	v_mfma_f32_16x16x32_bf16 v[50:53], v[90:93], v[146:149], v[50:53]
	v_mfma_f32_16x16x32_bf16 v[42:45], v[178:181], v[146:149], v[42:45]
	v_mfma_f32_16x16x32_bf16 v[38:41], v[186:189], v[138:141], v[38:41]
	v_mfma_f32_16x16x32_bf16 v[34:37], v[186:189], v[146:149], v[34:37]
	v_mfma_f32_16x16x32_bf16 v[62:65], v[74:77], v[138:141], v[62:65]
	v_mfma_f32_16x16x32_bf16 v[58:61], v[74:77], v[146:149], v[58:61]
	v_mfma_f32_16x16x32_bf16 v[54:57], v[90:93], v[138:141], v[54:57]
	v_mfma_f32_16x16x32_bf16 v[50:53], v[94:97], v[150:153], v[50:53]
	v_mfma_f32_16x16x32_bf16 v[46:49], v[178:181], v[138:141], v[46:49]
	v_mfma_f32_16x16x32_bf16 v[42:45], v[182:185], v[150:153], v[42:45]
	v_mfma_f32_16x16x32_bf16 v[38:41], v[190:193], v[142:145], v[38:41]
	v_mfma_f32_16x16x32_bf16 v[34:37], v[190:193], v[150:153], v[34:37]
	v_mfma_f32_16x16x32_bf16 v[194:197], v[82:85], v[142:145], v[62:65]
	v_mfma_f32_16x16x32_bf16 v[218:221], v[82:85], v[150:153], v[58:61]
	v_mfma_f32_16x16x32_bf16 v[222:225], v[94:97], v[142:145], v[54:57]
	v_mfma_f32_16x16x32_bf16 v[226:229], v[182:185], v[142:145], v[46:49]
	s_setprio 0
	s_setprio 1
	v_mfma_f32_16x16x32_bf16 v[2:5], v[186:189], v[206:209], v[2:5]
	v_mfma_f32_16x16x32_bf16 v[30:33], v[74:77], v[122:125], v[30:33]
	v_mfma_f32_16x16x32_bf16 v[26:29], v[74:77], v[206:209], v[26:29]
	v_mfma_f32_16x16x32_bf16 v[22:25], v[90:93], v[122:125], v[22:25]
	v_mfma_f32_16x16x32_bf16 v[18:21], v[90:93], v[206:209], v[18:21]
	v_mfma_f32_16x16x32_bf16 v[14:17], v[178:181], v[122:125], v[14:17]
	v_mfma_f32_16x16x32_bf16 v[10:13], v[178:181], v[206:209], v[10:13]
	v_mfma_f32_16x16x32_bf16 v[6:9], v[186:189], v[122:125], v[6:9]
	v_mfma_f32_16x16x32_bf16 v[2:5], v[190:193], v[210:213], v[2:5]
	v_mfma_f32_16x16x32_bf16 v[136:139], v[82:85], v[202:205], v[30:33]
	v_mfma_f32_16x16x32_bf16 v[140:143], v[82:85], v[210:213], v[26:29]
	v_mfma_f32_16x16x32_bf16 v[144:147], v[94:97], v[202:205], v[22:25]
	v_mfma_f32_16x16x32_bf16 v[148:151], v[94:97], v[210:213], v[18:21]
	v_mfma_f32_16x16x32_bf16 v[230:233], v[182:185], v[202:205], v[14:17]
	v_mfma_f32_16x16x32_bf16 v[178:181], v[182:185], v[210:213], v[10:13]
	v_mfma_f32_16x16x32_bf16 v[182:185], v[190:193], v[202:205], v[6:9]
	s_setprio 0
	s_barrier
	s_nop 0
	ds_read_b128 v[6:9], v167
	ds_read_b128 v[10:13], v167 offset:1024
	ds_read_b128 v[18:21], v167 offset:2048
	ds_read_b128 v[186:189], v167 offset:3072
	ds_read_b128 v[14:17], v162 offset:32768
	ds_read_b128 v[22:25], v162 offset:33792
	ds_read_b128 v[26:29], v163 offset:32768
	ds_read_b128 v[46:49], v163 offset:33792
	ds_read_b128 v[190:193], v164 offset:32768
	ds_read_b128 v[202:205], v164 offset:33792
	ds_read_b128 v[206:209], v165 offset:32768
	ds_read_b128 v[210:213], v165 offset:33792
	s_waitcnt vmcnt(2)
	s_barrier
	s_waitcnt lgkmcnt(0)
	s_setprio 1
	s_waitcnt lgkmcnt(0)
	v_mfma_f32_16x16x32_bf16 v[30:33], v[14:17], v[6:9], v[126:129]
	v_mfma_f32_16x16x32_bf16 v[122:125], v[22:25], v[10:13], v[30:33]
	v_mfma_f32_16x16x32_bf16 v[30:33], v[14:17], v[18:21], v[198:201]
	v_mfma_f32_16x16x32_bf16 v[94:97], v[22:25], v[186:189], v[30:33]
	v_mfma_f32_16x16x32_bf16 v[30:33], v[26:29], v[6:9], v[118:121]
	v_mfma_f32_16x16x32_bf16 v[126:129], v[46:49], v[10:13], v[30:33]
	v_mfma_f32_16x16x32_bf16 v[30:33], v[26:29], v[18:21], v[114:117]
	v_mfma_f32_16x16x32_bf16 v[90:93], v[46:49], v[186:189], v[30:33]
	v_mfma_f32_16x16x32_bf16 v[30:33], v[190:193], v[6:9], v[110:113]
	v_mfma_f32_16x16x32_bf16 v[118:121], v[202:205], v[10:13], v[30:33]
	v_mfma_f32_16x16x32_bf16 v[30:33], v[190:193], v[18:21], v[106:109]
	v_mfma_f32_16x16x32_bf16 v[82:85], v[202:205], v[186:189], v[30:33]
	v_mfma_f32_16x16x32_bf16 v[30:33], v[206:209], v[6:9], v[102:105]
	v_mfma_f32_16x16x32_bf16 v[106:109], v[210:213], v[10:13], v[30:33]
	v_mfma_f32_16x16x32_bf16 v[30:33], v[206:209], v[18:21], v[98:101]
	v_mfma_f32_16x16x32_bf16 v[74:77], v[210:213], v[186:189], v[30:33]
	s_setprio 0
	s_barrier
	ds_read_b128 v[198:201], v168
	ds_read_b128 v[234:237], v168 offset:1024
	ds_read_b128 v[238:241], v168 offset:2048
	ds_read_b128 v[242:245], v168 offset:3072
	s_waitcnt vmcnt(0)
	s_barrier
	s_waitcnt lgkmcnt(0)
	s_setprio 1
	s_waitcnt lgkmcnt(0)
	v_mfma_f32_16x16x32_bf16 v[30:33], v[14:17], v[198:201], v[214:217]
	v_mfma_f32_16x16x32_bf16 v[14:17], v[14:17], v[238:241], v[154:157]
	v_mfma_f32_16x16x32_bf16 v[58:61], v[22:25], v[234:237], v[30:33]
	v_mfma_f32_16x16x32_bf16 v[30:33], v[22:25], v[242:245], v[14:17]
	v_mfma_f32_16x16x32_bf16 v[14:17], v[26:29], v[198:201], v[86:89]
	v_mfma_f32_16x16x32_bf16 v[62:65], v[46:49], v[234:237], v[14:17]
	v_mfma_f32_16x16x32_bf16 v[14:17], v[26:29], v[238:241], v[170:173]
	v_mfma_f32_16x16x32_bf16 v[26:29], v[46:49], v[242:245], v[14:17]
	v_mfma_f32_16x16x32_bf16 v[14:17], v[190:193], v[198:201], v[78:81]
	v_mfma_f32_16x16x32_bf16 v[54:57], v[202:205], v[234:237], v[14:17]
	v_mfma_f32_16x16x32_bf16 v[14:17], v[190:193], v[238:241], v[174:177]
	v_mfma_f32_16x16x32_bf16 v[22:25], v[202:205], v[242:245], v[14:17]
	v_mfma_f32_16x16x32_bf16 v[14:17], v[206:209], v[198:201], v[70:73]
	v_mfma_f32_16x16x32_bf16 v[46:49], v[210:213], v[234:237], v[14:17]
	v_mfma_f32_16x16x32_bf16 v[14:17], v[206:209], v[238:241], v[66:69]
	v_mfma_f32_16x16x32_bf16 v[14:17], v[210:213], v[242:245], v[14:17]
	s_setprio 0
	s_barrier
	ds_read_b128 v[152:155], v162 offset:49152
	ds_read_b128 v[156:159], v162 offset:50176
	ds_read_b128 v[170:173], v163 offset:49152
	ds_read_b128 v[174:177], v163 offset:50176
	ds_read_b128 v[190:193], v164 offset:49152
	ds_read_b128 v[202:205], v164 offset:50176
	ds_read_b128 v[206:209], v165 offset:49152
	ds_read_b128 v[210:213], v165 offset:50176
	s_barrier
	s_waitcnt lgkmcnt(0)
	s_setprio 1
	s_waitcnt lgkmcnt(0)
	v_mfma_f32_16x16x32_bf16 v[66:69], v[152:155], v[6:9], v[194:197]
	v_mfma_f32_16x16x32_bf16 v[114:117], v[156:159], v[10:13], v[66:69]
	v_mfma_f32_16x16x32_bf16 v[66:69], v[152:155], v[18:21], v[218:221]
	v_mfma_f32_16x16x32_bf16 v[50:53], v[170:173], v[18:21], v[50:53]
	v_mfma_f32_16x16x32_bf16 v[86:89], v[156:159], v[186:189], v[66:69]
	v_mfma_f32_16x16x32_bf16 v[66:69], v[170:173], v[6:9], v[222:225]
	v_mfma_f32_16x16x32_bf16 v[78:81], v[174:177], v[186:189], v[50:53]
	v_mfma_f32_16x16x32_bf16 v[50:53], v[190:193], v[6:9], v[226:229]
	v_mfma_f32_16x16x32_bf16 v[6:9], v[206:209], v[6:9], v[38:41]
	v_mfma_f32_16x16x32_bf16 v[42:45], v[190:193], v[18:21], v[42:45]
	v_mfma_f32_16x16x32_bf16 v[98:101], v[210:213], v[10:13], v[6:9]
	v_mfma_f32_16x16x32_bf16 v[6:9], v[206:209], v[18:21], v[34:37]
	v_mfma_f32_16x16x32_bf16 v[110:113], v[174:177], v[10:13], v[66:69]
	v_mfma_f32_16x16x32_bf16 v[102:105], v[202:205], v[10:13], v[50:53]
	v_mfma_f32_16x16x32_bf16 v[70:73], v[202:205], v[186:189], v[42:45]
	v_mfma_f32_16x16x32_bf16 v[66:69], v[210:213], v[186:189], v[6:9]
	s_setprio 0
	s_setprio 1
	v_mfma_f32_16x16x32_bf16 v[6:9], v[152:155], v[198:201], v[136:139]
	v_mfma_f32_16x16x32_bf16 v[50:53], v[156:159], v[234:237], v[6:9]
	v_mfma_f32_16x16x32_bf16 v[6:9], v[152:155], v[238:241], v[140:143]
	v_mfma_f32_16x16x32_bf16 v[18:21], v[156:159], v[242:245], v[6:9]
	v_mfma_f32_16x16x32_bf16 v[6:9], v[170:173], v[198:201], v[144:147]
	v_mfma_f32_16x16x32_bf16 v[42:45], v[174:177], v[234:237], v[6:9]
	v_mfma_f32_16x16x32_bf16 v[6:9], v[170:173], v[238:241], v[148:151]
	v_mfma_f32_16x16x32_bf16 v[10:13], v[174:177], v[242:245], v[6:9]
	v_mfma_f32_16x16x32_bf16 v[6:9], v[190:193], v[198:201], v[230:233]
	v_mfma_f32_16x16x32_bf16 v[38:41], v[202:205], v[234:237], v[6:9]
	v_mfma_f32_16x16x32_bf16 v[6:9], v[190:193], v[238:241], v[178:181]
	v_mfma_f32_16x16x32_bf16 v[34:37], v[206:209], v[198:201], v[182:185]
	v_mfma_f32_16x16x32_bf16 v[2:5], v[206:209], v[238:241], v[2:5]
	v_mfma_f32_16x16x32_bf16 v[6:9], v[202:205], v[242:245], v[6:9]
	v_mfma_f32_16x16x32_bf16 v[34:37], v[210:213], v[234:237], v[34:37]
	v_mfma_f32_16x16x32_bf16 v[2:5], v[210:213], v[242:245], v[2:5]
	s_setprio 0
	s_barrier
	s_and_saveexec_b64 s[6:7], s[2:3]
	s_cbranch_execz .LBB0_294
	s_barrier

.LBB0_315:
	ds_read_b128 v[140:143], v156
	ds_read_b128 v[150:153], v156 offset:1024
	ds_read_b128 v[166:169], v156 offset:2048
	ds_read_b128 v[170:173], v156 offset:3072
	v_lshl_add_u64 v[144:145], v[136:137], 0, s[48:49]
	s_mov_b32 m0, s70
	v_lshl_add_u64 v[154:155], v[144:145], 0, s[22:23]
	ds_read_b128 v[174:177], v157
	ds_read_b128 v[178:181], v157 offset:1024
	ds_read_b128 v[182:185], v158
	ds_read_b128 v[186:189], v158 offset:1024
	ds_read_b128 v[190:193], v159
	ds_read_b128 v[194:197], v159 offset:1024
	ds_read_b128 v[198:201], v160
	ds_read_b128 v[202:205], v160 offset:1024
	global_load_lds_dwordx4 v[154:155], off
	v_lshl_add_u64 v[154:155], v[138:139], 0, s[48:49]
	v_lshl_add_u64 v[206:207], v[154:155], 0, s[22:23]
	s_mov_b32 m0, s68
	s_nop 0
	global_load_lds_dwordx4 v[206:207], off
	s_waitcnt lgkmcnt(8)
	s_barrier
	s_setprio 1
	s_waitcnt lgkmcnt(7)
	v_mfma_f32_16x16x32_bf16 v[126:129], v[174:177], v[140:143], v[126:129]
	v_mfma_f32_16x16x32_bf16 v[122:125], v[174:177], v[166:169], v[122:125]
	s_waitcnt lgkmcnt(5)
	v_mfma_f32_16x16x32_bf16 v[118:121], v[182:185], v[140:143], v[118:121]
	v_mfma_f32_16x16x32_bf16 v[114:117], v[182:185], v[166:169], v[114:117]
	s_waitcnt lgkmcnt(3)
	v_mfma_f32_16x16x32_bf16 v[110:113], v[190:193], v[140:143], v[110:113]
	v_mfma_f32_16x16x32_bf16 v[106:109], v[190:193], v[166:169], v[106:109]
	s_waitcnt lgkmcnt(1)
	v_mfma_f32_16x16x32_bf16 v[102:105], v[198:201], v[140:143], v[102:105]
	v_mfma_f32_16x16x32_bf16 v[98:101], v[198:201], v[166:169], v[98:101]
	v_mfma_f32_16x16x32_bf16 v[126:129], v[178:181], v[150:153], v[126:129]
	v_mfma_f32_16x16x32_bf16 v[122:125], v[178:181], v[170:173], v[122:125]
	v_mfma_f32_16x16x32_bf16 v[118:121], v[186:189], v[150:153], v[118:121]
	v_mfma_f32_16x16x32_bf16 v[114:117], v[186:189], v[170:173], v[114:117]
	v_mfma_f32_16x16x32_bf16 v[110:113], v[194:197], v[150:153], v[110:113]
	v_mfma_f32_16x16x32_bf16 v[106:109], v[194:197], v[170:173], v[106:109]
	s_waitcnt lgkmcnt(0)
	v_mfma_f32_16x16x32_bf16 v[102:105], v[202:205], v[150:153], v[102:105]
	v_mfma_f32_16x16x32_bf16 v[98:101], v[202:205], v[170:173], v[98:101]
	s_setprio 0
	s_barrier
	v_lshl_add_u64 v[222:223], v[132:133], 0, s[48:49]
	s_mov_b32 m0, s59
	v_lshl_add_u64 v[224:225], v[222:223], 0, s[26:27]
	ds_read_b128 v[206:209], v161
	ds_read_b128 v[210:213], v161 offset:1024
	ds_read_b128 v[214:217], v161 offset:2048
	ds_read_b128 v[218:221], v161 offset:3072
	global_load_lds_dwordx4 v[224:225], off
	v_lshl_add_u64 v[224:225], v[134:135], 0, s[48:49]
	v_lshl_add_u64 v[226:227], v[224:225], 0, s[26:27]
	s_mov_b32 m0, s60
	s_nop 0
	global_load_lds_dwordx4 v[226:227], off
	s_barrier
	s_setprio 1
	s_waitcnt lgkmcnt(3)
	v_mfma_f32_16x16x32_bf16 v[94:97], v[174:177], v[206:209], v[94:97]
	s_waitcnt lgkmcnt(1)
	v_mfma_f32_16x16x32_bf16 v[90:93], v[174:177], v[214:217], v[90:93]
	v_mfma_f32_16x16x32_bf16 v[86:89], v[182:185], v[206:209], v[86:89]
	v_mfma_f32_16x16x32_bf16 v[82:85], v[182:185], v[214:217], v[82:85]
	v_mfma_f32_16x16x32_bf16 v[78:81], v[190:193], v[206:209], v[78:81]
	v_mfma_f32_16x16x32_bf16 v[74:77], v[190:193], v[214:217], v[74:77]
	v_mfma_f32_16x16x32_bf16 v[70:73], v[198:201], v[206:209], v[70:73]
	v_mfma_f32_16x16x32_bf16 v[66:69], v[198:201], v[214:217], v[66:69]
	v_mfma_f32_16x16x32_bf16 v[94:97], v[178:181], v[210:213], v[94:97]
	s_waitcnt lgkmcnt(0)
	v_mfma_f32_16x16x32_bf16 v[90:93], v[178:181], v[218:221], v[90:93]
	v_mfma_f32_16x16x32_bf16 v[86:89], v[186:189], v[210:213], v[86:89]
	v_mfma_f32_16x16x32_bf16 v[82:85], v[186:189], v[218:221], v[82:85]
	v_mfma_f32_16x16x32_bf16 v[78:81], v[194:197], v[210:213], v[78:81]
	v_mfma_f32_16x16x32_bf16 v[74:77], v[194:197], v[218:221], v[74:77]
	v_mfma_f32_16x16x32_bf16 v[70:73], v[202:205], v[210:213], v[70:73]
	v_mfma_f32_16x16x32_bf16 v[66:69], v[202:205], v[218:221], v[66:69]
	s_setprio 0
	s_mov_b32 m0, s39
	v_lshl_add_u64 v[226:227], v[144:145], 0, s[26:27]
	s_barrier
	ds_read_b128 v[174:177], v157 offset:16384
	ds_read_b128 v[178:181], v157 offset:17408
	ds_read_b128 v[182:185], v158 offset:16384
	ds_read_b128 v[186:189], v158 offset:17408
	ds_read_b128 v[190:193], v159 offset:16384
	ds_read_b128 v[194:197], v159 offset:17408
	ds_read_b128 v[198:201], v160 offset:16384
	ds_read_b128 v[202:205], v160 offset:17408
	global_load_lds_dwordx4 v[226:227], off
	v_lshl_add_u64 v[226:227], v[154:155], 0, s[26:27]
	s_mov_b32 m0, s61
	s_nop 0
	global_load_lds_dwordx4 v[226:227], off
	s_barrier
	s_setprio 1
	s_waitcnt lgkmcnt(7)
	v_mfma_f32_16x16x32_bf16 v[62:65], v[174:177], v[140:143], v[62:65]
	v_mfma_f32_16x16x32_bf16 v[58:61], v[174:177], v[166:169], v[58:61]
	s_waitcnt lgkmcnt(5)
	v_mfma_f32_16x16x32_bf16 v[54:57], v[182:185], v[140:143], v[54:57]
	v_mfma_f32_16x16x32_bf16 v[50:53], v[182:185], v[166:169], v[50:53]
	s_waitcnt lgkmcnt(3)
	v_mfma_f32_16x16x32_bf16 v[46:49], v[190:193], v[140:143], v[46:49]
	v_mfma_f32_16x16x32_bf16 v[42:45], v[190:193], v[166:169], v[42:45]
	s_waitcnt lgkmcnt(1)
	v_mfma_f32_16x16x32_bf16 v[38:41], v[198:201], v[140:143], v[38:41]
	v_mfma_f32_16x16x32_bf16 v[34:37], v[198:201], v[166:169], v[34:37]
	v_mfma_f32_16x16x32_bf16 v[62:65], v[178:181], v[150:153], v[62:65]
	v_mfma_f32_16x16x32_bf16 v[58:61], v[178:181], v[170:173], v[58:61]
	v_mfma_f32_16x16x32_bf16 v[54:57], v[186:189], v[150:153], v[54:57]
	v_mfma_f32_16x16x32_bf16 v[50:53], v[186:189], v[170:173], v[50:53]
	v_mfma_f32_16x16x32_bf16 v[46:49], v[194:197], v[150:153], v[46:49]
	v_mfma_f32_16x16x32_bf16 v[42:45], v[194:197], v[170:173], v[42:45]
	s_waitcnt lgkmcnt(0)
	v_mfma_f32_16x16x32_bf16 v[38:41], v[202:205], v[150:153], v[38:41]
	v_mfma_f32_16x16x32_bf16 v[34:37], v[202:205], v[170:173], v[34:37]
	s_setprio 0
	s_barrier
	s_mov_b32 m0, s62
	v_lshl_add_u64 v[140:141], v[222:223], 0, s[28:29]
	global_load_lds_dwordx4 v[140:141], off
	v_lshl_add_u64 v[140:141], v[224:225], 0, s[28:29]
	s_mov_b32 m0, s63
	s_nop 0
	global_load_lds_dwordx4 v[140:141], off
	s_waitcnt vmcnt(6)
	s_barrier
	s_setprio 1
	v_mfma_f32_16x16x32_bf16 v[30:33], v[174:177], v[206:209], v[30:33]
	v_mfma_f32_16x16x32_bf16 v[26:29], v[174:177], v[214:217], v[26:29]
	v_mfma_f32_16x16x32_bf16 v[22:25], v[182:185], v[206:209], v[22:25]
	v_mfma_f32_16x16x32_bf16 v[18:21], v[182:185], v[214:217], v[18:21]
	v_mfma_f32_16x16x32_bf16 v[14:17], v[190:193], v[206:209], v[14:17]
	v_mfma_f32_16x16x32_bf16 v[10:13], v[190:193], v[214:217], v[10:13]
	v_mfma_f32_16x16x32_bf16 v[6:9], v[198:201], v[206:209], v[6:9]
	v_mfma_f32_16x16x32_bf16 v[2:5], v[198:201], v[214:217], v[2:5]
	v_mfma_f32_16x16x32_bf16 v[30:33], v[178:181], v[210:213], v[30:33]
	v_mfma_f32_16x16x32_bf16 v[26:29], v[178:181], v[218:221], v[26:29]
	v_mfma_f32_16x16x32_bf16 v[22:25], v[186:189], v[210:213], v[22:25]
	v_mfma_f32_16x16x32_bf16 v[18:21], v[186:189], v[218:221], v[18:21]
	v_mfma_f32_16x16x32_bf16 v[14:17], v[194:197], v[210:213], v[14:17]
	v_mfma_f32_16x16x32_bf16 v[10:13], v[194:197], v[218:221], v[10:13]
	v_mfma_f32_16x16x32_bf16 v[6:9], v[202:205], v[210:213], v[6:9]
	v_mfma_f32_16x16x32_bf16 v[2:5], v[202:205], v[218:221], v[2:5]
	s_setprio 0
	s_barrier
	ds_read_b128 v[140:143], v162
	ds_read_b128 v[150:153], v162 offset:1024
	ds_read_b128 v[166:169], v162 offset:2048
	ds_read_b128 v[170:173], v162 offset:3072
	s_mov_b32 m0, s64
	v_lshl_add_u64 v[206:207], v[144:145], 0, s[28:29]
	ds_read_b128 v[174:177], v157 offset:32768
	ds_read_b128 v[178:181], v157 offset:33792
	ds_read_b128 v[182:185], v158 offset:32768
	ds_read_b128 v[186:189], v158 offset:33792
	ds_read_b128 v[190:193], v159 offset:32768
	ds_read_b128 v[194:197], v159 offset:33792
	ds_read_b128 v[198:201], v160 offset:32768
	ds_read_b128 v[202:205], v160 offset:33792
	global_load_lds_dwordx4 v[206:207], off
	v_lshl_add_u64 v[206:207], v[154:155], 0, s[28:29]
	s_mov_b32 m0, s65
	s_nop 0
	global_load_lds_dwordx4 v[206:207], off
	s_waitcnt lgkmcnt(8)
	s_barrier
	s_setprio 1
	s_waitcnt lgkmcnt(7)
	v_mfma_f32_16x16x32_bf16 v[126:129], v[174:177], v[140:143], v[126:129]
	v_mfma_f32_16x16x32_bf16 v[122:125], v[174:177], v[166:169], v[122:125]
	s_waitcnt lgkmcnt(5)
	v_mfma_f32_16x16x32_bf16 v[118:121], v[182:185], v[140:143], v[118:121]
	v_mfma_f32_16x16x32_bf16 v[114:117], v[182:185], v[166:169], v[114:117]
	s_waitcnt lgkmcnt(3)
	v_mfma_f32_16x16x32_bf16 v[110:113], v[190:193], v[140:143], v[110:113]
	v_mfma_f32_16x16x32_bf16 v[106:109], v[190:193], v[166:169], v[106:109]
	s_waitcnt lgkmcnt(1)
	v_mfma_f32_16x16x32_bf16 v[102:105], v[198:201], v[140:143], v[102:105]
	v_mfma_f32_16x16x32_bf16 v[98:101], v[198:201], v[166:169], v[98:101]
	v_mfma_f32_16x16x32_bf16 v[126:129], v[178:181], v[150:153], v[126:129]
	v_mfma_f32_16x16x32_bf16 v[122:125], v[178:181], v[170:173], v[122:125]
	v_mfma_f32_16x16x32_bf16 v[118:121], v[186:189], v[150:153], v[118:121]
	v_mfma_f32_16x16x32_bf16 v[114:117], v[186:189], v[170:173], v[114:117]
	v_mfma_f32_16x16x32_bf16 v[110:113], v[194:197], v[150:153], v[110:113]
	v_mfma_f32_16x16x32_bf16 v[106:109], v[194:197], v[170:173], v[106:109]
	s_waitcnt lgkmcnt(0)
	v_mfma_f32_16x16x32_bf16 v[102:105], v[202:205], v[150:153], v[102:105]
	v_mfma_f32_16x16x32_bf16 v[98:101], v[202:205], v[170:173], v[98:101]
	s_setprio 0
	s_barrier
	s_mov_b32 m0, s54
	v_lshl_add_u64 v[226:227], v[222:223], 0, s[30:31]
	ds_read_b128 v[206:209], v163
	ds_read_b128 v[210:213], v163 offset:1024
	ds_read_b128 v[214:217], v163 offset:2048
	ds_read_b128 v[218:221], v163 offset:3072
	global_load_lds_dwordx4 v[226:227], off
	v_lshl_add_u64 v[226:227], v[224:225], 0, s[30:31]
	s_mov_b32 m0, s55
	s_nop 0
	global_load_lds_dwordx4 v[226:227], off
	s_barrier
	s_setprio 1
	s_waitcnt lgkmcnt(3)
	v_mfma_f32_16x16x32_bf16 v[94:97], v[174:177], v[206:209], v[94:97]
	s_waitcnt lgkmcnt(1)
	v_mfma_f32_16x16x32_bf16 v[90:93], v[174:177], v[214:217], v[90:93]
	v_mfma_f32_16x16x32_bf16 v[86:89], v[182:185], v[206:209], v[86:89]
	v_mfma_f32_16x16x32_bf16 v[82:85], v[182:185], v[214:217], v[82:85]
	v_mfma_f32_16x16x32_bf16 v[78:81], v[190:193], v[206:209], v[78:81]
	v_mfma_f32_16x16x32_bf16 v[74:77], v[190:193], v[214:217], v[74:77]
	v_mfma_f32_16x16x32_bf16 v[70:73], v[198:201], v[206:209], v[70:73]
	v_mfma_f32_16x16x32_bf16 v[66:69], v[198:201], v[214:217], v[66:69]
	v_mfma_f32_16x16x32_bf16 v[94:97], v[178:181], v[210:213], v[94:97]
	s_waitcnt lgkmcnt(0)
	v_mfma_f32_16x16x32_bf16 v[90:93], v[178:181], v[218:221], v[90:93]
	v_mfma_f32_16x16x32_bf16 v[86:89], v[186:189], v[210:213], v[86:89]
	v_mfma_f32_16x16x32_bf16 v[82:85], v[186:189], v[218:221], v[82:85]
	v_mfma_f32_16x16x32_bf16 v[78:81], v[194:197], v[210:213], v[78:81]
	v_mfma_f32_16x16x32_bf16 v[74:77], v[194:197], v[218:221], v[74:77]
	v_mfma_f32_16x16x32_bf16 v[70:73], v[202:205], v[210:213], v[70:73]
	v_mfma_f32_16x16x32_bf16 v[66:69], v[202:205], v[218:221], v[66:69]
	s_setprio 0
	s_mov_b32 m0, s66
	v_lshl_add_u64 v[144:145], v[144:145], 0, s[30:31]
	s_barrier
	ds_read_b128 v[174:177], v157 offset:49152
	ds_read_b128 v[178:181], v157 offset:50176
	ds_read_b128 v[182:185], v158 offset:49152
	ds_read_b128 v[186:189], v158 offset:50176
	ds_read_b128 v[190:193], v159 offset:49152
	ds_read_b128 v[194:197], v159 offset:50176
	ds_read_b128 v[198:201], v160 offset:49152
	ds_read_b128 v[202:205], v160 offset:50176
	global_load_lds_dwordx4 v[144:145], off
	v_lshl_add_u64 v[144:145], v[154:155], 0, s[30:31]
	s_mov_b32 m0, s67
	s_nop 0
	global_load_lds_dwordx4 v[144:145], off
	s_barrier
	s_setprio 1
	s_waitcnt lgkmcnt(7)
	v_mfma_f32_16x16x32_bf16 v[62:65], v[174:177], v[140:143], v[62:65]
	v_mfma_f32_16x16x32_bf16 v[58:61], v[174:177], v[166:169], v[58:61]
	s_waitcnt lgkmcnt(5)
	v_mfma_f32_16x16x32_bf16 v[54:57], v[182:185], v[140:143], v[54:57]
	v_mfma_f32_16x16x32_bf16 v[50:53], v[182:185], v[166:169], v[50:53]
	s_waitcnt lgkmcnt(3)
	v_mfma_f32_16x16x32_bf16 v[46:49], v[190:193], v[140:143], v[46:49]
	v_mfma_f32_16x16x32_bf16 v[42:45], v[190:193], v[166:169], v[42:45]
	s_waitcnt lgkmcnt(1)
	v_mfma_f32_16x16x32_bf16 v[38:41], v[198:201], v[140:143], v[38:41]
	v_mfma_f32_16x16x32_bf16 v[34:37], v[198:201], v[166:169], v[34:37]
	v_mfma_f32_16x16x32_bf16 v[62:65], v[178:181], v[150:153], v[62:65]
	v_mfma_f32_16x16x32_bf16 v[58:61], v[178:181], v[170:173], v[58:61]
	v_mfma_f32_16x16x32_bf16 v[54:57], v[186:189], v[150:153], v[54:57]
	v_mfma_f32_16x16x32_bf16 v[50:53], v[186:189], v[170:173], v[50:53]
	v_mfma_f32_16x16x32_bf16 v[46:49], v[194:197], v[150:153], v[46:49]
	v_mfma_f32_16x16x32_bf16 v[42:45], v[194:197], v[170:173], v[42:45]
	s_waitcnt lgkmcnt(0)
	v_mfma_f32_16x16x32_bf16 v[38:41], v[202:205], v[150:153], v[38:41]
	v_mfma_f32_16x16x32_bf16 v[34:37], v[202:205], v[170:173], v[34:37]
	s_setprio 0
	s_barrier
	s_mov_b32 m0, s50
	v_lshl_add_u64 v[140:141], v[222:223], 0, s[34:35]
	global_load_lds_dwordx4 v[140:141], off
	v_lshl_add_u64 v[140:141], v[224:225], 0, s[34:35]
	s_mov_b32 m0, s51
	s_nop 0
	global_load_lds_dwordx4 v[140:141], off
	s_waitcnt vmcnt(6)
	s_barrier
	s_setprio 1
	v_mfma_f32_16x16x32_bf16 v[30:33], v[174:177], v[206:209], v[30:33]
	v_mfma_f32_16x16x32_bf16 v[26:29], v[174:177], v[214:217], v[26:29]
	v_mfma_f32_16x16x32_bf16 v[22:25], v[182:185], v[206:209], v[22:25]
	v_mfma_f32_16x16x32_bf16 v[18:21], v[182:185], v[214:217], v[18:21]
	v_mfma_f32_16x16x32_bf16 v[14:17], v[190:193], v[206:209], v[14:17]
	v_mfma_f32_16x16x32_bf16 v[10:13], v[190:193], v[214:217], v[10:13]
	v_mfma_f32_16x16x32_bf16 v[6:9], v[198:201], v[206:209], v[6:9]
	v_mfma_f32_16x16x32_bf16 v[2:5], v[198:201], v[214:217], v[2:5]
	v_mfma_f32_16x16x32_bf16 v[30:33], v[178:181], v[210:213], v[30:33]
	v_mfma_f32_16x16x32_bf16 v[26:29], v[178:181], v[218:221], v[26:29]
	v_mfma_f32_16x16x32_bf16 v[22:25], v[186:189], v[210:213], v[22:25]
	v_mfma_f32_16x16x32_bf16 v[18:21], v[186:189], v[218:221], v[18:21]
	v_mfma_f32_16x16x32_bf16 v[14:17], v[194:197], v[210:213], v[14:17]
	v_mfma_f32_16x16x32_bf16 v[10:13], v[194:197], v[218:221], v[10:13]
	v_mfma_f32_16x16x32_bf16 v[6:9], v[202:205], v[210:213], v[6:9]
	v_mfma_f32_16x16x32_bf16 v[2:5], v[202:205], v[218:221], v[2:5]
	s_setprio 0
	s_add_i32 s69, s69, 2
	s_add_u32 s48, s48, 0x100
	s_addc_u32 s49, s49, 0
	s_cmp_lt_u32 s69, 12
	s_barrier
	s_cbranch_scc1 .LBB0_315
	s_add_u32 s0, s46, 0x40780
	s_addc_u32 s1, s47, 0
	s_mov_b32 m0, s70
	v_lshl_add_u64 v[144:145], v[148:149], 1, s[0:1]
	ds_read_b128 v[132:135], v156
	ds_read_b128 v[136:139], v156 offset:1024
	ds_read_b128 v[140:143], v156 offset:2048
	ds_read_b128 v[150:153], v156 offset:3072
	ds_read_b128 v[166:169], v157
	ds_read_b128 v[170:173], v157 offset:1024
	ds_read_b128 v[174:177], v158
	ds_read_b128 v[178:181], v158 offset:1024
	ds_read_b128 v[182:185], v159
	ds_read_b128 v[186:189], v159 offset:1024
	ds_read_b128 v[190:193], v160
	ds_read_b128 v[194:197], v160 offset:1024
	global_load_lds_dwordx4 v[144:145], off
	v_lshl_add_u64 v[130:131], v[130:131], 1, s[0:1]
	s_mov_b32 m0, s68
	s_nop 0
	global_load_lds_dwordx4 v[130:131], off
	s_barrier
	s_waitcnt lgkmcnt(0)
	s_setprio 1
	s_waitcnt lgkmcnt(0)
	v_mfma_f32_16x16x32_bf16 v[126:129], v[166:169], v[132:135], v[126:129]
	v_mfma_f32_16x16x32_bf16 v[122:125], v[166:169], v[140:143], v[122:125]
	v_mfma_f32_16x16x32_bf16 v[114:117], v[174:177], v[140:143], v[114:117]
	v_mfma_f32_16x16x32_bf16 v[110:113], v[182:185], v[132:135], v[110:113]
	v_mfma_f32_16x16x32_bf16 v[106:109], v[182:185], v[140:143], v[106:109]
	v_mfma_f32_16x16x32_bf16 v[102:105], v[190:193], v[132:135], v[102:105]
	v_mfma_f32_16x16x32_bf16 v[98:101], v[190:193], v[140:143], v[98:101]
	v_mfma_f32_16x16x32_bf16 v[126:129], v[170:173], v[136:139], v[126:129]
	v_mfma_f32_16x16x32_bf16 v[122:125], v[170:173], v[150:153], v[122:125]
	v_mfma_f32_16x16x32_bf16 v[118:121], v[174:177], v[132:135], v[118:121]
	v_mfma_f32_16x16x32_bf16 v[114:117], v[178:181], v[150:153], v[114:117]
	v_mfma_f32_16x16x32_bf16 v[110:113], v[186:189], v[136:139], v[110:113]
	v_mfma_f32_16x16x32_bf16 v[106:109], v[186:189], v[150:153], v[106:109]
	v_mfma_f32_16x16x32_bf16 v[102:105], v[194:197], v[136:139], v[102:105]
	v_mfma_f32_16x16x32_bf16 v[98:101], v[194:197], v[150:153], v[98:101]
	v_mfma_f32_16x16x32_bf16 v[198:201], v[178:181], v[136:139], v[118:121]
	s_setprio 0
	s_barrier
	s_nop 0
	ds_read_b128 v[118:121], v161
	ds_read_b128 v[202:205], v161 offset:1024
	ds_read_b128 v[206:209], v161 offset:2048
	ds_read_b128 v[210:213], v161 offset:3072
	s_barrier
	s_waitcnt lgkmcnt(0)
	s_setprio 1
	s_waitcnt lgkmcnt(0)
	v_mfma_f32_16x16x32_bf16 v[78:81], v[182:185], v[118:121], v[78:81]
	v_mfma_f32_16x16x32_bf16 v[74:77], v[182:185], v[206:209], v[74:77]
	v_mfma_f32_16x16x32_bf16 v[70:73], v[190:193], v[118:121], v[70:73]
	v_mfma_f32_16x16x32_bf16 v[66:69], v[190:193], v[206:209], v[66:69]
	v_mfma_f32_16x16x32_bf16 v[94:97], v[166:169], v[118:121], v[94:97]
	v_mfma_f32_16x16x32_bf16 v[90:93], v[166:169], v[206:209], v[90:93]
	v_mfma_f32_16x16x32_bf16 v[86:89], v[174:177], v[118:121], v[86:89]
	v_mfma_f32_16x16x32_bf16 v[82:85], v[174:177], v[206:209], v[82:85]
	v_mfma_f32_16x16x32_bf16 v[78:81], v[186:189], v[202:205], v[78:81]
	v_mfma_f32_16x16x32_bf16 v[74:77], v[186:189], v[210:213], v[74:77]
	v_mfma_f32_16x16x32_bf16 v[70:73], v[194:197], v[202:205], v[70:73]
	v_mfma_f32_16x16x32_bf16 v[66:69], v[194:197], v[210:213], v[66:69]
	v_mfma_f32_16x16x32_bf16 v[214:217], v[170:173], v[202:205], v[94:97]
	v_mfma_f32_16x16x32_bf16 v[166:169], v[170:173], v[210:213], v[90:93]
	v_mfma_f32_16x16x32_bf16 v[170:173], v[178:181], v[202:205], v[86:89]
	v_mfma_f32_16x16x32_bf16 v[174:177], v[178:181], v[210:213], v[82:85]
	s_setprio 0
	s_barrier
	s_nop 0
	ds_read_b128 v[82:85], v157 offset:16384
	ds_read_b128 v[86:89], v157 offset:17408
	ds_read_b128 v[90:93], v158 offset:16384
	ds_read_b128 v[94:97], v158 offset:17408
	ds_read_b128 v[178:181], v159 offset:16384
	ds_read_b128 v[182:185], v159 offset:17408
	ds_read_b128 v[186:189], v160 offset:16384
	ds_read_b128 v[190:193], v160 offset:17408
	s_waitcnt vmcnt(4)
	s_barrier
	s_waitcnt lgkmcnt(0)
	s_setprio 1
	s_waitcnt lgkmcnt(0)
	v_mfma_f32_16x16x32_bf16 v[46:49], v[178:181], v[132:135], v[46:49]
	v_mfma_f32_16x16x32_bf16 v[42:45], v[178:181], v[140:143], v[42:45]
	v_mfma_f32_16x16x32_bf16 v[38:41], v[186:189], v[132:135], v[38:41]
	v_mfma_f32_16x16x32_bf16 v[34:37], v[186:189], v[140:143], v[34:37]
	v_mfma_f32_16x16x32_bf16 v[62:65], v[82:85], v[132:135], v[62:65]
	v_mfma_f32_16x16x32_bf16 v[58:61], v[82:85], v[140:143], v[58:61]
	v_mfma_f32_16x16x32_bf16 v[54:57], v[90:93], v[132:135], v[54:57]
	v_mfma_f32_16x16x32_bf16 v[50:53], v[90:93], v[140:143], v[50:53]
	v_mfma_f32_16x16x32_bf16 v[46:49], v[182:185], v[136:139], v[46:49]
	v_mfma_f32_16x16x32_bf16 v[42:45], v[182:185], v[150:153], v[42:45]
	v_mfma_f32_16x16x32_bf16 v[38:41], v[190:193], v[136:139], v[38:41]
	v_mfma_f32_16x16x32_bf16 v[34:37], v[190:193], v[150:153], v[34:37]
	v_mfma_f32_16x16x32_bf16 v[194:197], v[86:89], v[136:139], v[62:65]
	v_mfma_f32_16x16x32_bf16 v[218:221], v[86:89], v[150:153], v[58:61]
	v_mfma_f32_16x16x32_bf16 v[222:225], v[94:97], v[136:139], v[54:57]
	v_mfma_f32_16x16x32_bf16 v[226:229], v[94:97], v[150:153], v[50:53]
	s_setprio 0
	s_setprio 1
	v_mfma_f32_16x16x32_bf16 v[2:5], v[186:189], v[206:209], v[2:5]
	v_mfma_f32_16x16x32_bf16 v[30:33], v[82:85], v[118:121], v[30:33]
	v_mfma_f32_16x16x32_bf16 v[26:29], v[82:85], v[206:209], v[26:29]
	v_mfma_f32_16x16x32_bf16 v[22:25], v[90:93], v[118:121], v[22:25]
	v_mfma_f32_16x16x32_bf16 v[18:21], v[90:93], v[206:209], v[18:21]
	v_mfma_f32_16x16x32_bf16 v[14:17], v[178:181], v[118:121], v[14:17]
	v_mfma_f32_16x16x32_bf16 v[10:13], v[178:181], v[206:209], v[10:13]
	v_mfma_f32_16x16x32_bf16 v[6:9], v[186:189], v[118:121], v[6:9]
	v_mfma_f32_16x16x32_bf16 v[2:5], v[190:193], v[210:213], v[2:5]
	v_mfma_f32_16x16x32_bf16 v[130:133], v[86:89], v[202:205], v[30:33]
	v_mfma_f32_16x16x32_bf16 v[134:137], v[86:89], v[210:213], v[26:29]
	v_mfma_f32_16x16x32_bf16 v[138:141], v[94:97], v[202:205], v[22:25]
	v_mfma_f32_16x16x32_bf16 v[142:145], v[94:97], v[210:213], v[18:21]
	v_mfma_f32_16x16x32_bf16 v[150:153], v[182:185], v[202:205], v[14:17]
	v_mfma_f32_16x16x32_bf16 v[178:181], v[182:185], v[210:213], v[10:13]
	v_mfma_f32_16x16x32_bf16 v[182:185], v[190:193], v[202:205], v[6:9]
	s_setprio 0
	s_barrier
	s_nop 0
	ds_read_b128 v[6:9], v162
	ds_read_b128 v[10:13], v162 offset:1024
	ds_read_b128 v[14:17], v162 offset:2048
	ds_read_b128 v[186:189], v162 offset:3072
	ds_read_b128 v[18:21], v157 offset:32768
	ds_read_b128 v[22:25], v157 offset:33792
	ds_read_b128 v[26:29], v158 offset:32768
	ds_read_b128 v[30:33], v158 offset:33792
	ds_read_b128 v[50:53], v159 offset:32768
	ds_read_b128 v[190:193], v159 offset:33792
	ds_read_b128 v[202:205], v160 offset:32768
	ds_read_b128 v[206:209], v160 offset:33792
	s_waitcnt vmcnt(2)
	s_barrier
	s_waitcnt lgkmcnt(0)
	s_setprio 1
	s_waitcnt lgkmcnt(0)
	v_mfma_f32_16x16x32_bf16 v[54:57], v[18:21], v[6:9], v[126:129]
	v_mfma_f32_16x16x32_bf16 v[118:121], v[22:25], v[10:13], v[54:57]
	v_mfma_f32_16x16x32_bf16 v[54:57], v[18:21], v[14:17], v[122:125]
	v_mfma_f32_16x16x32_bf16 v[86:89], v[22:25], v[186:189], v[54:57]
	v_mfma_f32_16x16x32_bf16 v[54:57], v[26:29], v[6:9], v[198:201]
	v_mfma_f32_16x16x32_bf16 v[122:125], v[30:33], v[10:13], v[54:57]
	v_mfma_f32_16x16x32_bf16 v[54:57], v[26:29], v[14:17], v[114:117]
	v_mfma_f32_16x16x32_bf16 v[90:93], v[30:33], v[186:189], v[54:57]
	v_mfma_f32_16x16x32_bf16 v[54:57], v[50:53], v[6:9], v[110:113]
	v_mfma_f32_16x16x32_bf16 v[126:129], v[190:193], v[10:13], v[54:57]
	v_mfma_f32_16x16x32_bf16 v[54:57], v[50:53], v[14:17], v[106:109]
	v_mfma_f32_16x16x32_bf16 v[94:97], v[190:193], v[186:189], v[54:57]
	v_mfma_f32_16x16x32_bf16 v[54:57], v[202:205], v[6:9], v[102:105]
	v_mfma_f32_16x16x32_bf16 v[114:117], v[206:209], v[10:13], v[54:57]
	v_mfma_f32_16x16x32_bf16 v[54:57], v[202:205], v[14:17], v[98:101]
	v_mfma_f32_16x16x32_bf16 v[82:85], v[206:209], v[186:189], v[54:57]
	s_setprio 0
	s_barrier
	ds_read_b128 v[198:201], v163
	ds_read_b128 v[210:213], v163 offset:1024
	ds_read_b128 v[230:233], v163 offset:2048
	ds_read_b128 v[234:237], v163 offset:3072
	s_waitcnt vmcnt(0)
	s_barrier
	s_waitcnt lgkmcnt(0)
	s_setprio 1
	s_waitcnt lgkmcnt(0)
	v_mfma_f32_16x16x32_bf16 v[54:57], v[18:21], v[198:201], v[214:217]
	v_mfma_f32_16x16x32_bf16 v[18:21], v[18:21], v[230:233], v[166:169]
	v_mfma_f32_16x16x32_bf16 v[54:57], v[22:25], v[210:213], v[54:57]
	v_mfma_f32_16x16x32_bf16 v[22:25], v[22:25], v[234:237], v[18:21]
	v_mfma_f32_16x16x32_bf16 v[18:21], v[26:29], v[198:201], v[170:173]
	v_mfma_f32_16x16x32_bf16 v[58:61], v[30:33], v[210:213], v[18:21]
	v_mfma_f32_16x16x32_bf16 v[18:21], v[26:29], v[230:233], v[174:177]
	v_mfma_f32_16x16x32_bf16 v[26:29], v[30:33], v[234:237], v[18:21]
	v_mfma_f32_16x16x32_bf16 v[18:21], v[50:53], v[198:201], v[78:81]
	v_mfma_f32_16x16x32_bf16 v[62:65], v[190:193], v[210:213], v[18:21]
	v_mfma_f32_16x16x32_bf16 v[18:21], v[50:53], v[230:233], v[74:77]
	v_mfma_f32_16x16x32_bf16 v[30:33], v[190:193], v[234:237], v[18:21]
	v_mfma_f32_16x16x32_bf16 v[18:21], v[202:205], v[198:201], v[70:73]
	v_mfma_f32_16x16x32_bf16 v[50:53], v[206:209], v[210:213], v[18:21]
	v_mfma_f32_16x16x32_bf16 v[18:21], v[202:205], v[230:233], v[66:69]
	v_mfma_f32_16x16x32_bf16 v[18:21], v[206:209], v[234:237], v[18:21]
	s_setprio 0
	s_barrier
	ds_read_b128 v[166:169], v157 offset:49152
	ds_read_b128 v[170:173], v157 offset:50176
	ds_read_b128 v[174:177], v158 offset:49152
	ds_read_b128 v[190:193], v158 offset:50176
	ds_read_b128 v[202:205], v159 offset:49152
	ds_read_b128 v[206:209], v159 offset:50176
	ds_read_b128 v[214:217], v160 offset:49152
	ds_read_b128 v[238:241], v160 offset:50176
	s_barrier
	s_waitcnt lgkmcnt(0)
	s_setprio 1
	s_waitcnt lgkmcnt(0)
	v_mfma_f32_16x16x32_bf16 v[66:69], v[166:169], v[6:9], v[194:197]
	v_mfma_f32_16x16x32_bf16 v[110:113], v[170:173], v[10:13], v[66:69]
	v_mfma_f32_16x16x32_bf16 v[66:69], v[166:169], v[14:17], v[218:221]
	v_mfma_f32_16x16x32_bf16 v[78:81], v[170:173], v[186:189], v[66:69]
	v_mfma_f32_16x16x32_bf16 v[66:69], v[174:177], v[6:9], v[222:225]
	v_mfma_f32_16x16x32_bf16 v[46:49], v[202:205], v[6:9], v[46:49]
	v_mfma_f32_16x16x32_bf16 v[6:9], v[214:217], v[6:9], v[38:41]
	v_mfma_f32_16x16x32_bf16 v[106:109], v[190:193], v[10:13], v[66:69]
	v_mfma_f32_16x16x32_bf16 v[66:69], v[174:177], v[14:17], v[226:229]
	v_mfma_f32_16x16x32_bf16 v[42:45], v[202:205], v[14:17], v[42:45]
	v_mfma_f32_16x16x32_bf16 v[98:101], v[238:241], v[10:13], v[6:9]
	v_mfma_f32_16x16x32_bf16 v[6:9], v[214:217], v[14:17], v[34:37]
	v_mfma_f32_16x16x32_bf16 v[74:77], v[190:193], v[186:189], v[66:69]
	v_mfma_f32_16x16x32_bf16 v[102:105], v[206:209], v[10:13], v[46:49]
	v_mfma_f32_16x16x32_bf16 v[70:73], v[206:209], v[186:189], v[42:45]
	v_mfma_f32_16x16x32_bf16 v[66:69], v[238:241], v[186:189], v[6:9]
	s_setprio 0
	s_setprio 1
	v_mfma_f32_16x16x32_bf16 v[6:9], v[166:169], v[198:201], v[130:133]
	v_mfma_f32_16x16x32_bf16 v[46:49], v[170:173], v[210:213], v[6:9]
	v_mfma_f32_16x16x32_bf16 v[6:9], v[166:169], v[230:233], v[134:137]
	v_mfma_f32_16x16x32_bf16 v[14:17], v[170:173], v[234:237], v[6:9]
	v_mfma_f32_16x16x32_bf16 v[6:9], v[174:177], v[198:201], v[138:141]
	v_mfma_f32_16x16x32_bf16 v[42:45], v[190:193], v[210:213], v[6:9]
	v_mfma_f32_16x16x32_bf16 v[6:9], v[174:177], v[230:233], v[142:145]
	v_mfma_f32_16x16x32_bf16 v[10:13], v[190:193], v[234:237], v[6:9]
	v_mfma_f32_16x16x32_bf16 v[6:9], v[202:205], v[198:201], v[150:153]
	v_mfma_f32_16x16x32_bf16 v[38:41], v[206:209], v[210:213], v[6:9]
	v_mfma_f32_16x16x32_bf16 v[6:9], v[202:205], v[230:233], v[178:181]
	v_mfma_f32_16x16x32_bf16 v[34:37], v[214:217], v[198:201], v[182:185]
	v_mfma_f32_16x16x32_bf16 v[2:5], v[214:217], v[230:233], v[2:5]
	v_mfma_f32_16x16x32_bf16 v[6:9], v[206:209], v[234:237], v[6:9]
	v_mfma_f32_16x16x32_bf16 v[34:37], v[238:241], v[210:213], v[34:37]
	v_mfma_f32_16x16x32_bf16 v[2:5], v[238:241], v[234:237], v[2:5]
	s_setprio 0
	s_barrier
	s_and_saveexec_b64 s[46:47], s[6:7]
	s_cbranch_execz .LBB0_318
	s_barrier

.LBB0_359:
	ds_read_b128 v[156:159], v145
	ds_read_b128 v[160:163], v145 offset:1024
	ds_read_b128 v[164:167], v145 offset:2048
	ds_read_b128 v[168:171], v145 offset:3072
	v_lshl_add_u64 v[220:221], v[138:139], 0, s[40:41]
	s_mov_b32 m0, s63
	v_lshl_add_u64 v[204:205], v[220:221], 0, s[20:21]
	v_lshl_add_u64 v[222:223], v[140:141], 0, s[40:41]
	ds_read_b128 v[172:175], v146
	ds_read_b128 v[176:179], v146 offset:1024
	ds_read_b128 v[180:183], v147
	ds_read_b128 v[184:187], v147 offset:1024
	ds_read_b128 v[188:191], v148
	ds_read_b128 v[192:195], v148 offset:1024
	ds_read_b128 v[196:199], v149
	ds_read_b128 v[200:203], v149 offset:1024
	global_load_lds_dwordx4 v[204:205], off
	v_lshl_add_u64 v[204:205], v[222:223], 0, s[20:21]
	s_mov_b32 m0, s46
	s_nop 0
	global_load_lds_dwordx4 v[204:205], off
	s_waitcnt lgkmcnt(8)
	s_barrier
	s_setprio 1
	s_waitcnt lgkmcnt(7)
	v_mfma_f32_16x16x32_bf16 v[126:129], v[172:175], v[156:159], v[126:129]
	v_mfma_f32_16x16x32_bf16 v[122:125], v[172:175], v[164:167], v[122:125]
	s_waitcnt lgkmcnt(5)
	v_mfma_f32_16x16x32_bf16 v[118:121], v[180:183], v[156:159], v[118:121]
	v_mfma_f32_16x16x32_bf16 v[114:117], v[180:183], v[164:167], v[114:117]
	s_waitcnt lgkmcnt(3)
	v_mfma_f32_16x16x32_bf16 v[110:113], v[188:191], v[156:159], v[110:113]
	v_mfma_f32_16x16x32_bf16 v[106:109], v[188:191], v[164:167], v[106:109]
	s_waitcnt lgkmcnt(1)
	v_mfma_f32_16x16x32_bf16 v[102:105], v[196:199], v[156:159], v[102:105]
	v_mfma_f32_16x16x32_bf16 v[98:101], v[196:199], v[164:167], v[98:101]
	v_mfma_f32_16x16x32_bf16 v[126:129], v[176:179], v[160:163], v[126:129]
	v_mfma_f32_16x16x32_bf16 v[122:125], v[176:179], v[168:171], v[122:125]
	v_mfma_f32_16x16x32_bf16 v[118:121], v[184:187], v[160:163], v[118:121]
	v_mfma_f32_16x16x32_bf16 v[114:117], v[184:187], v[168:171], v[114:117]
	v_mfma_f32_16x16x32_bf16 v[110:113], v[192:195], v[160:163], v[110:113]
	v_mfma_f32_16x16x32_bf16 v[106:109], v[192:195], v[168:171], v[106:109]
	s_waitcnt lgkmcnt(0)
	v_mfma_f32_16x16x32_bf16 v[102:105], v[200:203], v[160:163], v[102:105]
	v_mfma_f32_16x16x32_bf16 v[98:101], v[200:203], v[168:171], v[98:101]
	s_setprio 0
	s_barrier
	v_lshl_add_u64 v[224:225], v[134:135], 0, s[40:41]
	s_mov_b32 m0, s37
	v_lshl_add_u64 v[226:227], v[224:225], 0, s[22:23]
	ds_read_b128 v[204:207], v150
	ds_read_b128 v[208:211], v150 offset:1024
	ds_read_b128 v[212:215], v150 offset:2048
	ds_read_b128 v[216:219], v150 offset:3072
	global_load_lds_dwordx4 v[226:227], off
	v_lshl_add_u64 v[226:227], v[136:137], 0, s[40:41]
	v_lshl_add_u64 v[228:229], v[226:227], 0, s[22:23]
	s_mov_b32 m0, s55
	s_nop 0
	global_load_lds_dwordx4 v[228:229], off
	s_barrier
	s_setprio 1
	s_waitcnt lgkmcnt(3)
	v_mfma_f32_16x16x32_bf16 v[94:97], v[172:175], v[204:207], v[94:97]
	s_waitcnt lgkmcnt(1)
	v_mfma_f32_16x16x32_bf16 v[90:93], v[172:175], v[212:215], v[90:93]
	v_mfma_f32_16x16x32_bf16 v[86:89], v[180:183], v[204:207], v[86:89]
	v_mfma_f32_16x16x32_bf16 v[82:85], v[180:183], v[212:215], v[82:85]
	v_mfma_f32_16x16x32_bf16 v[78:81], v[188:191], v[204:207], v[78:81]
	v_mfma_f32_16x16x32_bf16 v[74:77], v[188:191], v[212:215], v[74:77]
	v_mfma_f32_16x16x32_bf16 v[70:73], v[196:199], v[204:207], v[70:73]
	v_mfma_f32_16x16x32_bf16 v[66:69], v[196:199], v[212:215], v[66:69]
	v_mfma_f32_16x16x32_bf16 v[94:97], v[176:179], v[208:211], v[94:97]
	s_waitcnt lgkmcnt(0)
	v_mfma_f32_16x16x32_bf16 v[90:93], v[176:179], v[216:219], v[90:93]
	v_mfma_f32_16x16x32_bf16 v[86:89], v[184:187], v[208:211], v[86:89]
	v_mfma_f32_16x16x32_bf16 v[82:85], v[184:187], v[216:219], v[82:85]
	v_mfma_f32_16x16x32_bf16 v[78:81], v[192:195], v[208:211], v[78:81]
	v_mfma_f32_16x16x32_bf16 v[74:77], v[192:195], v[216:219], v[74:77]
	v_mfma_f32_16x16x32_bf16 v[70:73], v[200:203], v[208:211], v[70:73]
	v_mfma_f32_16x16x32_bf16 v[66:69], v[200:203], v[216:219], v[66:69]
	s_setprio 0
	s_mov_b32 m0, s35
	v_lshl_add_u64 v[228:229], v[220:221], 0, s[22:23]
	s_barrier
	ds_read_b128 v[172:175], v146 offset:16384
	ds_read_b128 v[176:179], v146 offset:17408
	ds_read_b128 v[180:183], v147 offset:16384
	ds_read_b128 v[184:187], v147 offset:17408
	ds_read_b128 v[188:191], v148 offset:16384
	ds_read_b128 v[192:195], v148 offset:17408
	ds_read_b128 v[196:199], v149 offset:16384
	ds_read_b128 v[200:203], v149 offset:17408
	global_load_lds_dwordx4 v[228:229], off
	v_lshl_add_u64 v[228:229], v[222:223], 0, s[22:23]
	s_mov_b32 m0, s56
	s_nop 0
	global_load_lds_dwordx4 v[228:229], off
	s_barrier
	s_setprio 1
	s_waitcnt lgkmcnt(7)
	v_mfma_f32_16x16x32_bf16 v[62:65], v[172:175], v[156:159], v[62:65]
	v_mfma_f32_16x16x32_bf16 v[58:61], v[172:175], v[164:167], v[58:61]
	s_waitcnt lgkmcnt(5)
	v_mfma_f32_16x16x32_bf16 v[54:57], v[180:183], v[156:159], v[54:57]
	v_mfma_f32_16x16x32_bf16 v[50:53], v[180:183], v[164:167], v[50:53]
	s_waitcnt lgkmcnt(3)
	v_mfma_f32_16x16x32_bf16 v[46:49], v[188:191], v[156:159], v[46:49]
	v_mfma_f32_16x16x32_bf16 v[42:45], v[188:191], v[164:167], v[42:45]
	s_waitcnt lgkmcnt(1)
	v_mfma_f32_16x16x32_bf16 v[38:41], v[196:199], v[156:159], v[38:41]
	v_mfma_f32_16x16x32_bf16 v[34:37], v[196:199], v[164:167], v[34:37]
	v_mfma_f32_16x16x32_bf16 v[62:65], v[176:179], v[160:163], v[62:65]
	v_mfma_f32_16x16x32_bf16 v[58:61], v[176:179], v[168:171], v[58:61]
	v_mfma_f32_16x16x32_bf16 v[54:57], v[184:187], v[160:163], v[54:57]
	v_mfma_f32_16x16x32_bf16 v[50:53], v[184:187], v[168:171], v[50:53]
	v_mfma_f32_16x16x32_bf16 v[46:49], v[192:195], v[160:163], v[46:49]
	v_mfma_f32_16x16x32_bf16 v[42:45], v[192:195], v[168:171], v[42:45]
	s_waitcnt lgkmcnt(0)
	v_mfma_f32_16x16x32_bf16 v[38:41], v[200:203], v[160:163], v[38:41]
	v_mfma_f32_16x16x32_bf16 v[34:37], v[200:203], v[168:171], v[34:37]
	s_setprio 0
	s_barrier
	s_mov_b32 m0, s57
	v_lshl_add_u64 v[156:157], v[224:225], 0, s[26:27]
	global_load_lds_dwordx4 v[156:157], off
	v_lshl_add_u64 v[156:157], v[226:227], 0, s[26:27]
	s_mov_b32 m0, s58
	s_nop 0
	global_load_lds_dwordx4 v[156:157], off
	s_waitcnt vmcnt(6)
	s_barrier
	s_setprio 1
	v_mfma_f32_16x16x32_bf16 v[30:33], v[172:175], v[204:207], v[30:33]
	v_mfma_f32_16x16x32_bf16 v[26:29], v[172:175], v[212:215], v[26:29]
	v_mfma_f32_16x16x32_bf16 v[22:25], v[180:183], v[204:207], v[22:25]
	v_mfma_f32_16x16x32_bf16 v[18:21], v[180:183], v[212:215], v[18:21]
	v_mfma_f32_16x16x32_bf16 v[14:17], v[188:191], v[204:207], v[14:17]
	v_mfma_f32_16x16x32_bf16 v[10:13], v[188:191], v[212:215], v[10:13]
	v_mfma_f32_16x16x32_bf16 v[6:9], v[196:199], v[204:207], v[6:9]
	v_mfma_f32_16x16x32_bf16 v[2:5], v[196:199], v[212:215], v[2:5]
	v_mfma_f32_16x16x32_bf16 v[30:33], v[176:179], v[208:211], v[30:33]
	v_mfma_f32_16x16x32_bf16 v[26:29], v[176:179], v[216:219], v[26:29]
	v_mfma_f32_16x16x32_bf16 v[22:25], v[184:187], v[208:211], v[22:25]
	v_mfma_f32_16x16x32_bf16 v[18:21], v[184:187], v[216:219], v[18:21]
	v_mfma_f32_16x16x32_bf16 v[14:17], v[192:195], v[208:211], v[14:17]
	v_mfma_f32_16x16x32_bf16 v[10:13], v[192:195], v[216:219], v[10:13]
	v_mfma_f32_16x16x32_bf16 v[6:9], v[200:203], v[208:211], v[6:9]
	v_mfma_f32_16x16x32_bf16 v[2:5], v[200:203], v[216:219], v[2:5]
	s_setprio 0
	s_barrier
	ds_read_b128 v[156:159], v151
	ds_read_b128 v[160:163], v151 offset:1024
	ds_read_b128 v[164:167], v151 offset:2048
	ds_read_b128 v[168:171], v151 offset:3072
	s_mov_b32 m0, s59
	v_lshl_add_u64 v[204:205], v[220:221], 0, s[26:27]
	ds_read_b128 v[172:175], v146 offset:32768
	ds_read_b128 v[176:179], v146 offset:33792
	ds_read_b128 v[180:183], v147 offset:32768
	ds_read_b128 v[184:187], v147 offset:33792
	ds_read_b128 v[188:191], v148 offset:32768
	ds_read_b128 v[192:195], v148 offset:33792
	ds_read_b128 v[196:199], v149 offset:32768
	ds_read_b128 v[200:203], v149 offset:33792
	global_load_lds_dwordx4 v[204:205], off
	v_lshl_add_u64 v[204:205], v[222:223], 0, s[26:27]
	s_mov_b32 m0, s60
	s_nop 0
	global_load_lds_dwordx4 v[204:205], off
	s_waitcnt lgkmcnt(8)
	s_barrier
	s_setprio 1
	s_waitcnt lgkmcnt(7)
	v_mfma_f32_16x16x32_bf16 v[126:129], v[172:175], v[156:159], v[126:129]
	v_mfma_f32_16x16x32_bf16 v[122:125], v[172:175], v[164:167], v[122:125]
	s_waitcnt lgkmcnt(5)
	v_mfma_f32_16x16x32_bf16 v[118:121], v[180:183], v[156:159], v[118:121]
	v_mfma_f32_16x16x32_bf16 v[114:117], v[180:183], v[164:167], v[114:117]
	s_waitcnt lgkmcnt(3)
	v_mfma_f32_16x16x32_bf16 v[110:113], v[188:191], v[156:159], v[110:113]
	v_mfma_f32_16x16x32_bf16 v[106:109], v[188:191], v[164:167], v[106:109]
	s_waitcnt lgkmcnt(1)
	v_mfma_f32_16x16x32_bf16 v[102:105], v[196:199], v[156:159], v[102:105]
	v_mfma_f32_16x16x32_bf16 v[98:101], v[196:199], v[164:167], v[98:101]
	v_mfma_f32_16x16x32_bf16 v[126:129], v[176:179], v[160:163], v[126:129]
	v_mfma_f32_16x16x32_bf16 v[122:125], v[176:179], v[168:171], v[122:125]
	v_mfma_f32_16x16x32_bf16 v[118:121], v[184:187], v[160:163], v[118:121]
	v_mfma_f32_16x16x32_bf16 v[114:117], v[184:187], v[168:171], v[114:117]
	v_mfma_f32_16x16x32_bf16 v[110:113], v[192:195], v[160:163], v[110:113]
	v_mfma_f32_16x16x32_bf16 v[106:109], v[192:195], v[168:171], v[106:109]
	s_waitcnt lgkmcnt(0)
	v_mfma_f32_16x16x32_bf16 v[102:105], v[200:203], v[160:163], v[102:105]
	v_mfma_f32_16x16x32_bf16 v[98:101], v[200:203], v[168:171], v[98:101]
	s_setprio 0
	s_barrier
	s_mov_b32 m0, s50
	v_lshl_add_u64 v[228:229], v[224:225], 0, s[28:29]
	ds_read_b128 v[204:207], v152
	ds_read_b128 v[208:211], v152 offset:1024
	ds_read_b128 v[212:215], v152 offset:2048
	ds_read_b128 v[216:219], v152 offset:3072
	global_load_lds_dwordx4 v[228:229], off
	v_lshl_add_u64 v[228:229], v[226:227], 0, s[28:29]
	s_mov_b32 m0, s51
	s_nop 0
	global_load_lds_dwordx4 v[228:229], off
	s_barrier
	s_setprio 1
	s_waitcnt lgkmcnt(3)
	v_mfma_f32_16x16x32_bf16 v[94:97], v[172:175], v[204:207], v[94:97]
	s_waitcnt lgkmcnt(1)
	v_mfma_f32_16x16x32_bf16 v[90:93], v[172:175], v[212:215], v[90:93]
	v_mfma_f32_16x16x32_bf16 v[86:89], v[180:183], v[204:207], v[86:89]
	v_mfma_f32_16x16x32_bf16 v[82:85], v[180:183], v[212:215], v[82:85]
	v_mfma_f32_16x16x32_bf16 v[78:81], v[188:191], v[204:207], v[78:81]
	v_mfma_f32_16x16x32_bf16 v[74:77], v[188:191], v[212:215], v[74:77]
	v_mfma_f32_16x16x32_bf16 v[70:73], v[196:199], v[204:207], v[70:73]
	v_mfma_f32_16x16x32_bf16 v[66:69], v[196:199], v[212:215], v[66:69]
	v_mfma_f32_16x16x32_bf16 v[94:97], v[176:179], v[208:211], v[94:97]
	s_waitcnt lgkmcnt(0)
	v_mfma_f32_16x16x32_bf16 v[90:93], v[176:179], v[216:219], v[90:93]
	v_mfma_f32_16x16x32_bf16 v[86:89], v[184:187], v[208:211], v[86:89]
	v_mfma_f32_16x16x32_bf16 v[82:85], v[184:187], v[216:219], v[82:85]
	v_mfma_f32_16x16x32_bf16 v[78:81], v[192:195], v[208:211], v[78:81]
	v_mfma_f32_16x16x32_bf16 v[74:77], v[192:195], v[216:219], v[74:77]
	v_mfma_f32_16x16x32_bf16 v[70:73], v[200:203], v[208:211], v[70:73]
	v_mfma_f32_16x16x32_bf16 v[66:69], v[200:203], v[216:219], v[66:69]
	s_setprio 0
	s_mov_b32 m0, s61
	v_lshl_add_u64 v[220:221], v[220:221], 0, s[28:29]
	s_barrier
	ds_read_b128 v[172:175], v146 offset:49152
	ds_read_b128 v[176:179], v146 offset:50176
	ds_read_b128 v[180:183], v147 offset:49152
	ds_read_b128 v[184:187], v147 offset:50176
	ds_read_b128 v[188:191], v148 offset:49152
	ds_read_b128 v[192:195], v148 offset:50176
	ds_read_b128 v[196:199], v149 offset:49152
	ds_read_b128 v[200:203], v149 offset:50176
	global_load_lds_dwordx4 v[220:221], off
	v_lshl_add_u64 v[220:221], v[222:223], 0, s[28:29]
	s_mov_b32 m0, s62
	s_nop 0
	global_load_lds_dwordx4 v[220:221], off
	s_barrier
	s_setprio 1
	s_waitcnt lgkmcnt(7)
	v_mfma_f32_16x16x32_bf16 v[62:65], v[172:175], v[156:159], v[62:65]
	v_mfma_f32_16x16x32_bf16 v[58:61], v[172:175], v[164:167], v[58:61]
	s_waitcnt lgkmcnt(5)
	v_mfma_f32_16x16x32_bf16 v[54:57], v[180:183], v[156:159], v[54:57]
	v_mfma_f32_16x16x32_bf16 v[50:53], v[180:183], v[164:167], v[50:53]
	s_waitcnt lgkmcnt(3)
	v_mfma_f32_16x16x32_bf16 v[46:49], v[188:191], v[156:159], v[46:49]
	v_mfma_f32_16x16x32_bf16 v[42:45], v[188:191], v[164:167], v[42:45]
	s_waitcnt lgkmcnt(1)
	v_mfma_f32_16x16x32_bf16 v[38:41], v[196:199], v[156:159], v[38:41]
	v_mfma_f32_16x16x32_bf16 v[34:37], v[196:199], v[164:167], v[34:37]
	v_mfma_f32_16x16x32_bf16 v[62:65], v[176:179], v[160:163], v[62:65]
	v_mfma_f32_16x16x32_bf16 v[58:61], v[176:179], v[168:171], v[58:61]
	v_mfma_f32_16x16x32_bf16 v[54:57], v[184:187], v[160:163], v[54:57]
	v_mfma_f32_16x16x32_bf16 v[50:53], v[184:187], v[168:171], v[50:53]
	v_mfma_f32_16x16x32_bf16 v[46:49], v[192:195], v[160:163], v[46:49]
	v_mfma_f32_16x16x32_bf16 v[42:45], v[192:195], v[168:171], v[42:45]
	s_waitcnt lgkmcnt(0)
	v_mfma_f32_16x16x32_bf16 v[38:41], v[200:203], v[160:163], v[38:41]
	v_mfma_f32_16x16x32_bf16 v[34:37], v[200:203], v[168:171], v[34:37]
	s_setprio 0
	s_barrier
	s_mov_b32 m0, s48
	v_lshl_add_u64 v[156:157], v[224:225], 0, s[30:31]
	global_load_lds_dwordx4 v[156:157], off
	v_lshl_add_u64 v[156:157], v[226:227], 0, s[30:31]
	s_mov_b32 m0, s49
	s_nop 0
	global_load_lds_dwordx4 v[156:157], off
	s_waitcnt vmcnt(6)
	s_barrier
	s_setprio 1
	v_mfma_f32_16x16x32_bf16 v[30:33], v[172:175], v[204:207], v[30:33]
	v_mfma_f32_16x16x32_bf16 v[26:29], v[172:175], v[212:215], v[26:29]
	v_mfma_f32_16x16x32_bf16 v[22:25], v[180:183], v[204:207], v[22:25]
	v_mfma_f32_16x16x32_bf16 v[18:21], v[180:183], v[212:215], v[18:21]
	v_mfma_f32_16x16x32_bf16 v[14:17], v[188:191], v[204:207], v[14:17]
	v_mfma_f32_16x16x32_bf16 v[10:13], v[188:191], v[212:215], v[10:13]
	v_mfma_f32_16x16x32_bf16 v[6:9], v[196:199], v[204:207], v[6:9]
	v_mfma_f32_16x16x32_bf16 v[2:5], v[196:199], v[212:215], v[2:5]
	v_mfma_f32_16x16x32_bf16 v[30:33], v[176:179], v[208:211], v[30:33]
	v_mfma_f32_16x16x32_bf16 v[26:29], v[176:179], v[216:219], v[26:29]
	v_mfma_f32_16x16x32_bf16 v[22:25], v[184:187], v[208:211], v[22:25]
	v_mfma_f32_16x16x32_bf16 v[18:21], v[184:187], v[216:219], v[18:21]
	v_mfma_f32_16x16x32_bf16 v[14:17], v[192:195], v[208:211], v[14:17]
	v_mfma_f32_16x16x32_bf16 v[10:13], v[192:195], v[216:219], v[10:13]
	v_mfma_f32_16x16x32_bf16 v[6:9], v[200:203], v[208:211], v[6:9]
	v_mfma_f32_16x16x32_bf16 v[2:5], v[200:203], v[216:219], v[2:5]
	s_setprio 0
	s_add_i32 s47, s47, 2
	s_add_u32 s40, s40, 0x100
	s_addc_u32 s41, s41, 0
	s_cmp_lt_u32 s47, 12
	s_barrier
	s_cbranch_scc1 .LBB0_359
	s_add_u32 s0, s38, 0x40780
	s_addc_u32 s1, s39, 0
	s_mov_b32 m0, s63
	v_lshl_add_u64 v[196:197], v[130:131], 1, s[0:1]
	ds_read_b128 v[134:137], v145
	ds_read_b128 v[138:141], v145 offset:1024
	ds_read_b128 v[156:159], v145 offset:2048
	ds_read_b128 v[160:163], v145 offset:3072
	ds_read_b128 v[164:167], v146
	ds_read_b128 v[168:171], v146 offset:1024
	ds_read_b128 v[172:175], v147
	ds_read_b128 v[176:179], v147 offset:1024
	ds_read_b128 v[180:183], v148
	ds_read_b128 v[184:187], v148 offset:1024
	ds_read_b128 v[188:191], v149
	ds_read_b128 v[192:195], v149 offset:1024
	global_load_lds_dwordx4 v[196:197], off
	v_lshl_add_u64 v[132:133], v[132:133], 1, s[0:1]
	s_mov_b32 m0, s46
	s_nop 0
	global_load_lds_dwordx4 v[132:133], off
	s_barrier
	s_waitcnt lgkmcnt(0)
	s_setprio 1
	s_waitcnt lgkmcnt(0)
	v_mfma_f32_16x16x32_bf16 v[126:129], v[164:167], v[134:137], v[126:129]
	v_mfma_f32_16x16x32_bf16 v[118:121], v[172:175], v[134:137], v[118:121]
	v_mfma_f32_16x16x32_bf16 v[110:113], v[180:183], v[134:137], v[110:113]
	v_mfma_f32_16x16x32_bf16 v[102:105], v[188:191], v[134:137], v[102:105]
	v_mfma_f32_16x16x32_bf16 v[126:129], v[168:171], v[138:141], v[126:129]
	v_mfma_f32_16x16x32_bf16 v[122:125], v[164:167], v[156:159], v[122:125]
	v_mfma_f32_16x16x32_bf16 v[118:121], v[176:179], v[138:141], v[118:121]
	v_mfma_f32_16x16x32_bf16 v[114:117], v[172:175], v[156:159], v[114:117]
	v_mfma_f32_16x16x32_bf16 v[110:113], v[184:187], v[138:141], v[110:113]
	v_mfma_f32_16x16x32_bf16 v[106:109], v[180:183], v[156:159], v[106:109]
	v_mfma_f32_16x16x32_bf16 v[102:105], v[192:195], v[138:141], v[102:105]
	v_mfma_f32_16x16x32_bf16 v[98:101], v[188:191], v[156:159], v[98:101]
	v_mfma_f32_16x16x32_bf16 v[196:199], v[168:171], v[160:163], v[122:125]
	v_mfma_f32_16x16x32_bf16 v[200:203], v[176:179], v[160:163], v[114:117]
	v_mfma_f32_16x16x32_bf16 v[204:207], v[184:187], v[160:163], v[106:109]
	v_mfma_f32_16x16x32_bf16 v[208:211], v[192:195], v[160:163], v[98:101]
	s_setprio 0
	s_barrier
	s_nop 1
	ds_read_b128 v[98:101], v150
	ds_read_b128 v[106:109], v150 offset:1024
	ds_read_b128 v[114:117], v150 offset:2048
	ds_read_b128 v[122:125], v150 offset:3072
	s_barrier
	s_waitcnt lgkmcnt(0)
	s_setprio 1
	s_waitcnt lgkmcnt(0)
	v_mfma_f32_16x16x32_bf16 v[94:97], v[164:167], v[98:101], v[94:97]
	v_mfma_f32_16x16x32_bf16 v[86:89], v[172:175], v[98:101], v[86:89]
	v_mfma_f32_16x16x32_bf16 v[78:81], v[180:183], v[98:101], v[78:81]
	v_mfma_f32_16x16x32_bf16 v[70:73], v[188:191], v[98:101], v[70:73]
	v_mfma_f32_16x16x32_bf16 v[94:97], v[168:171], v[106:109], v[94:97]
	v_mfma_f32_16x16x32_bf16 v[90:93], v[164:167], v[114:117], v[90:93]
	v_mfma_f32_16x16x32_bf16 v[86:89], v[176:179], v[106:109], v[86:89]
	v_mfma_f32_16x16x32_bf16 v[82:85], v[172:175], v[114:117], v[82:85]
	v_mfma_f32_16x16x32_bf16 v[78:81], v[184:187], v[106:109], v[78:81]
	v_mfma_f32_16x16x32_bf16 v[74:77], v[180:183], v[114:117], v[74:77]
	v_mfma_f32_16x16x32_bf16 v[70:73], v[192:195], v[106:109], v[70:73]
	v_mfma_f32_16x16x32_bf16 v[66:69], v[188:191], v[114:117], v[66:69]
	v_mfma_f32_16x16x32_bf16 v[164:167], v[168:171], v[122:125], v[90:93]
	v_mfma_f32_16x16x32_bf16 v[168:171], v[176:179], v[122:125], v[82:85]
	v_mfma_f32_16x16x32_bf16 v[172:175], v[184:187], v[122:125], v[74:77]
	v_mfma_f32_16x16x32_bf16 v[176:179], v[192:195], v[122:125], v[66:69]
	s_setprio 0
	s_barrier
	s_nop 1
	ds_read_b128 v[66:69], v146 offset:16384
	ds_read_b128 v[74:77], v146 offset:17408
	ds_read_b128 v[82:85], v147 offset:16384
	ds_read_b128 v[90:93], v147 offset:17408
	ds_read_b128 v[180:183], v148 offset:16384
	ds_read_b128 v[184:187], v148 offset:17408
	ds_read_b128 v[188:191], v149 offset:16384
	ds_read_b128 v[192:195], v149 offset:17408
	s_waitcnt vmcnt(4)
	s_barrier
	s_waitcnt lgkmcnt(0)
	s_setprio 1
	s_waitcnt lgkmcnt(0)
	v_mfma_f32_16x16x32_bf16 v[62:65], v[66:69], v[134:137], v[62:65]
	v_mfma_f32_16x16x32_bf16 v[54:57], v[82:85], v[134:137], v[54:57]
	v_mfma_f32_16x16x32_bf16 v[46:49], v[180:183], v[134:137], v[46:49]
	v_mfma_f32_16x16x32_bf16 v[38:41], v[188:191], v[134:137], v[38:41]
	v_mfma_f32_16x16x32_bf16 v[62:65], v[74:77], v[138:141], v[62:65]
	v_mfma_f32_16x16x32_bf16 v[58:61], v[66:69], v[156:159], v[58:61]
	v_mfma_f32_16x16x32_bf16 v[54:57], v[90:93], v[138:141], v[54:57]
	v_mfma_f32_16x16x32_bf16 v[50:53], v[82:85], v[156:159], v[50:53]
	v_mfma_f32_16x16x32_bf16 v[46:49], v[184:187], v[138:141], v[46:49]
	v_mfma_f32_16x16x32_bf16 v[42:45], v[180:183], v[156:159], v[42:45]
	v_mfma_f32_16x16x32_bf16 v[38:41], v[192:195], v[138:141], v[38:41]
	v_mfma_f32_16x16x32_bf16 v[34:37], v[188:191], v[156:159], v[34:37]
	v_mfma_f32_16x16x32_bf16 v[212:215], v[74:77], v[160:163], v[58:61]
	v_mfma_f32_16x16x32_bf16 v[216:219], v[90:93], v[160:163], v[50:53]
	v_mfma_f32_16x16x32_bf16 v[220:223], v[184:187], v[160:163], v[42:45]
	v_mfma_f32_16x16x32_bf16 v[132:135], v[192:195], v[160:163], v[34:37]
	s_setprio 0
	s_setprio 1
	v_mfma_f32_16x16x32_bf16 v[30:33], v[66:69], v[98:101], v[30:33]
	v_mfma_f32_16x16x32_bf16 v[22:25], v[82:85], v[98:101], v[22:25]
	v_mfma_f32_16x16x32_bf16 v[14:17], v[180:183], v[98:101], v[14:17]
	v_mfma_f32_16x16x32_bf16 v[6:9], v[188:191], v[98:101], v[6:9]
	v_mfma_f32_16x16x32_bf16 v[30:33], v[74:77], v[106:109], v[30:33]
	v_mfma_f32_16x16x32_bf16 v[26:29], v[66:69], v[114:117], v[26:29]
	v_mfma_f32_16x16x32_bf16 v[22:25], v[90:93], v[106:109], v[22:25]
	v_mfma_f32_16x16x32_bf16 v[18:21], v[82:85], v[114:117], v[18:21]
	v_mfma_f32_16x16x32_bf16 v[14:17], v[184:187], v[106:109], v[14:17]
	v_mfma_f32_16x16x32_bf16 v[10:13], v[180:183], v[114:117], v[10:13]
	v_mfma_f32_16x16x32_bf16 v[6:9], v[192:195], v[106:109], v[6:9]
	v_mfma_f32_16x16x32_bf16 v[2:5], v[188:191], v[114:117], v[2:5]
	v_mfma_f32_16x16x32_bf16 v[136:139], v[74:77], v[122:125], v[26:29]
	v_mfma_f32_16x16x32_bf16 v[156:159], v[90:93], v[122:125], v[18:21]
	v_mfma_f32_16x16x32_bf16 v[160:163], v[184:187], v[122:125], v[10:13]
	v_mfma_f32_16x16x32_bf16 v[180:183], v[192:195], v[122:125], v[2:5]
	s_setprio 0
	s_barrier
	ds_read_b128 v[184:187], v151
	ds_read_b128 v[188:191], v151 offset:1024
	ds_read_b128 v[192:195], v151 offset:2048
	ds_read_b128 v[224:227], v151 offset:3072
	ds_read_b128 v[2:5], v146 offset:32768
	ds_read_b128 v[10:13], v146 offset:33792
	ds_read_b128 v[18:21], v147 offset:32768
	ds_read_b128 v[34:37], v147 offset:33792
	ds_read_b128 v[228:231], v148 offset:32768
	ds_read_b128 v[232:235], v148 offset:33792
	ds_read_b128 v[236:239], v149 offset:32768
	ds_read_b128 v[240:243], v149 offset:33792
	s_waitcnt vmcnt(2)
	s_barrier
	s_waitcnt lgkmcnt(0)
	s_setprio 1
	s_waitcnt lgkmcnt(0)
	v_mfma_f32_16x16x32_bf16 v[26:29], v[2:5], v[184:187], v[126:129]
	v_mfma_f32_16x16x32_bf16 v[122:125], v[10:13], v[188:191], v[26:29]
	v_mfma_f32_16x16x32_bf16 v[26:29], v[2:5], v[192:195], v[196:199]
	v_mfma_f32_16x16x32_bf16 v[90:93], v[10:13], v[224:227], v[26:29]
	v_mfma_f32_16x16x32_bf16 v[26:29], v[18:21], v[184:187], v[118:121]
	v_mfma_f32_16x16x32_bf16 v[114:117], v[34:37], v[188:191], v[26:29]
	v_mfma_f32_16x16x32_bf16 v[26:29], v[18:21], v[192:195], v[200:203]
	v_mfma_f32_16x16x32_bf16 v[82:85], v[34:37], v[224:227], v[26:29]
	v_mfma_f32_16x16x32_bf16 v[26:29], v[228:231], v[184:187], v[110:113]
	v_mfma_f32_16x16x32_bf16 v[106:109], v[232:235], v[188:191], v[26:29]
	v_mfma_f32_16x16x32_bf16 v[26:29], v[228:231], v[192:195], v[204:207]
	v_mfma_f32_16x16x32_bf16 v[74:77], v[232:235], v[224:227], v[26:29]
	v_mfma_f32_16x16x32_bf16 v[26:29], v[236:239], v[184:187], v[102:105]
	v_mfma_f32_16x16x32_bf16 v[98:101], v[240:243], v[188:191], v[26:29]
	v_mfma_f32_16x16x32_bf16 v[26:29], v[236:239], v[192:195], v[208:211]
	v_mfma_f32_16x16x32_bf16 v[66:69], v[240:243], v[224:227], v[26:29]
	s_setprio 0
	s_barrier
	ds_read_b128 v[196:199], v152
	ds_read_b128 v[200:203], v152 offset:1024
	ds_read_b128 v[204:207], v152 offset:2048
	ds_read_b128 v[208:211], v152 offset:3072
	s_waitcnt vmcnt(0)
	s_barrier
	s_waitcnt lgkmcnt(0)
	s_setprio 1
	s_waitcnt lgkmcnt(0)
	v_mfma_f32_16x16x32_bf16 v[26:29], v[2:5], v[196:199], v[94:97]
	v_mfma_f32_16x16x32_bf16 v[2:5], v[2:5], v[204:207], v[164:167]
	v_mfma_f32_16x16x32_bf16 v[58:61], v[10:13], v[200:203], v[26:29]
	v_mfma_f32_16x16x32_bf16 v[26:29], v[10:13], v[208:211], v[2:5]
	v_mfma_f32_16x16x32_bf16 v[2:5], v[18:21], v[196:199], v[86:89]
	v_mfma_f32_16x16x32_bf16 v[50:53], v[34:37], v[200:203], v[2:5]
	v_mfma_f32_16x16x32_bf16 v[2:5], v[18:21], v[204:207], v[168:171]
	v_mfma_f32_16x16x32_bf16 v[18:21], v[34:37], v[208:211], v[2:5]
	v_mfma_f32_16x16x32_bf16 v[2:5], v[228:231], v[196:199], v[78:81]
	v_mfma_f32_16x16x32_bf16 v[42:45], v[232:235], v[200:203], v[2:5]
	v_mfma_f32_16x16x32_bf16 v[2:5], v[228:231], v[204:207], v[172:175]
	v_mfma_f32_16x16x32_bf16 v[10:13], v[232:235], v[208:211], v[2:5]
	v_mfma_f32_16x16x32_bf16 v[2:5], v[236:239], v[196:199], v[70:73]
	v_mfma_f32_16x16x32_bf16 v[34:37], v[240:243], v[200:203], v[2:5]
	v_mfma_f32_16x16x32_bf16 v[2:5], v[236:239], v[204:207], v[176:179]
	v_mfma_f32_16x16x32_bf16 v[2:5], v[240:243], v[208:211], v[2:5]
	s_setprio 0
	s_barrier
	ds_read_b128 v[164:167], v146 offset:49152
	ds_read_b128 v[168:171], v146 offset:50176
	ds_read_b128 v[172:175], v147 offset:49152
	ds_read_b128 v[176:179], v147 offset:50176
	ds_read_b128 v[228:231], v148 offset:49152
	ds_read_b128 v[232:235], v148 offset:50176
	ds_read_b128 v[236:239], v149 offset:49152
	ds_read_b128 v[240:243], v149 offset:50176
	s_barrier
	s_waitcnt lgkmcnt(0)
	s_setprio 1
	s_waitcnt lgkmcnt(0)
	v_mfma_f32_16x16x32_bf16 v[62:65], v[164:167], v[184:187], v[62:65]
	v_mfma_f32_16x16x32_bf16 v[54:57], v[172:175], v[184:187], v[54:57]
	v_mfma_f32_16x16x32_bf16 v[46:49], v[228:231], v[184:187], v[46:49]
	v_mfma_f32_16x16x32_bf16 v[38:41], v[236:239], v[184:187], v[38:41]
	v_mfma_f32_16x16x32_bf16 v[126:129], v[168:171], v[188:191], v[62:65]
	v_mfma_f32_16x16x32_bf16 v[62:65], v[164:167], v[192:195], v[212:215]
	v_mfma_f32_16x16x32_bf16 v[118:121], v[176:179], v[188:191], v[54:57]
	v_mfma_f32_16x16x32_bf16 v[54:57], v[172:175], v[192:195], v[216:219]
	v_mfma_f32_16x16x32_bf16 v[110:113], v[232:235], v[188:191], v[46:49]
	v_mfma_f32_16x16x32_bf16 v[46:49], v[228:231], v[192:195], v[220:223]
	v_mfma_f32_16x16x32_bf16 v[102:105], v[240:243], v[188:191], v[38:41]
	v_mfma_f32_16x16x32_bf16 v[38:41], v[236:239], v[192:195], v[132:135]
	v_mfma_f32_16x16x32_bf16 v[94:97], v[168:171], v[224:227], v[62:65]
	v_mfma_f32_16x16x32_bf16 v[86:89], v[176:179], v[224:227], v[54:57]
	v_mfma_f32_16x16x32_bf16 v[78:81], v[232:235], v[224:227], v[46:49]
	v_mfma_f32_16x16x32_bf16 v[70:73], v[240:243], v[224:227], v[38:41]
	s_setprio 0
	s_setprio 1
	v_mfma_f32_16x16x32_bf16 v[30:33], v[164:167], v[196:199], v[30:33]
	v_mfma_f32_16x16x32_bf16 v[22:25], v[172:175], v[196:199], v[22:25]
	v_mfma_f32_16x16x32_bf16 v[14:17], v[228:231], v[196:199], v[14:17]
	v_mfma_f32_16x16x32_bf16 v[6:9], v[236:239], v[196:199], v[6:9]
	v_mfma_f32_16x16x32_bf16 v[62:65], v[168:171], v[200:203], v[30:33]
	v_mfma_f32_16x16x32_bf16 v[30:33], v[164:167], v[204:207], v[136:139]
	v_mfma_f32_16x16x32_bf16 v[54:57], v[176:179], v[200:203], v[22:25]
	v_mfma_f32_16x16x32_bf16 v[22:25], v[172:175], v[204:207], v[156:159]
	v_mfma_f32_16x16x32_bf16 v[46:49], v[232:235], v[200:203], v[14:17]
	v_mfma_f32_16x16x32_bf16 v[14:17], v[228:231], v[204:207], v[160:163]
	v_mfma_f32_16x16x32_bf16 v[38:41], v[240:243], v[200:203], v[6:9]
	v_mfma_f32_16x16x32_bf16 v[6:9], v[236:239], v[204:207], v[180:183]
	v_mfma_f32_16x16x32_bf16 v[30:33], v[168:171], v[208:211], v[30:33]
	v_mfma_f32_16x16x32_bf16 v[22:25], v[176:179], v[208:211], v[22:25]
	v_mfma_f32_16x16x32_bf16 v[14:17], v[232:235], v[208:211], v[14:17]
	v_mfma_f32_16x16x32_bf16 v[6:9], v[240:243], v[208:211], v[6:9]
	s_setprio 0
	s_barrier
	s_and_saveexec_b64 s[38:39], s[4:5]
	s_cbranch_execz .LBB0_362
	s_barrier

.LBB0_398:
	ds_read_b128 v[152:155], v143
	ds_read_b128 v[156:159], v143 offset:1024
	ds_read_b128 v[160:163], v143 offset:2048
	ds_read_b128 v[164:167], v143 offset:3072
	v_lshl_add_u64 v[216:217], v[138:139], 0, s[26:27]
	s_mov_b32 m0, s50
	v_lshl_add_u64 v[200:201], v[216:217], 0, s[6:7]
	v_lshl_add_u64 v[218:219], v[140:141], 0, s[26:27]
	ds_read_b128 v[168:171], v144
	ds_read_b128 v[172:175], v144 offset:1024
	ds_read_b128 v[176:179], v145
	ds_read_b128 v[180:183], v145 offset:1024
	ds_read_b128 v[184:187], v146
	ds_read_b128 v[188:191], v146 offset:1024
	ds_read_b128 v[192:195], v147
	ds_read_b128 v[196:199], v147 offset:1024
	global_load_lds_dwordx4 v[200:201], off
	v_lshl_add_u64 v[200:201], v[218:219], 0, s[6:7]
	s_mov_b32 m0, s48
	s_nop 0
	global_load_lds_dwordx4 v[200:201], off
	s_waitcnt lgkmcnt(8)
	s_barrier
	s_setprio 1
	s_waitcnt lgkmcnt(7)
	v_mfma_f32_16x16x32_bf16 v[126:129], v[168:171], v[152:155], v[126:129]
	v_mfma_f32_16x16x32_bf16 v[122:125], v[168:171], v[160:163], v[122:125]
	s_waitcnt lgkmcnt(5)
	v_mfma_f32_16x16x32_bf16 v[118:121], v[176:179], v[152:155], v[118:121]
	v_mfma_f32_16x16x32_bf16 v[114:117], v[176:179], v[160:163], v[114:117]
	s_waitcnt lgkmcnt(3)
	v_mfma_f32_16x16x32_bf16 v[110:113], v[184:187], v[152:155], v[110:113]
	v_mfma_f32_16x16x32_bf16 v[106:109], v[184:187], v[160:163], v[106:109]
	s_waitcnt lgkmcnt(1)
	v_mfma_f32_16x16x32_bf16 v[102:105], v[192:195], v[152:155], v[102:105]
	v_mfma_f32_16x16x32_bf16 v[98:101], v[192:195], v[160:163], v[98:101]
	v_mfma_f32_16x16x32_bf16 v[126:129], v[172:175], v[156:159], v[126:129]
	v_mfma_f32_16x16x32_bf16 v[122:125], v[172:175], v[164:167], v[122:125]
	v_mfma_f32_16x16x32_bf16 v[118:121], v[180:183], v[156:159], v[118:121]
	v_mfma_f32_16x16x32_bf16 v[114:117], v[180:183], v[164:167], v[114:117]
	v_mfma_f32_16x16x32_bf16 v[110:113], v[188:191], v[156:159], v[110:113]
	v_mfma_f32_16x16x32_bf16 v[106:109], v[188:191], v[164:167], v[106:109]
	s_waitcnt lgkmcnt(0)
	v_mfma_f32_16x16x32_bf16 v[102:105], v[196:199], v[156:159], v[102:105]
	v_mfma_f32_16x16x32_bf16 v[98:101], v[196:199], v[164:167], v[98:101]
	s_setprio 0
	s_barrier
	v_lshl_add_u64 v[220:221], v[134:135], 0, s[26:27]
	s_mov_b32 m0, s35
	v_lshl_add_u64 v[222:223], v[220:221], 0, s[8:9]
	ds_read_b128 v[200:203], v148
	ds_read_b128 v[204:207], v148 offset:1024
	ds_read_b128 v[208:211], v148 offset:2048
	ds_read_b128 v[212:215], v148 offset:3072
	global_load_lds_dwordx4 v[222:223], off
	v_lshl_add_u64 v[222:223], v[136:137], 0, s[26:27]
	v_lshl_add_u64 v[224:225], v[222:223], 0, s[8:9]
	s_mov_b32 m0, s36
	s_nop 0
	global_load_lds_dwordx4 v[224:225], off
	s_barrier
	s_setprio 1
	s_waitcnt lgkmcnt(3)
	v_mfma_f32_16x16x32_bf16 v[94:97], v[168:171], v[200:203], v[94:97]
	s_waitcnt lgkmcnt(1)
	v_mfma_f32_16x16x32_bf16 v[90:93], v[168:171], v[208:211], v[90:93]
	v_mfma_f32_16x16x32_bf16 v[86:89], v[176:179], v[200:203], v[86:89]
	v_mfma_f32_16x16x32_bf16 v[82:85], v[176:179], v[208:211], v[82:85]
	v_mfma_f32_16x16x32_bf16 v[78:81], v[184:187], v[200:203], v[78:81]
	v_mfma_f32_16x16x32_bf16 v[74:77], v[184:187], v[208:211], v[74:77]
	v_mfma_f32_16x16x32_bf16 v[70:73], v[192:195], v[200:203], v[70:73]
	v_mfma_f32_16x16x32_bf16 v[66:69], v[192:195], v[208:211], v[66:69]
	v_mfma_f32_16x16x32_bf16 v[94:97], v[172:175], v[204:207], v[94:97]
	s_waitcnt lgkmcnt(0)
	v_mfma_f32_16x16x32_bf16 v[90:93], v[172:175], v[212:215], v[90:93]
	v_mfma_f32_16x16x32_bf16 v[86:89], v[180:183], v[204:207], v[86:89]
	v_mfma_f32_16x16x32_bf16 v[82:85], v[180:183], v[212:215], v[82:85]
	v_mfma_f32_16x16x32_bf16 v[78:81], v[188:191], v[204:207], v[78:81]
	v_mfma_f32_16x16x32_bf16 v[74:77], v[188:191], v[212:215], v[74:77]
	v_mfma_f32_16x16x32_bf16 v[70:73], v[196:199], v[204:207], v[70:73]
	v_mfma_f32_16x16x32_bf16 v[66:69], v[196:199], v[212:215], v[66:69]
	s_setprio 0
	s_mov_b32 m0, s34
	v_lshl_add_u64 v[224:225], v[216:217], 0, s[8:9]
	s_barrier
	ds_read_b128 v[168:171], v144 offset:16384
	ds_read_b128 v[172:175], v144 offset:17408
	ds_read_b128 v[176:179], v145 offset:16384
	ds_read_b128 v[180:183], v145 offset:17408
	ds_read_b128 v[184:187], v146 offset:16384
	ds_read_b128 v[188:191], v146 offset:17408
	ds_read_b128 v[192:195], v147 offset:16384
	ds_read_b128 v[196:199], v147 offset:17408
	global_load_lds_dwordx4 v[224:225], off
	v_lshl_add_u64 v[224:225], v[218:219], 0, s[8:9]
	s_mov_b32 m0, s37
	s_nop 0
	global_load_lds_dwordx4 v[224:225], off
	s_barrier
	s_setprio 1
	s_waitcnt lgkmcnt(7)
	v_mfma_f32_16x16x32_bf16 v[62:65], v[168:171], v[152:155], v[62:65]
	v_mfma_f32_16x16x32_bf16 v[58:61], v[168:171], v[160:163], v[58:61]
	s_waitcnt lgkmcnt(5)
	v_mfma_f32_16x16x32_bf16 v[54:57], v[176:179], v[152:155], v[54:57]
	v_mfma_f32_16x16x32_bf16 v[50:53], v[176:179], v[160:163], v[50:53]
	s_waitcnt lgkmcnt(3)
	v_mfma_f32_16x16x32_bf16 v[46:49], v[184:187], v[152:155], v[46:49]
	v_mfma_f32_16x16x32_bf16 v[42:45], v[184:187], v[160:163], v[42:45]
	s_waitcnt lgkmcnt(1)
	v_mfma_f32_16x16x32_bf16 v[38:41], v[192:195], v[152:155], v[38:41]
	v_mfma_f32_16x16x32_bf16 v[34:37], v[192:195], v[160:163], v[34:37]
	v_mfma_f32_16x16x32_bf16 v[62:65], v[172:175], v[156:159], v[62:65]
	v_mfma_f32_16x16x32_bf16 v[58:61], v[172:175], v[164:167], v[58:61]
	v_mfma_f32_16x16x32_bf16 v[54:57], v[180:183], v[156:159], v[54:57]
	v_mfma_f32_16x16x32_bf16 v[50:53], v[180:183], v[164:167], v[50:53]
	v_mfma_f32_16x16x32_bf16 v[46:49], v[188:191], v[156:159], v[46:49]
	v_mfma_f32_16x16x32_bf16 v[42:45], v[188:191], v[164:167], v[42:45]
	s_waitcnt lgkmcnt(0)
	v_mfma_f32_16x16x32_bf16 v[38:41], v[196:199], v[156:159], v[38:41]
	v_mfma_f32_16x16x32_bf16 v[34:37], v[196:199], v[164:167], v[34:37]
	s_setprio 0
	s_barrier
	s_mov_b32 m0, s38
	v_lshl_add_u64 v[152:153], v[220:221], 0, s[16:17]
	global_load_lds_dwordx4 v[152:153], off
	v_lshl_add_u64 v[152:153], v[222:223], 0, s[16:17]
	s_mov_b32 m0, s39
	s_nop 0
	global_load_lds_dwordx4 v[152:153], off
	s_waitcnt vmcnt(6)
	s_barrier
	s_setprio 1
	v_mfma_f32_16x16x32_bf16 v[30:33], v[168:171], v[200:203], v[30:33]
	v_mfma_f32_16x16x32_bf16 v[26:29], v[168:171], v[208:211], v[26:29]
	v_mfma_f32_16x16x32_bf16 v[22:25], v[176:179], v[200:203], v[22:25]
	v_mfma_f32_16x16x32_bf16 v[18:21], v[176:179], v[208:211], v[18:21]
	v_mfma_f32_16x16x32_bf16 v[14:17], v[184:187], v[200:203], v[14:17]
	v_mfma_f32_16x16x32_bf16 v[10:13], v[184:187], v[208:211], v[10:13]
	v_mfma_f32_16x16x32_bf16 v[6:9], v[192:195], v[200:203], v[6:9]
	v_mfma_f32_16x16x32_bf16 v[2:5], v[192:195], v[208:211], v[2:5]
	v_mfma_f32_16x16x32_bf16 v[30:33], v[172:175], v[204:207], v[30:33]
	v_mfma_f32_16x16x32_bf16 v[26:29], v[172:175], v[212:215], v[26:29]
	v_mfma_f32_16x16x32_bf16 v[22:25], v[180:183], v[204:207], v[22:25]
	v_mfma_f32_16x16x32_bf16 v[18:21], v[180:183], v[212:215], v[18:21]
	v_mfma_f32_16x16x32_bf16 v[14:17], v[188:191], v[204:207], v[14:17]
	v_mfma_f32_16x16x32_bf16 v[10:13], v[188:191], v[212:215], v[10:13]
	v_mfma_f32_16x16x32_bf16 v[6:9], v[196:199], v[204:207], v[6:9]
	v_mfma_f32_16x16x32_bf16 v[2:5], v[196:199], v[212:215], v[2:5]
	s_setprio 0
	s_barrier
	ds_read_b128 v[152:155], v149
	ds_read_b128 v[156:159], v149 offset:1024
	ds_read_b128 v[160:163], v149 offset:2048
	ds_read_b128 v[164:167], v149 offset:3072
	s_mov_b32 m0, s40
	v_lshl_add_u64 v[200:201], v[216:217], 0, s[16:17]
	ds_read_b128 v[168:171], v144 offset:32768
	ds_read_b128 v[172:175], v144 offset:33792
	ds_read_b128 v[176:179], v145 offset:32768
	ds_read_b128 v[180:183], v145 offset:33792
	ds_read_b128 v[184:187], v146 offset:32768
	ds_read_b128 v[188:191], v146 offset:33792
	ds_read_b128 v[192:195], v147 offset:32768
	ds_read_b128 v[196:199], v147 offset:33792
	global_load_lds_dwordx4 v[200:201], off
	v_lshl_add_u64 v[200:201], v[218:219], 0, s[16:17]
	s_mov_b32 m0, s41
	s_nop 0
	global_load_lds_dwordx4 v[200:201], off
	s_waitcnt lgkmcnt(8)
	s_barrier
	s_setprio 1
	s_waitcnt lgkmcnt(7)
	v_mfma_f32_16x16x32_bf16 v[126:129], v[168:171], v[152:155], v[126:129]
	v_mfma_f32_16x16x32_bf16 v[122:125], v[168:171], v[160:163], v[122:125]
	s_waitcnt lgkmcnt(5)
	v_mfma_f32_16x16x32_bf16 v[118:121], v[176:179], v[152:155], v[118:121]
	v_mfma_f32_16x16x32_bf16 v[114:117], v[176:179], v[160:163], v[114:117]
	s_waitcnt lgkmcnt(3)
	v_mfma_f32_16x16x32_bf16 v[110:113], v[184:187], v[152:155], v[110:113]
	v_mfma_f32_16x16x32_bf16 v[106:109], v[184:187], v[160:163], v[106:109]
	s_waitcnt lgkmcnt(1)
	v_mfma_f32_16x16x32_bf16 v[102:105], v[192:195], v[152:155], v[102:105]
	v_mfma_f32_16x16x32_bf16 v[98:101], v[192:195], v[160:163], v[98:101]
	v_mfma_f32_16x16x32_bf16 v[126:129], v[172:175], v[156:159], v[126:129]
	v_mfma_f32_16x16x32_bf16 v[122:125], v[172:175], v[164:167], v[122:125]
	v_mfma_f32_16x16x32_bf16 v[118:121], v[180:183], v[156:159], v[118:121]
	v_mfma_f32_16x16x32_bf16 v[114:117], v[180:183], v[164:167], v[114:117]
	v_mfma_f32_16x16x32_bf16 v[110:113], v[188:191], v[156:159], v[110:113]
	v_mfma_f32_16x16x32_bf16 v[106:109], v[188:191], v[164:167], v[106:109]
	s_waitcnt lgkmcnt(0)
	v_mfma_f32_16x16x32_bf16 v[102:105], v[196:199], v[156:159], v[102:105]
	v_mfma_f32_16x16x32_bf16 v[98:101], v[196:199], v[164:167], v[98:101]
	s_setprio 0
	s_barrier
	s_mov_b32 m0, s28
	v_lshl_add_u64 v[224:225], v[220:221], 0, s[18:19]
	ds_read_b128 v[200:203], v150
	ds_read_b128 v[204:207], v150 offset:1024
	ds_read_b128 v[208:211], v150 offset:2048
	ds_read_b128 v[212:215], v150 offset:3072
	global_load_lds_dwordx4 v[224:225], off
	v_lshl_add_u64 v[224:225], v[222:223], 0, s[18:19]
	s_mov_b32 m0, s29
	s_nop 0
	global_load_lds_dwordx4 v[224:225], off
	s_barrier
	s_setprio 1
	s_waitcnt lgkmcnt(3)
	v_mfma_f32_16x16x32_bf16 v[94:97], v[168:171], v[200:203], v[94:97]
	s_waitcnt lgkmcnt(1)
	v_mfma_f32_16x16x32_bf16 v[90:93], v[168:171], v[208:211], v[90:93]
	v_mfma_f32_16x16x32_bf16 v[86:89], v[176:179], v[200:203], v[86:89]
	v_mfma_f32_16x16x32_bf16 v[82:85], v[176:179], v[208:211], v[82:85]
	v_mfma_f32_16x16x32_bf16 v[78:81], v[184:187], v[200:203], v[78:81]
	v_mfma_f32_16x16x32_bf16 v[74:77], v[184:187], v[208:211], v[74:77]
	v_mfma_f32_16x16x32_bf16 v[70:73], v[192:195], v[200:203], v[70:73]
	v_mfma_f32_16x16x32_bf16 v[66:69], v[192:195], v[208:211], v[66:69]
	v_mfma_f32_16x16x32_bf16 v[94:97], v[172:175], v[204:207], v[94:97]
	s_waitcnt lgkmcnt(0)
	v_mfma_f32_16x16x32_bf16 v[90:93], v[172:175], v[212:215], v[90:93]
	v_mfma_f32_16x16x32_bf16 v[86:89], v[180:183], v[204:207], v[86:89]
	v_mfma_f32_16x16x32_bf16 v[82:85], v[180:183], v[212:215], v[82:85]
	v_mfma_f32_16x16x32_bf16 v[78:81], v[188:191], v[204:207], v[78:81]
	v_mfma_f32_16x16x32_bf16 v[74:77], v[188:191], v[212:215], v[74:77]
	v_mfma_f32_16x16x32_bf16 v[70:73], v[196:199], v[204:207], v[70:73]
	v_mfma_f32_16x16x32_bf16 v[66:69], v[196:199], v[212:215], v[66:69]
	s_setprio 0
	s_mov_b32 m0, s42
	v_lshl_add_u64 v[216:217], v[216:217], 0, s[18:19]
	s_barrier
	ds_read_b128 v[168:171], v144 offset:49152
	ds_read_b128 v[172:175], v144 offset:50176
	ds_read_b128 v[176:179], v145 offset:49152
	ds_read_b128 v[180:183], v145 offset:50176
	ds_read_b128 v[184:187], v146 offset:49152
	ds_read_b128 v[188:191], v146 offset:50176
	ds_read_b128 v[192:195], v147 offset:49152
	ds_read_b128 v[196:199], v147 offset:50176
	global_load_lds_dwordx4 v[216:217], off
	v_lshl_add_u64 v[216:217], v[218:219], 0, s[18:19]
	s_mov_b32 m0, s43
	s_nop 0
	global_load_lds_dwordx4 v[216:217], off
	s_barrier
	s_setprio 1
	s_waitcnt lgkmcnt(7)
	v_mfma_f32_16x16x32_bf16 v[62:65], v[168:171], v[152:155], v[62:65]
	v_mfma_f32_16x16x32_bf16 v[58:61], v[168:171], v[160:163], v[58:61]
	s_waitcnt lgkmcnt(5)
	v_mfma_f32_16x16x32_bf16 v[54:57], v[176:179], v[152:155], v[54:57]
	v_mfma_f32_16x16x32_bf16 v[50:53], v[176:179], v[160:163], v[50:53]
	s_waitcnt lgkmcnt(3)
	v_mfma_f32_16x16x32_bf16 v[46:49], v[184:187], v[152:155], v[46:49]
	v_mfma_f32_16x16x32_bf16 v[42:45], v[184:187], v[160:163], v[42:45]
	s_waitcnt lgkmcnt(1)
	v_mfma_f32_16x16x32_bf16 v[38:41], v[192:195], v[152:155], v[38:41]
	v_mfma_f32_16x16x32_bf16 v[34:37], v[192:195], v[160:163], v[34:37]
	v_mfma_f32_16x16x32_bf16 v[62:65], v[172:175], v[156:159], v[62:65]
	v_mfma_f32_16x16x32_bf16 v[58:61], v[172:175], v[164:167], v[58:61]
	v_mfma_f32_16x16x32_bf16 v[54:57], v[180:183], v[156:159], v[54:57]
	v_mfma_f32_16x16x32_bf16 v[50:53], v[180:183], v[164:167], v[50:53]
	v_mfma_f32_16x16x32_bf16 v[46:49], v[188:191], v[156:159], v[46:49]
	v_mfma_f32_16x16x32_bf16 v[42:45], v[188:191], v[164:167], v[42:45]
	s_waitcnt lgkmcnt(0)
	v_mfma_f32_16x16x32_bf16 v[38:41], v[196:199], v[156:159], v[38:41]
	v_mfma_f32_16x16x32_bf16 v[34:37], v[196:199], v[164:167], v[34:37]
	s_setprio 0
	s_barrier
	s_mov_b32 m0, s46
	v_lshl_add_u64 v[152:153], v[220:221], 0, s[20:21]
	global_load_lds_dwordx4 v[152:153], off
	v_lshl_add_u64 v[152:153], v[222:223], 0, s[20:21]
	s_mov_b32 m0, s47
	s_nop 0
	global_load_lds_dwordx4 v[152:153], off
	s_waitcnt vmcnt(6)
	s_barrier
	s_setprio 1
	v_mfma_f32_16x16x32_bf16 v[30:33], v[168:171], v[200:203], v[30:33]
	v_mfma_f32_16x16x32_bf16 v[26:29], v[168:171], v[208:211], v[26:29]
	v_mfma_f32_16x16x32_bf16 v[22:25], v[176:179], v[200:203], v[22:25]
	v_mfma_f32_16x16x32_bf16 v[18:21], v[176:179], v[208:211], v[18:21]
	v_mfma_f32_16x16x32_bf16 v[14:17], v[184:187], v[200:203], v[14:17]
	v_mfma_f32_16x16x32_bf16 v[10:13], v[184:187], v[208:211], v[10:13]
	v_mfma_f32_16x16x32_bf16 v[6:9], v[192:195], v[200:203], v[6:9]
	v_mfma_f32_16x16x32_bf16 v[2:5], v[192:195], v[208:211], v[2:5]
	v_mfma_f32_16x16x32_bf16 v[30:33], v[172:175], v[204:207], v[30:33]
	v_mfma_f32_16x16x32_bf16 v[26:29], v[172:175], v[212:215], v[26:29]
	v_mfma_f32_16x16x32_bf16 v[22:25], v[180:183], v[204:207], v[22:25]
	v_mfma_f32_16x16x32_bf16 v[18:21], v[180:183], v[212:215], v[18:21]
	v_mfma_f32_16x16x32_bf16 v[14:17], v[188:191], v[204:207], v[14:17]
	v_mfma_f32_16x16x32_bf16 v[10:13], v[188:191], v[212:215], v[10:13]
	v_mfma_f32_16x16x32_bf16 v[6:9], v[196:199], v[204:207], v[6:9]
	v_mfma_f32_16x16x32_bf16 v[2:5], v[196:199], v[212:215], v[2:5]
	s_setprio 0
	s_add_i32 s49, s49, 2
	s_add_u32 s26, s26, 0x100
	s_addc_u32 s27, s27, 0
	s_cmp_lt_u32 s49, 40
	s_barrier
	s_cbranch_scc1 .LBB0_398
	s_add_u32 s22, s22, 0xb1580
	s_addc_u32 s23, s23, 0
	s_mov_b32 m0, s50
	v_lshl_add_u64 v[192:193], v[130:131], 1, s[22:23]
	ds_read_b128 v[134:137], v143
	ds_read_b128 v[138:141], v143 offset:1024
	ds_read_b128 v[152:155], v143 offset:2048
	ds_read_b128 v[156:159], v143 offset:3072
	ds_read_b128 v[160:163], v144
	ds_read_b128 v[164:167], v144 offset:1024
	ds_read_b128 v[168:171], v145
	ds_read_b128 v[172:175], v145 offset:1024
	ds_read_b128 v[176:179], v146
	ds_read_b128 v[180:183], v146 offset:1024
	ds_read_b128 v[184:187], v147
	ds_read_b128 v[188:191], v147 offset:1024
	global_load_lds_dwordx4 v[192:193], off
	v_lshl_add_u64 v[132:133], v[132:133], 1, s[22:23]
	s_mov_b32 m0, s48
	s_nop 0
	global_load_lds_dwordx4 v[132:133], off
	s_barrier
	s_waitcnt lgkmcnt(0)
	s_setprio 1
	s_waitcnt lgkmcnt(0)
	v_mfma_f32_16x16x32_bf16 v[126:129], v[160:163], v[134:137], v[126:129]
	v_mfma_f32_16x16x32_bf16 v[122:125], v[160:163], v[152:155], v[122:125]
	v_mfma_f32_16x16x32_bf16 v[118:121], v[168:171], v[134:137], v[118:121]
	v_mfma_f32_16x16x32_bf16 v[114:117], v[168:171], v[152:155], v[114:117]
	v_mfma_f32_16x16x32_bf16 v[110:113], v[176:179], v[134:137], v[110:113]
	v_mfma_f32_16x16x32_bf16 v[126:129], v[164:167], v[138:141], v[126:129]
	v_mfma_f32_16x16x32_bf16 v[122:125], v[164:167], v[156:159], v[122:125]
	v_mfma_f32_16x16x32_bf16 v[118:121], v[172:175], v[138:141], v[118:121]
	v_mfma_f32_16x16x32_bf16 v[114:117], v[172:175], v[156:159], v[114:117]
	v_mfma_f32_16x16x32_bf16 v[110:113], v[180:183], v[138:141], v[110:113]
	v_mfma_f32_16x16x32_bf16 v[106:109], v[176:179], v[152:155], v[106:109]
	v_mfma_f32_16x16x32_bf16 v[102:105], v[184:187], v[134:137], v[102:105]
	v_mfma_f32_16x16x32_bf16 v[98:101], v[184:187], v[152:155], v[98:101]
	v_mfma_f32_16x16x32_bf16 v[192:195], v[180:183], v[156:159], v[106:109]
	v_mfma_f32_16x16x32_bf16 v[196:199], v[188:191], v[138:141], v[102:105]
	v_mfma_f32_16x16x32_bf16 v[200:203], v[188:191], v[156:159], v[98:101]
	s_setprio 0
	s_barrier
	s_nop 2
	ds_read_b128 v[98:101], v148
	ds_read_b128 v[102:105], v148 offset:1024
	ds_read_b128 v[106:109], v148 offset:2048
	ds_read_b128 v[204:207], v148 offset:3072
	s_barrier
	s_waitcnt lgkmcnt(0)
	s_setprio 1
	s_waitcnt lgkmcnt(0)
	v_mfma_f32_16x16x32_bf16 v[94:97], v[160:163], v[98:101], v[94:97]
	v_mfma_f32_16x16x32_bf16 v[90:93], v[160:163], v[106:109], v[90:93]
	v_mfma_f32_16x16x32_bf16 v[86:89], v[168:171], v[98:101], v[86:89]
	v_mfma_f32_16x16x32_bf16 v[82:85], v[168:171], v[106:109], v[82:85]
	v_mfma_f32_16x16x32_bf16 v[94:97], v[164:167], v[102:105], v[94:97]
	v_mfma_f32_16x16x32_bf16 v[90:93], v[164:167], v[204:207], v[90:93]
	v_mfma_f32_16x16x32_bf16 v[86:89], v[172:175], v[102:105], v[86:89]
	v_mfma_f32_16x16x32_bf16 v[82:85], v[172:175], v[204:207], v[82:85]
	v_mfma_f32_16x16x32_bf16 v[78:81], v[176:179], v[98:101], v[78:81]
	v_mfma_f32_16x16x32_bf16 v[74:77], v[176:179], v[106:109], v[74:77]
	v_mfma_f32_16x16x32_bf16 v[70:73], v[184:187], v[98:101], v[70:73]
	v_mfma_f32_16x16x32_bf16 v[66:69], v[184:187], v[106:109], v[66:69]
	v_mfma_f32_16x16x32_bf16 v[160:163], v[180:183], v[102:105], v[78:81]
	v_mfma_f32_16x16x32_bf16 v[164:167], v[180:183], v[204:207], v[74:77]
	v_mfma_f32_16x16x32_bf16 v[168:171], v[188:191], v[102:105], v[70:73]
	v_mfma_f32_16x16x32_bf16 v[172:175], v[188:191], v[204:207], v[66:69]
	s_setprio 0
	s_barrier
	s_nop 1
	ds_read_b128 v[66:69], v144 offset:16384
	ds_read_b128 v[70:73], v144 offset:17408
	ds_read_b128 v[74:77], v145 offset:16384
	ds_read_b128 v[78:81], v145 offset:17408
	ds_read_b128 v[176:179], v146 offset:16384
	ds_read_b128 v[180:183], v146 offset:17408
	ds_read_b128 v[184:187], v147 offset:16384
	ds_read_b128 v[188:191], v147 offset:17408
	s_waitcnt vmcnt(4)
	s_barrier
	s_waitcnt lgkmcnt(0)
	s_setprio 1
	s_waitcnt lgkmcnt(0)
	v_mfma_f32_16x16x32_bf16 v[62:65], v[66:69], v[134:137], v[62:65]
	v_mfma_f32_16x16x32_bf16 v[58:61], v[66:69], v[152:155], v[58:61]
	v_mfma_f32_16x16x32_bf16 v[54:57], v[74:77], v[134:137], v[54:57]
	v_mfma_f32_16x16x32_bf16 v[50:53], v[74:77], v[152:155], v[50:53]
	v_mfma_f32_16x16x32_bf16 v[62:65], v[70:73], v[138:141], v[62:65]
	v_mfma_f32_16x16x32_bf16 v[58:61], v[70:73], v[156:159], v[58:61]
	v_mfma_f32_16x16x32_bf16 v[54:57], v[78:81], v[138:141], v[54:57]
	v_mfma_f32_16x16x32_bf16 v[50:53], v[78:81], v[156:159], v[50:53]
	v_mfma_f32_16x16x32_bf16 v[46:49], v[176:179], v[134:137], v[46:49]
	v_mfma_f32_16x16x32_bf16 v[42:45], v[176:179], v[152:155], v[42:45]
	v_mfma_f32_16x16x32_bf16 v[38:41], v[184:187], v[134:137], v[38:41]
	v_mfma_f32_16x16x32_bf16 v[34:37], v[184:187], v[152:155], v[34:37]
	v_mfma_f32_16x16x32_bf16 v[208:211], v[180:183], v[138:141], v[46:49]
	v_mfma_f32_16x16x32_bf16 v[212:215], v[180:183], v[156:159], v[42:45]
	v_mfma_f32_16x16x32_bf16 v[132:135], v[188:191], v[138:141], v[38:41]
	v_mfma_f32_16x16x32_bf16 v[136:139], v[188:191], v[156:159], v[34:37]
	s_setprio 0
	s_setprio 1
	v_mfma_f32_16x16x32_bf16 v[30:33], v[66:69], v[98:101], v[30:33]
	v_mfma_f32_16x16x32_bf16 v[26:29], v[66:69], v[106:109], v[26:29]
	v_mfma_f32_16x16x32_bf16 v[22:25], v[74:77], v[98:101], v[22:25]
	v_mfma_f32_16x16x32_bf16 v[30:33], v[70:73], v[102:105], v[30:33]
	v_mfma_f32_16x16x32_bf16 v[26:29], v[70:73], v[204:207], v[26:29]
	v_mfma_f32_16x16x32_bf16 v[22:25], v[78:81], v[102:105], v[22:25]
	v_mfma_f32_16x16x32_bf16 v[18:21], v[74:77], v[106:109], v[18:21]
	v_mfma_f32_16x16x32_bf16 v[14:17], v[176:179], v[98:101], v[14:17]
	v_mfma_f32_16x16x32_bf16 v[10:13], v[176:179], v[106:109], v[10:13]
	v_mfma_f32_16x16x32_bf16 v[6:9], v[184:187], v[98:101], v[6:9]
	v_mfma_f32_16x16x32_bf16 v[2:5], v[184:187], v[106:109], v[2:5]
	v_mfma_f32_16x16x32_bf16 v[152:155], v[78:81], v[204:207], v[18:21]
	v_mfma_f32_16x16x32_bf16 v[156:159], v[180:183], v[102:105], v[14:17]
	v_mfma_f32_16x16x32_bf16 v[176:179], v[180:183], v[204:207], v[10:13]
	v_mfma_f32_16x16x32_bf16 v[180:183], v[188:191], v[102:105], v[6:9]
	v_mfma_f32_16x16x32_bf16 v[184:187], v[188:191], v[204:207], v[2:5]
	s_setprio 0
	s_barrier
	ds_read_b128 v[18:21], v149
	ds_read_b128 v[188:191], v149 offset:1024
	ds_read_b128 v[204:207], v149 offset:2048
	ds_read_b128 v[216:219], v149 offset:3072
	ds_read_b128 v[2:5], v144 offset:32768
	ds_read_b128 v[6:9], v144 offset:33792
	ds_read_b128 v[10:13], v145 offset:32768
	ds_read_b128 v[14:17], v145 offset:33792
	ds_read_b128 v[46:49], v146 offset:32768
	ds_read_b128 v[220:223], v146 offset:33792
	ds_read_b128 v[224:227], v147 offset:32768
	ds_read_b128 v[228:231], v147 offset:33792
	s_waitcnt vmcnt(2)
	s_barrier
	s_waitcnt lgkmcnt(0)
	s_setprio 1
	s_waitcnt lgkmcnt(0)
	v_mfma_f32_16x16x32_bf16 v[34:37], v[2:5], v[18:21], v[126:129]
	v_mfma_f32_16x16x32_bf16 v[98:101], v[6:9], v[188:191], v[34:37]
	v_mfma_f32_16x16x32_bf16 v[34:37], v[2:5], v[204:207], v[122:125]
	v_mfma_f32_16x16x32_bf16 v[66:69], v[6:9], v[216:219], v[34:37]
	v_mfma_f32_16x16x32_bf16 v[34:37], v[10:13], v[18:21], v[118:121]
	v_mfma_f32_16x16x32_bf16 v[102:105], v[14:17], v[188:191], v[34:37]
	v_mfma_f32_16x16x32_bf16 v[34:37], v[10:13], v[204:207], v[114:117]
	v_mfma_f32_16x16x32_bf16 v[70:73], v[14:17], v[216:219], v[34:37]
	v_mfma_f32_16x16x32_bf16 v[34:37], v[46:49], v[18:21], v[110:113]
	v_mfma_f32_16x16x32_bf16 v[106:109], v[220:223], v[188:191], v[34:37]
	v_mfma_f32_16x16x32_bf16 v[34:37], v[46:49], v[204:207], v[192:195]
	v_mfma_f32_16x16x32_bf16 v[74:77], v[220:223], v[216:219], v[34:37]
	v_mfma_f32_16x16x32_bf16 v[34:37], v[224:227], v[18:21], v[196:199]
	v_mfma_f32_16x16x32_bf16 v[110:113], v[228:231], v[188:191], v[34:37]
	v_mfma_f32_16x16x32_bf16 v[34:37], v[224:227], v[204:207], v[200:203]
	v_mfma_f32_16x16x32_bf16 v[78:81], v[228:231], v[216:219], v[34:37]
	s_setprio 0
	s_barrier
	ds_read_b128 v[192:195], v150
	ds_read_b128 v[196:199], v150 offset:1024
	ds_read_b128 v[200:203], v150 offset:2048
	ds_read_b128 v[232:235], v150 offset:3072
	s_waitcnt vmcnt(0)
	s_barrier
	s_waitcnt lgkmcnt(0)
	s_setprio 1
	s_waitcnt lgkmcnt(0)
	v_mfma_f32_16x16x32_bf16 v[34:37], v[2:5], v[192:195], v[94:97]
	v_mfma_f32_16x16x32_bf16 v[2:5], v[2:5], v[200:203], v[90:93]
	v_mfma_f32_16x16x32_bf16 v[34:37], v[6:9], v[196:199], v[34:37]
	v_mfma_f32_16x16x32_bf16 v[2:5], v[6:9], v[232:235], v[2:5]
	v_mfma_f32_16x16x32_bf16 v[6:9], v[10:13], v[192:195], v[86:89]
	v_mfma_f32_16x16x32_bf16 v[38:41], v[14:17], v[196:199], v[6:9]
	v_mfma_f32_16x16x32_bf16 v[6:9], v[10:13], v[200:203], v[82:85]
	v_mfma_f32_16x16x32_bf16 v[6:9], v[14:17], v[232:235], v[6:9]
	v_mfma_f32_16x16x32_bf16 v[10:13], v[46:49], v[192:195], v[160:163]
	v_mfma_f32_16x16x32_bf16 v[14:17], v[224:227], v[192:195], v[168:171]
	v_mfma_f32_16x16x32_bf16 v[42:45], v[220:223], v[196:199], v[10:13]
	v_mfma_f32_16x16x32_bf16 v[10:13], v[46:49], v[200:203], v[164:167]
	v_mfma_f32_16x16x32_bf16 v[46:49], v[228:231], v[196:199], v[14:17]
	v_mfma_f32_16x16x32_bf16 v[14:17], v[224:227], v[200:203], v[172:175]
	v_mfma_f32_16x16x32_bf16 v[10:13], v[220:223], v[232:235], v[10:13]
	v_mfma_f32_16x16x32_bf16 v[14:17], v[228:231], v[232:235], v[14:17]
	s_setprio 0
	s_barrier
	ds_read_b128 v[160:163], v144 offset:49152
	ds_read_b128 v[164:167], v144 offset:50176
	ds_read_b128 v[168:171], v145 offset:49152
	ds_read_b128 v[172:175], v145 offset:50176
	ds_read_b128 v[220:223], v146 offset:49152
	ds_read_b128 v[224:227], v146 offset:50176
	ds_read_b128 v[228:231], v147 offset:49152
	ds_read_b128 v[236:239], v147 offset:50176
	s_barrier
	s_waitcnt lgkmcnt(0)
	s_setprio 1
	s_waitcnt lgkmcnt(0)
	v_mfma_f32_16x16x32_bf16 v[50:53], v[168:171], v[204:207], v[50:53]
	v_mfma_f32_16x16x32_bf16 v[62:65], v[160:163], v[18:21], v[62:65]
	v_mfma_f32_16x16x32_bf16 v[54:57], v[168:171], v[18:21], v[54:57]
	v_mfma_f32_16x16x32_bf16 v[86:89], v[172:175], v[216:219], v[50:53]
	v_mfma_f32_16x16x32_bf16 v[50:53], v[220:223], v[18:21], v[208:211]
	v_mfma_f32_16x16x32_bf16 v[18:21], v[228:231], v[18:21], v[132:135]
	v_mfma_f32_16x16x32_bf16 v[58:61], v[160:163], v[204:207], v[58:61]
	v_mfma_f32_16x16x32_bf16 v[122:125], v[224:227], v[188:191], v[50:53]
	v_mfma_f32_16x16x32_bf16 v[50:53], v[220:223], v[204:207], v[212:215]
	v_mfma_f32_16x16x32_bf16 v[126:129], v[236:239], v[188:191], v[18:21]
	v_mfma_f32_16x16x32_bf16 v[18:21], v[228:231], v[204:207], v[136:139]
	v_mfma_f32_16x16x32_bf16 v[114:117], v[164:167], v[188:191], v[62:65]
	v_mfma_f32_16x16x32_bf16 v[82:85], v[164:167], v[216:219], v[58:61]
	v_mfma_f32_16x16x32_bf16 v[118:121], v[172:175], v[188:191], v[54:57]
	v_mfma_f32_16x16x32_bf16 v[90:93], v[224:227], v[216:219], v[50:53]
	v_mfma_f32_16x16x32_bf16 v[94:97], v[236:239], v[216:219], v[18:21]
	s_setprio 0
	s_setprio 1
	v_mfma_f32_16x16x32_bf16 v[22:25], v[168:171], v[192:195], v[22:25]
	v_mfma_f32_16x16x32_bf16 v[18:21], v[160:163], v[192:195], v[30:33]
	v_mfma_f32_16x16x32_bf16 v[54:57], v[172:175], v[196:199], v[22:25]
	v_mfma_f32_16x16x32_bf16 v[22:25], v[168:171], v[200:203], v[152:155]
	v_mfma_f32_16x16x32_bf16 v[50:53], v[164:167], v[196:199], v[18:21]
	v_mfma_f32_16x16x32_bf16 v[18:21], v[160:163], v[200:203], v[26:29]
	v_mfma_f32_16x16x32_bf16 v[26:29], v[172:175], v[232:235], v[22:25]
	v_mfma_f32_16x16x32_bf16 v[22:25], v[220:223], v[192:195], v[156:159]
	v_mfma_f32_16x16x32_bf16 v[58:61], v[224:227], v[196:199], v[22:25]
	v_mfma_f32_16x16x32_bf16 v[22:25], v[220:223], v[200:203], v[176:179]
	v_mfma_f32_16x16x32_bf16 v[30:33], v[224:227], v[232:235], v[22:25]
	v_mfma_f32_16x16x32_bf16 v[22:25], v[228:231], v[192:195], v[180:183]
	v_mfma_f32_16x16x32_bf16 v[62:65], v[236:239], v[196:199], v[22:25]
	v_mfma_f32_16x16x32_bf16 v[22:25], v[228:231], v[200:203], v[184:187]
	v_mfma_f32_16x16x32_bf16 v[18:21], v[164:167], v[232:235], v[18:21]
	v_mfma_f32_16x16x32_bf16 v[22:25], v[236:239], v[232:235], v[22:25]
	s_setprio 0
	s_barrier
	s_and_saveexec_b64 s[22:23], s[2:3]
	s_cbranch_execz .LBB0_394
	s_barrier
	s_branch .LBB0_394
